# k10 + MFMA issue order: the two k-steps of each accumulator issued back-to-back (dependent pairs), same per-accumulator summation order
# speedup vs baseline: 1.0102x; 1.0072x over previous
.LBB0_202:
	ds_read_b128 v[148:151], v167
	ds_read_b128 v[152:155], v167 offset:1024
	ds_read_b128 v[156:159], v167 offset:2048
	ds_read_b128 v[160:163], v167 offset:3072
	ds_read_b128 v[172:175], v168
	ds_read_b128 v[176:179], v168 offset:1024
	ds_read_b128 v[180:183], v168 offset:2048
	ds_read_b128 v[184:187], v168 offset:3072
	s_add_u32 s0, s28, 0xfffc0080
	s_addc_u32 s1, s29, -1
	s_cmp_eq_u32 s51, 12
	s_cselect_b32 s31, s21, s1
	s_cselect_b32 s30, s47, s0
	s_cselect_b32 s3, s19, s50
	s_cselect_b32 s2, s48, s49
	v_lshl_add_u64 v[220:221], s[28:29], 0, v[140:141]
	s_add_i32 m0, s27, 0xc000
	ds_read_b128 v[188:191], v169
	ds_read_b128 v[192:195], v169 offset:1024
	ds_read_b128 v[196:199], v169 offset:2048
	ds_read_b128 v[200:203], v169 offset:3072
	ds_read_b128 v[204:207], v169 offset:4096
	ds_read_b128 v[208:211], v169 offset:5120
	ds_read_b128 v[212:215], v169 offset:6144
	ds_read_b128 v[216:219], v169 offset:7168
	global_load_lds_dwordx4 v[220:221], off
	v_lshl_add_u64 v[220:221], s[28:29], 0, v[142:143]
	s_add_i32 m0, s27, 0xe000
	s_nop 0
	global_load_lds_dwordx4 v[220:221], off
	s_waitcnt vmcnt(8)
	s_waitcnt lgkmcnt(0)
	s_barrier
	s_setprio 1
	s_waitcnt lgkmcnt(0)
	v_mfma_f32_16x16x32_bf16 v[126:129], v[148:151], v[188:191], v[126:129]
	v_mfma_f32_16x16x32_bf16 v[126:129], v[152:155], v[192:195], v[126:129]
	v_mfma_f32_16x16x32_bf16 v[118:121], v[156:159], v[188:191], v[118:121]
	v_mfma_f32_16x16x32_bf16 v[118:121], v[160:163], v[192:195], v[118:121]
	v_mfma_f32_16x16x32_bf16 v[110:113], v[148:151], v[196:199], v[110:113]
	v_mfma_f32_16x16x32_bf16 v[110:113], v[152:155], v[200:203], v[110:113]
	v_mfma_f32_16x16x32_bf16 v[106:109], v[156:159], v[196:199], v[106:109]
	v_mfma_f32_16x16x32_bf16 v[106:109], v[160:163], v[200:203], v[106:109]
	v_mfma_f32_16x16x32_bf16 v[94:97], v[148:151], v[204:207], v[94:97]
	v_mfma_f32_16x16x32_bf16 v[94:97], v[152:155], v[208:211], v[94:97]
	v_mfma_f32_16x16x32_bf16 v[90:93], v[156:159], v[204:207], v[90:93]
	v_mfma_f32_16x16x32_bf16 v[90:93], v[160:163], v[208:211], v[90:93]
	v_mfma_f32_16x16x32_bf16 v[78:81], v[148:151], v[212:215], v[78:81]
	v_mfma_f32_16x16x32_bf16 v[78:81], v[152:155], v[216:219], v[78:81]
	v_mfma_f32_16x16x32_bf16 v[74:77], v[156:159], v[212:215], v[74:77]
	v_mfma_f32_16x16x32_bf16 v[74:77], v[160:163], v[216:219], v[74:77]
	s_setprio 0
	s_setprio 1
	v_mfma_f32_16x16x32_bf16 v[122:125], v[172:175], v[188:191], v[122:125]
	v_mfma_f32_16x16x32_bf16 v[122:125], v[176:179], v[192:195], v[122:125]
	v_mfma_f32_16x16x32_bf16 v[114:117], v[180:183], v[188:191], v[114:117]
	v_mfma_f32_16x16x32_bf16 v[114:117], v[184:187], v[192:195], v[114:117]
	v_mfma_f32_16x16x32_bf16 v[102:105], v[172:175], v[196:199], v[102:105]
	v_mfma_f32_16x16x32_bf16 v[102:105], v[176:179], v[200:203], v[102:105]
	v_mfma_f32_16x16x32_bf16 v[98:101], v[180:183], v[196:199], v[98:101]
	v_mfma_f32_16x16x32_bf16 v[98:101], v[184:187], v[200:203], v[98:101]
	v_mfma_f32_16x16x32_bf16 v[86:89], v[172:175], v[204:207], v[86:89]
	v_mfma_f32_16x16x32_bf16 v[86:89], v[176:179], v[208:211], v[86:89]
	v_mfma_f32_16x16x32_bf16 v[82:85], v[180:183], v[204:207], v[82:85]
	v_mfma_f32_16x16x32_bf16 v[82:85], v[184:187], v[208:211], v[82:85]
	v_mfma_f32_16x16x32_bf16 v[70:73], v[172:175], v[212:215], v[70:73]
	v_mfma_f32_16x16x32_bf16 v[70:73], v[176:179], v[216:219], v[70:73]
	v_mfma_f32_16x16x32_bf16 v[66:69], v[180:183], v[212:215], v[66:69]
	v_mfma_f32_16x16x32_bf16 v[66:69], v[184:187], v[216:219], v[66:69]
	s_setprio 0
	s_barrier
	s_add_i32 s0, s43, s36
	v_lshl_add_u64 v[220:221], s[2:3], 0, v[132:133]
	s_mov_b32 m0, s0
	ds_read_b128 v[188:191], v169 offset:16384
	ds_read_b128 v[192:195], v169 offset:17408
	ds_read_b128 v[196:199], v169 offset:18432
	ds_read_b128 v[200:203], v169 offset:19456
	ds_read_b128 v[204:207], v169 offset:20480
	ds_read_b128 v[208:211], v169 offset:21504
	ds_read_b128 v[212:215], v169 offset:22528
	ds_read_b128 v[216:219], v169 offset:23552
	global_load_lds_dwordx4 v[220:221], off
	s_add_i32 m0, s0, 0x2000
	s_add_u32 s0, s2, 0x40000
	v_lshl_add_u64 v[222:223], s[2:3], 0, v[136:137]
	s_addc_u32 s1, s3, 0
	s_add_i32 s52, s44, s36
	global_load_lds_dwordx4 v[222:223], off
	v_lshl_add_u64 v[224:225], s[0:1], 0, v[132:133]
	s_mov_b32 m0, s52
	v_lshl_add_u64 v[226:227], s[30:31], 0, v[134:135]
	global_load_lds_dwordx4 v[224:225], off
	v_lshl_add_u64 v[224:225], s[0:1], 0, v[136:137]
	s_add_i32 m0, s52, 0x2000
	s_nop 0
	global_load_lds_dwordx4 v[224:225], off
	v_lshl_add_u64 v[224:225], s[30:31], 0, v[130:131]
	s_mov_b32 m0, s27
	s_nop 0
	global_load_lds_dwordx4 v[224:225], off
	s_mov_b32 m0, s37
	s_nop 0
	global_load_lds_dwordx4 v[226:227], off
	s_waitcnt vmcnt(8)
	s_waitcnt lgkmcnt(0)
	s_barrier
	s_setprio 1
	s_waitcnt lgkmcnt(0)
	v_mfma_f32_16x16x32_bf16 v[62:65], v[148:151], v[188:191], v[62:65]
	v_mfma_f32_16x16x32_bf16 v[62:65], v[152:155], v[192:195], v[62:65]
	v_mfma_f32_16x16x32_bf16 v[58:61], v[156:159], v[188:191], v[58:61]
	v_mfma_f32_16x16x32_bf16 v[58:61], v[160:163], v[192:195], v[58:61]
	v_mfma_f32_16x16x32_bf16 v[46:49], v[148:151], v[196:199], v[46:49]
	v_mfma_f32_16x16x32_bf16 v[46:49], v[152:155], v[200:203], v[46:49]
	v_mfma_f32_16x16x32_bf16 v[42:45], v[156:159], v[196:199], v[42:45]
	v_mfma_f32_16x16x32_bf16 v[42:45], v[160:163], v[200:203], v[42:45]
	v_mfma_f32_16x16x32_bf16 v[30:33], v[148:151], v[204:207], v[30:33]
	v_mfma_f32_16x16x32_bf16 v[30:33], v[152:155], v[208:211], v[30:33]
	v_mfma_f32_16x16x32_bf16 v[26:29], v[156:159], v[204:207], v[26:29]
	v_mfma_f32_16x16x32_bf16 v[26:29], v[160:163], v[208:211], v[26:29]
	v_mfma_f32_16x16x32_bf16 v[14:17], v[148:151], v[212:215], v[14:17]
	v_mfma_f32_16x16x32_bf16 v[14:17], v[152:155], v[216:219], v[14:17]
	v_mfma_f32_16x16x32_bf16 v[10:13], v[156:159], v[212:215], v[10:13]
	v_mfma_f32_16x16x32_bf16 v[10:13], v[160:163], v[216:219], v[10:13]
	s_setprio 0
	s_setprio 1
	v_mfma_f32_16x16x32_bf16 v[54:57], v[172:175], v[188:191], v[54:57]
	v_mfma_f32_16x16x32_bf16 v[54:57], v[176:179], v[192:195], v[54:57]
	v_mfma_f32_16x16x32_bf16 v[50:53], v[180:183], v[188:191], v[50:53]
	v_mfma_f32_16x16x32_bf16 v[50:53], v[184:187], v[192:195], v[50:53]
	v_mfma_f32_16x16x32_bf16 v[38:41], v[172:175], v[196:199], v[38:41]
	v_mfma_f32_16x16x32_bf16 v[38:41], v[176:179], v[200:203], v[38:41]
	v_mfma_f32_16x16x32_bf16 v[34:37], v[180:183], v[196:199], v[34:37]
	v_mfma_f32_16x16x32_bf16 v[34:37], v[184:187], v[200:203], v[34:37]
	v_mfma_f32_16x16x32_bf16 v[22:25], v[172:175], v[204:207], v[22:25]
	v_mfma_f32_16x16x32_bf16 v[22:25], v[176:179], v[208:211], v[22:25]
	v_mfma_f32_16x16x32_bf16 v[18:21], v[180:183], v[204:207], v[18:21]
	v_mfma_f32_16x16x32_bf16 v[18:21], v[184:187], v[208:211], v[18:21]
	v_mfma_f32_16x16x32_bf16 v[6:9], v[172:175], v[212:215], v[6:9]
	v_mfma_f32_16x16x32_bf16 v[6:9], v[176:179], v[216:219], v[6:9]
	v_mfma_f32_16x16x32_bf16 v[2:5], v[180:183], v[212:215], v[2:5]
	v_mfma_f32_16x16x32_bf16 v[2:5], v[184:187], v[216:219], v[2:5]
	s_setprio 0
	s_barrier
	s_add_i32 s52, 0, 0x18000
	s_add_i32 s53, 0, 0x1c000
	v_add_u32_e32 v160, s52, v166
	v_add_u32_e32 v164, s53, v166
	ds_read_b128 v[148:151], v160
	ds_read_b128 v[152:155], v160 offset:1024
	ds_read_b128 v[156:159], v160 offset:2048
	ds_read_b128 v[160:163], v160 offset:3072
	ds_read_b128 v[172:175], v164
	ds_read_b128 v[176:179], v164 offset:1024
	ds_read_b128 v[180:183], v164 offset:2048
	ds_read_b128 v[184:187], v164 offset:3072
	s_add_u32 s0, s30, 0x40000
	s_addc_u32 s1, s31, 0
	s_mov_b32 m0, s38
	v_lshl_add_u64 v[228:229], s[0:1], 0, v[130:131]
	ds_read_b128 v[188:191], v169 offset:32768
	ds_read_b128 v[192:195], v169 offset:33792
	ds_read_b128 v[196:199], v169 offset:34816
	ds_read_b128 v[200:203], v169 offset:35840
	ds_read_b128 v[204:207], v169 offset:36864
	ds_read_b128 v[208:211], v169 offset:37888
	ds_read_b128 v[212:215], v169 offset:38912
	ds_read_b128 v[216:219], v169 offset:39936
	global_load_lds_dwordx4 v[228:229], off
	v_lshl_add_u64 v[228:229], s[0:1], 0, v[134:135]
	s_mov_b32 m0, s39
	s_nop 0
	global_load_lds_dwordx4 v[228:229], off
	s_waitcnt vmcnt(8)
	s_waitcnt lgkmcnt(0)
	s_barrier
	s_setprio 1
	s_waitcnt lgkmcnt(0)
	v_mfma_f32_16x16x32_bf16 v[126:129], v[148:151], v[188:191], v[126:129]
	v_mfma_f32_16x16x32_bf16 v[126:129], v[152:155], v[192:195], v[126:129]
	v_mfma_f32_16x16x32_bf16 v[118:121], v[156:159], v[188:191], v[118:121]
	v_mfma_f32_16x16x32_bf16 v[118:121], v[160:163], v[192:195], v[118:121]
	v_mfma_f32_16x16x32_bf16 v[110:113], v[148:151], v[196:199], v[110:113]
	v_mfma_f32_16x16x32_bf16 v[110:113], v[152:155], v[200:203], v[110:113]
	v_mfma_f32_16x16x32_bf16 v[106:109], v[156:159], v[196:199], v[106:109]
	v_mfma_f32_16x16x32_bf16 v[106:109], v[160:163], v[200:203], v[106:109]
	v_mfma_f32_16x16x32_bf16 v[94:97], v[148:151], v[204:207], v[94:97]
	v_mfma_f32_16x16x32_bf16 v[94:97], v[152:155], v[208:211], v[94:97]
	v_mfma_f32_16x16x32_bf16 v[90:93], v[156:159], v[204:207], v[90:93]
	v_mfma_f32_16x16x32_bf16 v[90:93], v[160:163], v[208:211], v[90:93]
	v_mfma_f32_16x16x32_bf16 v[78:81], v[148:151], v[212:215], v[78:81]
	v_mfma_f32_16x16x32_bf16 v[78:81], v[152:155], v[216:219], v[78:81]
	v_mfma_f32_16x16x32_bf16 v[74:77], v[156:159], v[212:215], v[74:77]
	v_mfma_f32_16x16x32_bf16 v[74:77], v[160:163], v[216:219], v[74:77]
	s_setprio 0
	s_setprio 1
	v_mfma_f32_16x16x32_bf16 v[122:125], v[172:175], v[188:191], v[122:125]
	v_mfma_f32_16x16x32_bf16 v[122:125], v[176:179], v[192:195], v[122:125]
	v_mfma_f32_16x16x32_bf16 v[114:117], v[180:183], v[188:191], v[114:117]
	v_mfma_f32_16x16x32_bf16 v[114:117], v[184:187], v[192:195], v[114:117]
	v_mfma_f32_16x16x32_bf16 v[102:105], v[172:175], v[196:199], v[102:105]
	v_mfma_f32_16x16x32_bf16 v[102:105], v[176:179], v[200:203], v[102:105]
	v_mfma_f32_16x16x32_bf16 v[98:101], v[180:183], v[196:199], v[98:101]
	v_mfma_f32_16x16x32_bf16 v[98:101], v[184:187], v[200:203], v[98:101]
	v_mfma_f32_16x16x32_bf16 v[86:89], v[172:175], v[204:207], v[86:89]
	v_mfma_f32_16x16x32_bf16 v[86:89], v[176:179], v[208:211], v[86:89]
	v_mfma_f32_16x16x32_bf16 v[82:85], v[180:183], v[204:207], v[82:85]
	v_mfma_f32_16x16x32_bf16 v[82:85], v[184:187], v[208:211], v[82:85]
	v_mfma_f32_16x16x32_bf16 v[70:73], v[172:175], v[212:215], v[70:73]
	v_mfma_f32_16x16x32_bf16 v[70:73], v[176:179], v[216:219], v[70:73]
	v_mfma_f32_16x16x32_bf16 v[66:69], v[180:183], v[212:215], v[66:69]
	v_mfma_f32_16x16x32_bf16 v[66:69], v[184:187], v[216:219], v[66:69]
	s_setprio 0
	s_barrier
	s_add_i32 s0, s52, s36
	v_lshl_add_u64 v[220:221], v[220:221], 0, s[14:15]
	s_mov_b32 m0, s0
	ds_read_b128 v[188:191], v169 offset:49152
	ds_read_b128 v[192:195], v169 offset:50176
	ds_read_b128 v[196:199], v169 offset:51200
	ds_read_b128 v[200:203], v169 offset:52224
	ds_read_b128 v[204:207], v169 offset:53248
	ds_read_b128 v[208:211], v169 offset:54272
	ds_read_b128 v[212:215], v169 offset:55296
	ds_read_b128 v[216:219], v169 offset:56320
	global_load_lds_dwordx4 v[220:221], off
	s_add_i32 m0, s0, 0x2000
	s_add_u32 s0, s2, 0x40080
	v_lshl_add_u64 v[220:221], v[222:223], 0, s[14:15]
	s_addc_u32 s1, s3, 0
	s_add_i32 s2, s53, s36
	global_load_lds_dwordx4 v[220:221], off
	v_lshl_add_u64 v[220:221], s[0:1], 0, v[132:133]
	s_mov_b32 m0, s2
	s_nop 0
	global_load_lds_dwordx4 v[220:221], off
	v_lshl_add_u64 v[220:221], s[0:1], 0, v[136:137]
	s_add_i32 m0, s2, 0x2000
	s_nop 0
	global_load_lds_dwordx4 v[220:221], off
	v_lshl_add_u64 v[220:221], v[224:225], 0, s[14:15]
	s_mov_b32 m0, s40
	s_nop 0
	global_load_lds_dwordx4 v[220:221], off
	v_lshl_add_u64 v[220:221], v[226:227], 0, s[14:15]
	s_mov_b32 m0, s41
	s_nop 0
	global_load_lds_dwordx4 v[220:221], off
	s_waitcnt vmcnt(8)
	s_waitcnt lgkmcnt(0)
	s_barrier
	s_setprio 1
	s_waitcnt lgkmcnt(0)
	v_mfma_f32_16x16x32_bf16 v[62:65], v[148:151], v[188:191], v[62:65]
	v_mfma_f32_16x16x32_bf16 v[62:65], v[152:155], v[192:195], v[62:65]
	v_mfma_f32_16x16x32_bf16 v[58:61], v[156:159], v[188:191], v[58:61]
	v_mfma_f32_16x16x32_bf16 v[58:61], v[160:163], v[192:195], v[58:61]
	v_mfma_f32_16x16x32_bf16 v[46:49], v[148:151], v[196:199], v[46:49]
	v_mfma_f32_16x16x32_bf16 v[46:49], v[152:155], v[200:203], v[46:49]
	v_mfma_f32_16x16x32_bf16 v[42:45], v[156:159], v[196:199], v[42:45]
	v_mfma_f32_16x16x32_bf16 v[42:45], v[160:163], v[200:203], v[42:45]
	v_mfma_f32_16x16x32_bf16 v[30:33], v[148:151], v[204:207], v[30:33]
	v_mfma_f32_16x16x32_bf16 v[30:33], v[152:155], v[208:211], v[30:33]
	v_mfma_f32_16x16x32_bf16 v[26:29], v[156:159], v[204:207], v[26:29]
	v_mfma_f32_16x16x32_bf16 v[26:29], v[160:163], v[208:211], v[26:29]
	v_mfma_f32_16x16x32_bf16 v[14:17], v[148:151], v[212:215], v[14:17]
	v_mfma_f32_16x16x32_bf16 v[14:17], v[152:155], v[216:219], v[14:17]
	v_mfma_f32_16x16x32_bf16 v[10:13], v[156:159], v[212:215], v[10:13]
	v_mfma_f32_16x16x32_bf16 v[10:13], v[160:163], v[216:219], v[10:13]
	s_setprio 0
	s_setprio 1
	v_mfma_f32_16x16x32_bf16 v[54:57], v[172:175], v[188:191], v[54:57]
	v_mfma_f32_16x16x32_bf16 v[54:57], v[176:179], v[192:195], v[54:57]
	v_mfma_f32_16x16x32_bf16 v[50:53], v[180:183], v[188:191], v[50:53]
	v_mfma_f32_16x16x32_bf16 v[50:53], v[184:187], v[192:195], v[50:53]
	v_mfma_f32_16x16x32_bf16 v[38:41], v[172:175], v[196:199], v[38:41]
	v_mfma_f32_16x16x32_bf16 v[38:41], v[176:179], v[200:203], v[38:41]
	v_mfma_f32_16x16x32_bf16 v[34:37], v[180:183], v[196:199], v[34:37]
	v_mfma_f32_16x16x32_bf16 v[34:37], v[184:187], v[200:203], v[34:37]
	v_mfma_f32_16x16x32_bf16 v[22:25], v[172:175], v[204:207], v[22:25]
	v_mfma_f32_16x16x32_bf16 v[22:25], v[176:179], v[208:211], v[22:25]
	v_mfma_f32_16x16x32_bf16 v[18:21], v[180:183], v[204:207], v[18:21]
	v_mfma_f32_16x16x32_bf16 v[18:21], v[184:187], v[208:211], v[18:21]
	v_mfma_f32_16x16x32_bf16 v[6:9], v[172:175], v[212:215], v[6:9]
	v_mfma_f32_16x16x32_bf16 v[6:9], v[176:179], v[216:219], v[6:9]
	v_mfma_f32_16x16x32_bf16 v[2:5], v[180:183], v[212:215], v[2:5]
	v_mfma_f32_16x16x32_bf16 v[2:5], v[184:187], v[216:219], v[2:5]
	s_setprio 0
	s_barrier
	s_add_i32 s51, s51, 2
	s_add_u32 s28, s28, 0x100
	s_addc_u32 s29, s29, 0
	s_add_u32 s49, s49, 0x100
	s_addc_u32 s50, s50, 0
	s_cmp_gt_u32 s51, 13
	s_cbranch_scc0 .LBB0_202
	s_and_b64 vcc, exec, s[16:17]
	s_cbranch_vccz .LBB0_205
	s_barrier

.LBB0_283:
	ds_read_b128 v[114:117], v228
	ds_read_b128 v[118:121], v228 offset:1024
	ds_read_b128 v[122:125], v228 offset:2048
	ds_read_b128 v[126:129], v228 offset:3072
	ds_read_b128 v[146:149], v229
	ds_read_b128 v[150:153], v229 offset:1024
	ds_read_b128 v[154:157], v229 offset:2048
	ds_read_b128 v[158:161], v229 offset:3072
	s_add_u32 s0, s10, 0xfffc0080
	s_addc_u32 s1, s11, -1
	s_cmp_eq_u32 s51, 12
	s_cselect_b32 s13, s7, s1
	s_cselect_b32 s12, s9, s0
	s_cselect_b32 s3, s27, s37
	s_cselect_b32 s2, s29, s36
	v_lshl_add_u64 v[212:213], s[10:11], 0, v[180:181]
	s_add_i32 m0, s40, 0xc000
	ds_read_b128 v[162:165], v230
	ds_read_b128 v[166:169], v230 offset:1024
	ds_read_b128 v[188:191], v230 offset:2048
	ds_read_b128 v[192:195], v230 offset:3072
	ds_read_b128 v[196:199], v230 offset:4096
	ds_read_b128 v[200:203], v230 offset:5120
	ds_read_b128 v[204:207], v230 offset:6144
	ds_read_b128 v[208:211], v230 offset:7168
	global_load_lds_dwordx4 v[212:213], off
	v_lshl_add_u64 v[212:213], s[10:11], 0, v[182:183]
	s_add_i32 m0, s40, 0xe000
	s_nop 0
	global_load_lds_dwordx4 v[212:213], off
	s_waitcnt vmcnt(8)
	s_waitcnt lgkmcnt(0)
	s_barrier
	s_setprio 1
	s_waitcnt lgkmcnt(0)
	v_mfma_f32_16x16x32_bf16 v[142:145], v[114:117], v[162:165], v[142:145]
	v_mfma_f32_16x16x32_bf16 v[142:145], v[118:121], v[166:169], v[142:145]
	v_mfma_f32_16x16x32_bf16 v[138:141], v[122:125], v[162:165], v[138:141]
	v_mfma_f32_16x16x32_bf16 v[138:141], v[126:129], v[166:169], v[138:141]
	v_mfma_f32_16x16x32_bf16 v[134:137], v[114:117], v[188:191], v[134:137]
	v_mfma_f32_16x16x32_bf16 v[134:137], v[118:121], v[192:195], v[134:137]
	v_mfma_f32_16x16x32_bf16 v[130:133], v[122:125], v[188:191], v[130:133]
	v_mfma_f32_16x16x32_bf16 v[130:133], v[126:129], v[192:195], v[130:133]
	v_mfma_f32_16x16x32_bf16 v[110:113], v[114:117], v[196:199], v[110:113]
	v_mfma_f32_16x16x32_bf16 v[110:113], v[118:121], v[200:203], v[110:113]
	v_mfma_f32_16x16x32_bf16 v[106:109], v[122:125], v[196:199], v[106:109]
	v_mfma_f32_16x16x32_bf16 v[106:109], v[126:129], v[200:203], v[106:109]
	v_mfma_f32_16x16x32_bf16 v[102:105], v[114:117], v[204:207], v[102:105]
	v_mfma_f32_16x16x32_bf16 v[102:105], v[118:121], v[208:211], v[102:105]
	v_mfma_f32_16x16x32_bf16 v[98:101], v[122:125], v[204:207], v[98:101]
	v_mfma_f32_16x16x32_bf16 v[98:101], v[126:129], v[208:211], v[98:101]
	s_setprio 0
	s_setprio 1
	v_mfma_f32_16x16x32_bf16 v[62:65], v[146:149], v[162:165], v[62:65]
	v_mfma_f32_16x16x32_bf16 v[62:65], v[150:153], v[166:169], v[62:65]
	v_mfma_f32_16x16x32_bf16 v[58:61], v[154:157], v[162:165], v[58:61]
	v_mfma_f32_16x16x32_bf16 v[58:61], v[158:161], v[166:169], v[58:61]
	v_mfma_f32_16x16x32_bf16 v[54:57], v[146:149], v[188:191], v[54:57]
	v_mfma_f32_16x16x32_bf16 v[54:57], v[150:153], v[192:195], v[54:57]
	v_mfma_f32_16x16x32_bf16 v[50:53], v[154:157], v[188:191], v[50:53]
	v_mfma_f32_16x16x32_bf16 v[50:53], v[158:161], v[192:195], v[50:53]
	v_mfma_f32_16x16x32_bf16 v[46:49], v[146:149], v[196:199], v[46:49]
	v_mfma_f32_16x16x32_bf16 v[46:49], v[150:153], v[200:203], v[46:49]
	v_mfma_f32_16x16x32_bf16 v[42:45], v[154:157], v[196:199], v[42:45]
	v_mfma_f32_16x16x32_bf16 v[42:45], v[158:161], v[200:203], v[42:45]
	v_mfma_f32_16x16x32_bf16 v[38:41], v[146:149], v[204:207], v[38:41]
	v_mfma_f32_16x16x32_bf16 v[38:41], v[150:153], v[208:211], v[38:41]
	v_mfma_f32_16x16x32_bf16 v[34:37], v[154:157], v[204:207], v[34:37]
	v_mfma_f32_16x16x32_bf16 v[34:37], v[158:161], v[208:211], v[34:37]
	s_setprio 0
	s_barrier
	s_add_i32 s0, s49, s39
	v_lshl_add_u64 v[212:213], s[2:3], 0, v[172:173]
	s_mov_b32 m0, s0
	ds_read_b128 v[162:165], v230 offset:16384
	ds_read_b128 v[166:169], v230 offset:17408
	ds_read_b128 v[188:191], v230 offset:18432
	ds_read_b128 v[192:195], v230 offset:19456
	ds_read_b128 v[196:199], v230 offset:20480
	ds_read_b128 v[200:203], v230 offset:21504
	ds_read_b128 v[204:207], v230 offset:22528
	ds_read_b128 v[208:211], v230 offset:23552
	global_load_lds_dwordx4 v[212:213], off
	s_add_i32 m0, s0, 0x2000
	s_add_u32 s0, s2, 0x40000
	v_lshl_add_u64 v[214:215], s[2:3], 0, v[176:177]
	s_addc_u32 s1, s3, 0
	s_add_i32 s52, s50, s39
	global_load_lds_dwordx4 v[214:215], off
	v_lshl_add_u64 v[216:217], s[0:1], 0, v[172:173]
	s_mov_b32 m0, s52
	v_lshl_add_u64 v[218:219], s[12:13], 0, v[174:175]
	global_load_lds_dwordx4 v[216:217], off
	v_lshl_add_u64 v[216:217], s[0:1], 0, v[176:177]
	s_add_i32 m0, s52, 0x2000
	s_nop 0
	global_load_lds_dwordx4 v[216:217], off
	v_lshl_add_u64 v[216:217], s[12:13], 0, v[170:171]
	s_mov_b32 m0, s40
	s_nop 0
	global_load_lds_dwordx4 v[216:217], off
	s_mov_b32 m0, s41
	s_nop 0
	global_load_lds_dwordx4 v[218:219], off
	s_waitcnt vmcnt(8)
	s_waitcnt lgkmcnt(0)
	s_barrier
	s_setprio 1
	s_waitcnt lgkmcnt(0)
	v_mfma_f32_16x16x32_bf16 v[94:97], v[114:117], v[162:165], v[94:97]
	v_mfma_f32_16x16x32_bf16 v[94:97], v[118:121], v[166:169], v[94:97]
	v_mfma_f32_16x16x32_bf16 v[90:93], v[122:125], v[162:165], v[90:93]
	v_mfma_f32_16x16x32_bf16 v[90:93], v[126:129], v[166:169], v[90:93]
	v_mfma_f32_16x16x32_bf16 v[86:89], v[114:117], v[188:191], v[86:89]
	v_mfma_f32_16x16x32_bf16 v[86:89], v[118:121], v[192:195], v[86:89]
	v_mfma_f32_16x16x32_bf16 v[82:85], v[122:125], v[188:191], v[82:85]
	v_mfma_f32_16x16x32_bf16 v[82:85], v[126:129], v[192:195], v[82:85]
	v_mfma_f32_16x16x32_bf16 v[78:81], v[114:117], v[196:199], v[78:81]
	v_mfma_f32_16x16x32_bf16 v[78:81], v[118:121], v[200:203], v[78:81]
	v_mfma_f32_16x16x32_bf16 v[74:77], v[122:125], v[196:199], v[74:77]
	v_mfma_f32_16x16x32_bf16 v[74:77], v[126:129], v[200:203], v[74:77]
	v_mfma_f32_16x16x32_bf16 v[70:73], v[114:117], v[204:207], v[70:73]
	v_mfma_f32_16x16x32_bf16 v[70:73], v[118:121], v[208:211], v[70:73]
	v_mfma_f32_16x16x32_bf16 v[66:69], v[122:125], v[204:207], v[66:69]
	v_mfma_f32_16x16x32_bf16 v[66:69], v[126:129], v[208:211], v[66:69]
	s_setprio 0
	s_setprio 1
	v_mfma_f32_16x16x32_bf16 v[30:33], v[146:149], v[162:165], v[30:33]
	v_mfma_f32_16x16x32_bf16 v[30:33], v[150:153], v[166:169], v[30:33]
	v_mfma_f32_16x16x32_bf16 v[26:29], v[154:157], v[162:165], v[26:29]
	v_mfma_f32_16x16x32_bf16 v[26:29], v[158:161], v[166:169], v[26:29]
	v_mfma_f32_16x16x32_bf16 v[22:25], v[146:149], v[188:191], v[22:25]
	v_mfma_f32_16x16x32_bf16 v[22:25], v[150:153], v[192:195], v[22:25]
	v_mfma_f32_16x16x32_bf16 v[18:21], v[154:157], v[188:191], v[18:21]
	v_mfma_f32_16x16x32_bf16 v[18:21], v[158:161], v[192:195], v[18:21]
	v_mfma_f32_16x16x32_bf16 v[14:17], v[146:149], v[196:199], v[14:17]
	v_mfma_f32_16x16x32_bf16 v[14:17], v[150:153], v[200:203], v[14:17]
	v_mfma_f32_16x16x32_bf16 v[10:13], v[154:157], v[196:199], v[10:13]
	v_mfma_f32_16x16x32_bf16 v[10:13], v[158:161], v[200:203], v[10:13]
	v_mfma_f32_16x16x32_bf16 v[6:9], v[146:149], v[204:207], v[6:9]
	v_mfma_f32_16x16x32_bf16 v[6:9], v[150:153], v[208:211], v[6:9]
	v_mfma_f32_16x16x32_bf16 v[2:5], v[154:157], v[204:207], v[2:5]
	v_mfma_f32_16x16x32_bf16 v[2:5], v[158:161], v[208:211], v[2:5]
	s_setprio 0
	s_barrier
	s_add_i32 s52, 0, 0x18000
	s_add_i32 s53, 0, 0x1c000
	v_add_u32_e32 v126, s52, v223
	v_add_u32_e32 v158, s53, v223
	ds_read_b128 v[114:117], v126
	ds_read_b128 v[118:121], v126 offset:1024
	ds_read_b128 v[122:125], v126 offset:2048
	ds_read_b128 v[126:129], v126 offset:3072
	ds_read_b128 v[146:149], v158
	ds_read_b128 v[150:153], v158 offset:1024
	ds_read_b128 v[154:157], v158 offset:2048
	ds_read_b128 v[158:161], v158 offset:3072
	s_add_u32 s0, s12, 0x40000
	s_addc_u32 s1, s13, 0
	s_mov_b32 m0, s42
	v_lshl_add_u64 v[220:221], s[0:1], 0, v[170:171]
	ds_read_b128 v[162:165], v230 offset:32768
	ds_read_b128 v[166:169], v230 offset:33792
	ds_read_b128 v[188:191], v230 offset:34816
	ds_read_b128 v[192:195], v230 offset:35840
	ds_read_b128 v[196:199], v230 offset:36864
	ds_read_b128 v[200:203], v230 offset:37888
	ds_read_b128 v[204:207], v230 offset:38912
	ds_read_b128 v[208:211], v230 offset:39936
	global_load_lds_dwordx4 v[220:221], off
	v_lshl_add_u64 v[220:221], s[0:1], 0, v[174:175]
	s_mov_b32 m0, s43
	s_nop 0
	global_load_lds_dwordx4 v[220:221], off
	s_waitcnt vmcnt(8)
	s_waitcnt lgkmcnt(0)
	s_barrier
	s_setprio 1
	s_waitcnt lgkmcnt(0)
	v_mfma_f32_16x16x32_bf16 v[142:145], v[114:117], v[162:165], v[142:145]
	v_mfma_f32_16x16x32_bf16 v[142:145], v[118:121], v[166:169], v[142:145]
	v_mfma_f32_16x16x32_bf16 v[138:141], v[122:125], v[162:165], v[138:141]
	v_mfma_f32_16x16x32_bf16 v[138:141], v[126:129], v[166:169], v[138:141]
	v_mfma_f32_16x16x32_bf16 v[134:137], v[114:117], v[188:191], v[134:137]
	v_mfma_f32_16x16x32_bf16 v[134:137], v[118:121], v[192:195], v[134:137]
	v_mfma_f32_16x16x32_bf16 v[130:133], v[122:125], v[188:191], v[130:133]
	v_mfma_f32_16x16x32_bf16 v[130:133], v[126:129], v[192:195], v[130:133]
	v_mfma_f32_16x16x32_bf16 v[110:113], v[114:117], v[196:199], v[110:113]
	v_mfma_f32_16x16x32_bf16 v[110:113], v[118:121], v[200:203], v[110:113]
	v_mfma_f32_16x16x32_bf16 v[106:109], v[122:125], v[196:199], v[106:109]
	v_mfma_f32_16x16x32_bf16 v[106:109], v[126:129], v[200:203], v[106:109]
	v_mfma_f32_16x16x32_bf16 v[102:105], v[114:117], v[204:207], v[102:105]
	v_mfma_f32_16x16x32_bf16 v[102:105], v[118:121], v[208:211], v[102:105]
	v_mfma_f32_16x16x32_bf16 v[98:101], v[122:125], v[204:207], v[98:101]
	v_mfma_f32_16x16x32_bf16 v[98:101], v[126:129], v[208:211], v[98:101]
	s_setprio 0
	s_setprio 1
	v_mfma_f32_16x16x32_bf16 v[62:65], v[146:149], v[162:165], v[62:65]
	v_mfma_f32_16x16x32_bf16 v[62:65], v[150:153], v[166:169], v[62:65]
	v_mfma_f32_16x16x32_bf16 v[58:61], v[154:157], v[162:165], v[58:61]
	v_mfma_f32_16x16x32_bf16 v[58:61], v[158:161], v[166:169], v[58:61]
	v_mfma_f32_16x16x32_bf16 v[54:57], v[146:149], v[188:191], v[54:57]
	v_mfma_f32_16x16x32_bf16 v[54:57], v[150:153], v[192:195], v[54:57]
	v_mfma_f32_16x16x32_bf16 v[50:53], v[154:157], v[188:191], v[50:53]
	v_mfma_f32_16x16x32_bf16 v[50:53], v[158:161], v[192:195], v[50:53]
	v_mfma_f32_16x16x32_bf16 v[46:49], v[146:149], v[196:199], v[46:49]
	v_mfma_f32_16x16x32_bf16 v[46:49], v[150:153], v[200:203], v[46:49]
	v_mfma_f32_16x16x32_bf16 v[42:45], v[154:157], v[196:199], v[42:45]
	v_mfma_f32_16x16x32_bf16 v[42:45], v[158:161], v[200:203], v[42:45]
	v_mfma_f32_16x16x32_bf16 v[38:41], v[146:149], v[204:207], v[38:41]
	v_mfma_f32_16x16x32_bf16 v[38:41], v[150:153], v[208:211], v[38:41]
	v_mfma_f32_16x16x32_bf16 v[34:37], v[154:157], v[204:207], v[34:37]
	v_mfma_f32_16x16x32_bf16 v[34:37], v[158:161], v[208:211], v[34:37]
	s_setprio 0
	s_barrier
	s_add_i32 s0, s52, s39
	v_lshl_add_u64 v[212:213], v[212:213], 0, s[22:23]
	s_mov_b32 m0, s0
	ds_read_b128 v[162:165], v230 offset:49152
	ds_read_b128 v[166:169], v230 offset:50176
	ds_read_b128 v[188:191], v230 offset:51200
	ds_read_b128 v[192:195], v230 offset:52224
	ds_read_b128 v[196:199], v230 offset:53248
	ds_read_b128 v[200:203], v230 offset:54272
	ds_read_b128 v[204:207], v230 offset:55296
	ds_read_b128 v[208:211], v230 offset:56320
	global_load_lds_dwordx4 v[212:213], off
	s_add_i32 m0, s0, 0x2000
	s_add_u32 s0, s2, 0x40080
	v_lshl_add_u64 v[212:213], v[214:215], 0, s[22:23]
	s_addc_u32 s1, s3, 0
	s_add_i32 s2, s53, s39
	global_load_lds_dwordx4 v[212:213], off
	v_lshl_add_u64 v[212:213], s[0:1], 0, v[172:173]
	s_mov_b32 m0, s2
	s_nop 0
	global_load_lds_dwordx4 v[212:213], off
	v_lshl_add_u64 v[212:213], s[0:1], 0, v[176:177]
	s_add_i32 m0, s2, 0x2000
	s_nop 0
	global_load_lds_dwordx4 v[212:213], off
	v_lshl_add_u64 v[212:213], v[216:217], 0, s[22:23]
	s_mov_b32 m0, s45
	s_nop 0
	global_load_lds_dwordx4 v[212:213], off
	v_lshl_add_u64 v[212:213], v[218:219], 0, s[22:23]
	s_mov_b32 m0, s46
	s_nop 0
	global_load_lds_dwordx4 v[212:213], off
	s_waitcnt vmcnt(8)
	s_waitcnt lgkmcnt(0)
	s_barrier
	s_setprio 1
	s_waitcnt lgkmcnt(0)
	v_mfma_f32_16x16x32_bf16 v[94:97], v[114:117], v[162:165], v[94:97]
	v_mfma_f32_16x16x32_bf16 v[94:97], v[118:121], v[166:169], v[94:97]
	v_mfma_f32_16x16x32_bf16 v[90:93], v[122:125], v[162:165], v[90:93]
	v_mfma_f32_16x16x32_bf16 v[90:93], v[126:129], v[166:169], v[90:93]
	v_mfma_f32_16x16x32_bf16 v[86:89], v[114:117], v[188:191], v[86:89]
	v_mfma_f32_16x16x32_bf16 v[86:89], v[118:121], v[192:195], v[86:89]
	v_mfma_f32_16x16x32_bf16 v[82:85], v[122:125], v[188:191], v[82:85]
	v_mfma_f32_16x16x32_bf16 v[82:85], v[126:129], v[192:195], v[82:85]
	v_mfma_f32_16x16x32_bf16 v[78:81], v[114:117], v[196:199], v[78:81]
	v_mfma_f32_16x16x32_bf16 v[78:81], v[118:121], v[200:203], v[78:81]
	v_mfma_f32_16x16x32_bf16 v[74:77], v[122:125], v[196:199], v[74:77]
	v_mfma_f32_16x16x32_bf16 v[74:77], v[126:129], v[200:203], v[74:77]
	v_mfma_f32_16x16x32_bf16 v[70:73], v[114:117], v[204:207], v[70:73]
	v_mfma_f32_16x16x32_bf16 v[70:73], v[118:121], v[208:211], v[70:73]
	v_mfma_f32_16x16x32_bf16 v[66:69], v[122:125], v[204:207], v[66:69]
	v_mfma_f32_16x16x32_bf16 v[66:69], v[126:129], v[208:211], v[66:69]
	s_setprio 0
	s_setprio 1
	v_mfma_f32_16x16x32_bf16 v[30:33], v[146:149], v[162:165], v[30:33]
	v_mfma_f32_16x16x32_bf16 v[30:33], v[150:153], v[166:169], v[30:33]
	v_mfma_f32_16x16x32_bf16 v[26:29], v[154:157], v[162:165], v[26:29]
	v_mfma_f32_16x16x32_bf16 v[26:29], v[158:161], v[166:169], v[26:29]
	v_mfma_f32_16x16x32_bf16 v[22:25], v[146:149], v[188:191], v[22:25]
	v_mfma_f32_16x16x32_bf16 v[22:25], v[150:153], v[192:195], v[22:25]
	v_mfma_f32_16x16x32_bf16 v[18:21], v[154:157], v[188:191], v[18:21]
	v_mfma_f32_16x16x32_bf16 v[18:21], v[158:161], v[192:195], v[18:21]
	v_mfma_f32_16x16x32_bf16 v[14:17], v[146:149], v[196:199], v[14:17]
	v_mfma_f32_16x16x32_bf16 v[14:17], v[150:153], v[200:203], v[14:17]
	v_mfma_f32_16x16x32_bf16 v[10:13], v[154:157], v[196:199], v[10:13]
	v_mfma_f32_16x16x32_bf16 v[10:13], v[158:161], v[200:203], v[10:13]
	v_mfma_f32_16x16x32_bf16 v[6:9], v[146:149], v[204:207], v[6:9]
	v_mfma_f32_16x16x32_bf16 v[6:9], v[150:153], v[208:211], v[6:9]
	v_mfma_f32_16x16x32_bf16 v[2:5], v[154:157], v[204:207], v[2:5]
	v_mfma_f32_16x16x32_bf16 v[2:5], v[158:161], v[208:211], v[2:5]
	s_setprio 0
	s_barrier
	s_add_i32 s51, s51, 2
	s_add_u32 s10, s10, 0x100
	s_addc_u32 s11, s11, 0
	s_add_u32 s36, s36, 0x100
	s_addc_u32 s37, s37, 0
	s_cmp_gt_u32 s51, 13
	s_cbranch_scc0 .LBB0_283
	s_and_b64 vcc, exec, s[24:25]
	s_cbranch_vccz .LBB0_286
	s_barrier

.LBB0_382:
	ds_read_b128 v[130:133], v211
	ds_read_b128 v[134:137], v211 offset:1024
	ds_read_b128 v[138:141], v211 offset:2048
	ds_read_b128 v[142:145], v211 offset:3072
	ds_read_b128 v[146:149], v212
	ds_read_b128 v[150:153], v212 offset:1024
	ds_read_b128 v[154:157], v212 offset:2048
	ds_read_b128 v[158:161], v212 offset:3072
	s_add_u32 s0, s28, 0xfffc0080
	s_addc_u32 s1, s29, -1
	s_cmp_eq_u32 s51, 12
	s_cselect_b32 s31, s11, s1
	s_cselect_b32 s30, s21, s0
	s_cselect_b32 s3, s19, s50
	s_cselect_b32 s2, s48, s49
	v_lshl_add_u64 v[220:221], s[28:29], 0, v[186:187]
	s_add_i32 m0, s27, 0xc000
	ds_read_b128 v[162:165], v213
	ds_read_b128 v[166:169], v213 offset:1024
	ds_read_b128 v[170:173], v213 offset:2048
	ds_read_b128 v[174:177], v213 offset:3072
	ds_read_b128 v[194:197], v213 offset:4096
	ds_read_b128 v[198:201], v213 offset:5120
	ds_read_b128 v[202:205], v213 offset:6144
	ds_read_b128 v[216:219], v213 offset:7168
	global_load_lds_dwordx4 v[220:221], off
	v_lshl_add_u64 v[220:221], s[28:29], 0, v[188:189]
	s_add_i32 m0, s27, 0xe000
	s_nop 0
	global_load_lds_dwordx4 v[220:221], off
	s_waitcnt vmcnt(8)
	s_waitcnt lgkmcnt(0)
	s_barrier
	s_setprio 1
	s_waitcnt lgkmcnt(0)
	v_mfma_f32_16x16x32_bf16 v[126:129], v[130:133], v[162:165], v[126:129]
	v_mfma_f32_16x16x32_bf16 v[126:129], v[134:137], v[166:169], v[126:129]
	v_mfma_f32_16x16x32_bf16 v[122:125], v[138:141], v[162:165], v[122:125]
	v_mfma_f32_16x16x32_bf16 v[122:125], v[142:145], v[166:169], v[122:125]
	v_mfma_f32_16x16x32_bf16 v[110:113], v[130:133], v[170:173], v[110:113]
	v_mfma_f32_16x16x32_bf16 v[110:113], v[134:137], v[174:177], v[110:113]
	v_mfma_f32_16x16x32_bf16 v[106:109], v[138:141], v[170:173], v[106:109]
	v_mfma_f32_16x16x32_bf16 v[106:109], v[142:145], v[174:177], v[106:109]
	v_mfma_f32_16x16x32_bf16 v[94:97], v[130:133], v[194:197], v[94:97]
	v_mfma_f32_16x16x32_bf16 v[94:97], v[134:137], v[198:201], v[94:97]
	v_mfma_f32_16x16x32_bf16 v[90:93], v[138:141], v[194:197], v[90:93]
	v_mfma_f32_16x16x32_bf16 v[90:93], v[142:145], v[198:201], v[90:93]
	v_mfma_f32_16x16x32_bf16 v[78:81], v[130:133], v[202:205], v[78:81]
	v_mfma_f32_16x16x32_bf16 v[78:81], v[134:137], v[216:219], v[78:81]
	v_mfma_f32_16x16x32_bf16 v[74:77], v[138:141], v[202:205], v[74:77]
	v_mfma_f32_16x16x32_bf16 v[74:77], v[142:145], v[216:219], v[74:77]
	s_setprio 0
	s_setprio 1
	v_mfma_f32_16x16x32_bf16 v[118:121], v[146:149], v[162:165], v[118:121]
	v_mfma_f32_16x16x32_bf16 v[118:121], v[150:153], v[166:169], v[118:121]
	v_mfma_f32_16x16x32_bf16 v[114:117], v[154:157], v[162:165], v[114:117]
	v_mfma_f32_16x16x32_bf16 v[114:117], v[158:161], v[166:169], v[114:117]
	v_mfma_f32_16x16x32_bf16 v[102:105], v[146:149], v[170:173], v[102:105]
	v_mfma_f32_16x16x32_bf16 v[102:105], v[150:153], v[174:177], v[102:105]
	v_mfma_f32_16x16x32_bf16 v[98:101], v[154:157], v[170:173], v[98:101]
	v_mfma_f32_16x16x32_bf16 v[98:101], v[158:161], v[174:177], v[98:101]
	v_mfma_f32_16x16x32_bf16 v[86:89], v[146:149], v[194:197], v[86:89]
	v_mfma_f32_16x16x32_bf16 v[86:89], v[150:153], v[198:201], v[86:89]
	v_mfma_f32_16x16x32_bf16 v[82:85], v[154:157], v[194:197], v[82:85]
	v_mfma_f32_16x16x32_bf16 v[82:85], v[158:161], v[198:201], v[82:85]
	v_mfma_f32_16x16x32_bf16 v[70:73], v[146:149], v[202:205], v[70:73]
	v_mfma_f32_16x16x32_bf16 v[70:73], v[150:153], v[216:219], v[70:73]
	v_mfma_f32_16x16x32_bf16 v[66:69], v[154:157], v[202:205], v[66:69]
	v_mfma_f32_16x16x32_bf16 v[66:69], v[158:161], v[216:219], v[66:69]
	s_setprio 0
	s_barrier
	s_add_i32 s0, s46, s37
	v_lshl_add_u64 v[220:221], s[2:3], 0, v[180:181]
	s_mov_b32 m0, s0
	ds_read_b128 v[162:165], v213 offset:16384
	ds_read_b128 v[166:169], v213 offset:17408
	ds_read_b128 v[170:173], v213 offset:18432
	ds_read_b128 v[174:177], v213 offset:19456
	ds_read_b128 v[194:197], v213 offset:20480
	ds_read_b128 v[198:201], v213 offset:21504
	ds_read_b128 v[202:205], v213 offset:22528
	ds_read_b128 v[216:219], v213 offset:23552
	global_load_lds_dwordx4 v[220:221], off
	s_add_i32 m0, s0, 0x2000
	s_add_u32 s0, s2, 0x40000
	v_lshl_add_u64 v[222:223], s[2:3], 0, v[184:185]
	s_addc_u32 s1, s3, 0
	s_add_i32 s52, s47, s37
	global_load_lds_dwordx4 v[222:223], off
	v_lshl_add_u64 v[224:225], s[0:1], 0, v[180:181]
	s_mov_b32 m0, s52
	v_lshl_add_u64 v[226:227], s[30:31], 0, v[182:183]
	global_load_lds_dwordx4 v[224:225], off
	v_lshl_add_u64 v[224:225], s[0:1], 0, v[184:185]
	s_add_i32 m0, s52, 0x2000
	s_nop 0
	global_load_lds_dwordx4 v[224:225], off
	v_lshl_add_u64 v[224:225], s[30:31], 0, v[178:179]
	s_mov_b32 m0, s27
	s_nop 0
	global_load_lds_dwordx4 v[224:225], off
	s_mov_b32 m0, s38
	s_nop 0
	global_load_lds_dwordx4 v[226:227], off
	s_waitcnt vmcnt(8)
	s_waitcnt lgkmcnt(0)
	s_barrier
	s_setprio 1
	s_waitcnt lgkmcnt(0)
	v_mfma_f32_16x16x32_bf16 v[62:65], v[130:133], v[162:165], v[62:65]
	v_mfma_f32_16x16x32_bf16 v[62:65], v[134:137], v[166:169], v[62:65]
	v_mfma_f32_16x16x32_bf16 v[58:61], v[138:141], v[162:165], v[58:61]
	v_mfma_f32_16x16x32_bf16 v[58:61], v[142:145], v[166:169], v[58:61]
	v_mfma_f32_16x16x32_bf16 v[46:49], v[130:133], v[170:173], v[46:49]
	v_mfma_f32_16x16x32_bf16 v[46:49], v[134:137], v[174:177], v[46:49]
	v_mfma_f32_16x16x32_bf16 v[42:45], v[138:141], v[170:173], v[42:45]
	v_mfma_f32_16x16x32_bf16 v[42:45], v[142:145], v[174:177], v[42:45]
	v_mfma_f32_16x16x32_bf16 v[30:33], v[130:133], v[194:197], v[30:33]
	v_mfma_f32_16x16x32_bf16 v[30:33], v[134:137], v[198:201], v[30:33]
	v_mfma_f32_16x16x32_bf16 v[26:29], v[138:141], v[194:197], v[26:29]
	v_mfma_f32_16x16x32_bf16 v[26:29], v[142:145], v[198:201], v[26:29]
	v_mfma_f32_16x16x32_bf16 v[14:17], v[130:133], v[202:205], v[14:17]
	v_mfma_f32_16x16x32_bf16 v[14:17], v[134:137], v[216:219], v[14:17]
	v_mfma_f32_16x16x32_bf16 v[10:13], v[138:141], v[202:205], v[10:13]
	v_mfma_f32_16x16x32_bf16 v[10:13], v[142:145], v[216:219], v[10:13]
	s_setprio 0
	s_setprio 1
	v_mfma_f32_16x16x32_bf16 v[54:57], v[146:149], v[162:165], v[54:57]
	v_mfma_f32_16x16x32_bf16 v[54:57], v[150:153], v[166:169], v[54:57]
	v_mfma_f32_16x16x32_bf16 v[50:53], v[154:157], v[162:165], v[50:53]
	v_mfma_f32_16x16x32_bf16 v[50:53], v[158:161], v[166:169], v[50:53]
	v_mfma_f32_16x16x32_bf16 v[38:41], v[146:149], v[170:173], v[38:41]
	v_mfma_f32_16x16x32_bf16 v[38:41], v[150:153], v[174:177], v[38:41]
	v_mfma_f32_16x16x32_bf16 v[34:37], v[154:157], v[170:173], v[34:37]
	v_mfma_f32_16x16x32_bf16 v[34:37], v[158:161], v[174:177], v[34:37]
	v_mfma_f32_16x16x32_bf16 v[22:25], v[146:149], v[194:197], v[22:25]
	v_mfma_f32_16x16x32_bf16 v[22:25], v[150:153], v[198:201], v[22:25]
	v_mfma_f32_16x16x32_bf16 v[18:21], v[154:157], v[194:197], v[18:21]
	v_mfma_f32_16x16x32_bf16 v[18:21], v[158:161], v[198:201], v[18:21]
	v_mfma_f32_16x16x32_bf16 v[6:9], v[146:149], v[202:205], v[6:9]
	v_mfma_f32_16x16x32_bf16 v[6:9], v[150:153], v[216:219], v[6:9]
	v_mfma_f32_16x16x32_bf16 v[2:5], v[154:157], v[202:205], v[2:5]
	v_mfma_f32_16x16x32_bf16 v[2:5], v[158:161], v[216:219], v[2:5]
	s_setprio 0
	s_barrier
	s_add_i32 s52, 0, 0x18000
	s_add_i32 s53, 0, 0x1c000
	v_add_u32_e32 v142, s52, v207
	v_add_u32_e32 v158, s53, v207
	ds_read_b128 v[130:133], v142
	ds_read_b128 v[134:137], v142 offset:1024
	ds_read_b128 v[138:141], v142 offset:2048
	ds_read_b128 v[142:145], v142 offset:3072
	ds_read_b128 v[146:149], v158
	ds_read_b128 v[150:153], v158 offset:1024
	ds_read_b128 v[154:157], v158 offset:2048
	ds_read_b128 v[158:161], v158 offset:3072
	s_add_u32 s0, s30, 0x40000
	s_addc_u32 s1, s31, 0
	s_mov_b32 m0, s39
	v_lshl_add_u64 v[228:229], s[0:1], 0, v[178:179]
	ds_read_b128 v[162:165], v213 offset:32768
	ds_read_b128 v[166:169], v213 offset:33792
	ds_read_b128 v[170:173], v213 offset:34816
	ds_read_b128 v[174:177], v213 offset:35840
	ds_read_b128 v[194:197], v213 offset:36864
	ds_read_b128 v[198:201], v213 offset:37888
	ds_read_b128 v[202:205], v213 offset:38912
	ds_read_b128 v[216:219], v213 offset:39936
	global_load_lds_dwordx4 v[228:229], off
	v_lshl_add_u64 v[228:229], s[0:1], 0, v[182:183]
	s_mov_b32 m0, s40
	s_nop 0
	global_load_lds_dwordx4 v[228:229], off
	s_waitcnt vmcnt(8)
	s_waitcnt lgkmcnt(0)
	s_barrier
	s_setprio 1
	s_waitcnt lgkmcnt(0)
	v_mfma_f32_16x16x32_bf16 v[126:129], v[130:133], v[162:165], v[126:129]
	v_mfma_f32_16x16x32_bf16 v[126:129], v[134:137], v[166:169], v[126:129]
	v_mfma_f32_16x16x32_bf16 v[122:125], v[138:141], v[162:165], v[122:125]
	v_mfma_f32_16x16x32_bf16 v[122:125], v[142:145], v[166:169], v[122:125]
	v_mfma_f32_16x16x32_bf16 v[110:113], v[130:133], v[170:173], v[110:113]
	v_mfma_f32_16x16x32_bf16 v[110:113], v[134:137], v[174:177], v[110:113]
	v_mfma_f32_16x16x32_bf16 v[106:109], v[138:141], v[170:173], v[106:109]
	v_mfma_f32_16x16x32_bf16 v[106:109], v[142:145], v[174:177], v[106:109]
	v_mfma_f32_16x16x32_bf16 v[94:97], v[130:133], v[194:197], v[94:97]
	v_mfma_f32_16x16x32_bf16 v[94:97], v[134:137], v[198:201], v[94:97]
	v_mfma_f32_16x16x32_bf16 v[90:93], v[138:141], v[194:197], v[90:93]
	v_mfma_f32_16x16x32_bf16 v[90:93], v[142:145], v[198:201], v[90:93]
	v_mfma_f32_16x16x32_bf16 v[78:81], v[130:133], v[202:205], v[78:81]
	v_mfma_f32_16x16x32_bf16 v[78:81], v[134:137], v[216:219], v[78:81]
	v_mfma_f32_16x16x32_bf16 v[74:77], v[138:141], v[202:205], v[74:77]
	v_mfma_f32_16x16x32_bf16 v[74:77], v[142:145], v[216:219], v[74:77]
	s_setprio 0
	s_setprio 1
	v_mfma_f32_16x16x32_bf16 v[118:121], v[146:149], v[162:165], v[118:121]
	v_mfma_f32_16x16x32_bf16 v[118:121], v[150:153], v[166:169], v[118:121]
	v_mfma_f32_16x16x32_bf16 v[114:117], v[154:157], v[162:165], v[114:117]
	v_mfma_f32_16x16x32_bf16 v[114:117], v[158:161], v[166:169], v[114:117]
	v_mfma_f32_16x16x32_bf16 v[102:105], v[146:149], v[170:173], v[102:105]
	v_mfma_f32_16x16x32_bf16 v[102:105], v[150:153], v[174:177], v[102:105]
	v_mfma_f32_16x16x32_bf16 v[98:101], v[154:157], v[170:173], v[98:101]
	v_mfma_f32_16x16x32_bf16 v[98:101], v[158:161], v[174:177], v[98:101]
	v_mfma_f32_16x16x32_bf16 v[86:89], v[146:149], v[194:197], v[86:89]
	v_mfma_f32_16x16x32_bf16 v[86:89], v[150:153], v[198:201], v[86:89]
	v_mfma_f32_16x16x32_bf16 v[82:85], v[154:157], v[194:197], v[82:85]
	v_mfma_f32_16x16x32_bf16 v[82:85], v[158:161], v[198:201], v[82:85]
	v_mfma_f32_16x16x32_bf16 v[70:73], v[146:149], v[202:205], v[70:73]
	v_mfma_f32_16x16x32_bf16 v[70:73], v[150:153], v[216:219], v[70:73]
	v_mfma_f32_16x16x32_bf16 v[66:69], v[154:157], v[202:205], v[66:69]
	v_mfma_f32_16x16x32_bf16 v[66:69], v[158:161], v[216:219], v[66:69]
	s_setprio 0
	s_barrier
	s_add_i32 s0, s52, s37
	v_lshl_add_u64 v[220:221], v[220:221], 0, s[14:15]
	s_mov_b32 m0, s0
	ds_read_b128 v[162:165], v213 offset:49152
	ds_read_b128 v[166:169], v213 offset:50176
	ds_read_b128 v[170:173], v213 offset:51200
	ds_read_b128 v[174:177], v213 offset:52224
	ds_read_b128 v[194:197], v213 offset:53248
	ds_read_b128 v[198:201], v213 offset:54272
	ds_read_b128 v[202:205], v213 offset:55296
	ds_read_b128 v[216:219], v213 offset:56320
	global_load_lds_dwordx4 v[220:221], off
	s_add_i32 m0, s0, 0x2000
	s_add_u32 s0, s2, 0x40080
	v_lshl_add_u64 v[220:221], v[222:223], 0, s[14:15]
	s_addc_u32 s1, s3, 0
	s_add_i32 s2, s53, s37
	global_load_lds_dwordx4 v[220:221], off
	v_lshl_add_u64 v[220:221], s[0:1], 0, v[180:181]
	s_mov_b32 m0, s2
	s_nop 0
	global_load_lds_dwordx4 v[220:221], off
	v_lshl_add_u64 v[220:221], s[0:1], 0, v[184:185]
	s_add_i32 m0, s2, 0x2000
	s_nop 0
	global_load_lds_dwordx4 v[220:221], off
	v_lshl_add_u64 v[220:221], v[224:225], 0, s[14:15]
	s_mov_b32 m0, s42
	s_nop 0
	global_load_lds_dwordx4 v[220:221], off
	v_lshl_add_u64 v[220:221], v[226:227], 0, s[14:15]
	s_mov_b32 m0, s43
	s_nop 0
	global_load_lds_dwordx4 v[220:221], off
	s_waitcnt vmcnt(8)
	s_waitcnt lgkmcnt(0)
	s_barrier
	s_setprio 1
	s_waitcnt lgkmcnt(0)
	v_mfma_f32_16x16x32_bf16 v[62:65], v[130:133], v[162:165], v[62:65]
	v_mfma_f32_16x16x32_bf16 v[62:65], v[134:137], v[166:169], v[62:65]
	v_mfma_f32_16x16x32_bf16 v[58:61], v[138:141], v[162:165], v[58:61]
	v_mfma_f32_16x16x32_bf16 v[58:61], v[142:145], v[166:169], v[58:61]
	v_mfma_f32_16x16x32_bf16 v[46:49], v[130:133], v[170:173], v[46:49]
	v_mfma_f32_16x16x32_bf16 v[46:49], v[134:137], v[174:177], v[46:49]
	v_mfma_f32_16x16x32_bf16 v[42:45], v[138:141], v[170:173], v[42:45]
	v_mfma_f32_16x16x32_bf16 v[42:45], v[142:145], v[174:177], v[42:45]
	v_mfma_f32_16x16x32_bf16 v[30:33], v[130:133], v[194:197], v[30:33]
	v_mfma_f32_16x16x32_bf16 v[30:33], v[134:137], v[198:201], v[30:33]
	v_mfma_f32_16x16x32_bf16 v[26:29], v[138:141], v[194:197], v[26:29]
	v_mfma_f32_16x16x32_bf16 v[26:29], v[142:145], v[198:201], v[26:29]
	v_mfma_f32_16x16x32_bf16 v[14:17], v[130:133], v[202:205], v[14:17]
	v_mfma_f32_16x16x32_bf16 v[14:17], v[134:137], v[216:219], v[14:17]
	v_mfma_f32_16x16x32_bf16 v[10:13], v[138:141], v[202:205], v[10:13]
	v_mfma_f32_16x16x32_bf16 v[10:13], v[142:145], v[216:219], v[10:13]
	s_setprio 0
	s_setprio 1
	v_mfma_f32_16x16x32_bf16 v[54:57], v[146:149], v[162:165], v[54:57]
	v_mfma_f32_16x16x32_bf16 v[54:57], v[150:153], v[166:169], v[54:57]
	v_mfma_f32_16x16x32_bf16 v[50:53], v[154:157], v[162:165], v[50:53]
	v_mfma_f32_16x16x32_bf16 v[50:53], v[158:161], v[166:169], v[50:53]
	v_mfma_f32_16x16x32_bf16 v[38:41], v[146:149], v[170:173], v[38:41]
	v_mfma_f32_16x16x32_bf16 v[38:41], v[150:153], v[174:177], v[38:41]
	v_mfma_f32_16x16x32_bf16 v[34:37], v[154:157], v[170:173], v[34:37]
	v_mfma_f32_16x16x32_bf16 v[34:37], v[158:161], v[174:177], v[34:37]
	v_mfma_f32_16x16x32_bf16 v[22:25], v[146:149], v[194:197], v[22:25]
	v_mfma_f32_16x16x32_bf16 v[22:25], v[150:153], v[198:201], v[22:25]
	v_mfma_f32_16x16x32_bf16 v[18:21], v[154:157], v[194:197], v[18:21]
	v_mfma_f32_16x16x32_bf16 v[18:21], v[158:161], v[198:201], v[18:21]
	v_mfma_f32_16x16x32_bf16 v[6:9], v[146:149], v[202:205], v[6:9]
	v_mfma_f32_16x16x32_bf16 v[6:9], v[150:153], v[216:219], v[6:9]
	v_mfma_f32_16x16x32_bf16 v[2:5], v[154:157], v[202:205], v[2:5]
	v_mfma_f32_16x16x32_bf16 v[2:5], v[158:161], v[216:219], v[2:5]
	s_setprio 0
	s_barrier
	s_add_i32 s51, s51, 2
	s_add_u32 s28, s28, 0x100
	s_addc_u32 s29, s29, 0
	s_add_u32 s49, s49, 0x100
	s_addc_u32 s50, s50, 0
	s_cmp_gt_u32 s51, 13
	s_cbranch_scc0 .LBB0_382
	s_and_b64 vcc, exec, s[16:17]
	s_cbranch_vccz .LBB0_385
	s_barrier

.LBB0_471:
	ds_read_b128 v[148:151], v167
	ds_read_b128 v[152:155], v167 offset:1024
	ds_read_b128 v[156:159], v167 offset:2048
	ds_read_b128 v[160:163], v167 offset:3072
	ds_read_b128 v[172:175], v168
	ds_read_b128 v[176:179], v168 offset:1024
	ds_read_b128 v[180:183], v168 offset:2048
	ds_read_b128 v[184:187], v168 offset:3072
	s_add_u32 s0, s28, 0xfffc0080
	s_addc_u32 s1, s29, -1
	s_cmp_eq_u32 s53, 12
	s_cselect_b32 s31, s21, s1
	s_cselect_b32 s30, s49, s0
	s_cselect_b32 s3, s19, s52
	s_cselect_b32 s2, s50, s51
	v_lshl_add_u64 v[220:221], s[28:29], 0, v[140:141]
	s_add_i32 m0, s38, 0xc000
	ds_read_b128 v[188:191], v169
	ds_read_b128 v[192:195], v169 offset:1024
	ds_read_b128 v[196:199], v169 offset:2048
	ds_read_b128 v[200:203], v169 offset:3072
	ds_read_b128 v[204:207], v169 offset:4096
	ds_read_b128 v[208:211], v169 offset:5120
	ds_read_b128 v[212:215], v169 offset:6144
	ds_read_b128 v[216:219], v169 offset:7168
	global_load_lds_dwordx4 v[220:221], off
	v_lshl_add_u64 v[220:221], s[28:29], 0, v[142:143]
	s_add_i32 m0, s38, 0xe000
	s_nop 0
	global_load_lds_dwordx4 v[220:221], off
	s_waitcnt vmcnt(8)
	s_waitcnt lgkmcnt(0)
	s_barrier
	s_setprio 1
	s_waitcnt lgkmcnt(0)
	v_mfma_f32_16x16x32_bf16 v[126:129], v[148:151], v[188:191], v[126:129]
	v_mfma_f32_16x16x32_bf16 v[126:129], v[152:155], v[192:195], v[126:129]
	v_mfma_f32_16x16x32_bf16 v[118:121], v[156:159], v[188:191], v[118:121]
	v_mfma_f32_16x16x32_bf16 v[118:121], v[160:163], v[192:195], v[118:121]
	v_mfma_f32_16x16x32_bf16 v[110:113], v[148:151], v[196:199], v[110:113]
	v_mfma_f32_16x16x32_bf16 v[110:113], v[152:155], v[200:203], v[110:113]
	v_mfma_f32_16x16x32_bf16 v[102:105], v[156:159], v[196:199], v[102:105]
	v_mfma_f32_16x16x32_bf16 v[102:105], v[160:163], v[200:203], v[102:105]
	v_mfma_f32_16x16x32_bf16 v[94:97], v[148:151], v[204:207], v[94:97]
	v_mfma_f32_16x16x32_bf16 v[94:97], v[152:155], v[208:211], v[94:97]
	v_mfma_f32_16x16x32_bf16 v[86:89], v[156:159], v[204:207], v[86:89]
	v_mfma_f32_16x16x32_bf16 v[86:89], v[160:163], v[208:211], v[86:89]
	v_mfma_f32_16x16x32_bf16 v[78:81], v[148:151], v[212:215], v[78:81]
	v_mfma_f32_16x16x32_bf16 v[78:81], v[152:155], v[216:219], v[78:81]
	v_mfma_f32_16x16x32_bf16 v[70:73], v[156:159], v[212:215], v[70:73]
	v_mfma_f32_16x16x32_bf16 v[70:73], v[160:163], v[216:219], v[70:73]
	s_setprio 0
	s_setprio 1
	v_mfma_f32_16x16x32_bf16 v[122:125], v[172:175], v[188:191], v[122:125]
	v_mfma_f32_16x16x32_bf16 v[122:125], v[176:179], v[192:195], v[122:125]
	v_mfma_f32_16x16x32_bf16 v[114:117], v[180:183], v[188:191], v[114:117]
	v_mfma_f32_16x16x32_bf16 v[114:117], v[184:187], v[192:195], v[114:117]
	v_mfma_f32_16x16x32_bf16 v[106:109], v[172:175], v[196:199], v[106:109]
	v_mfma_f32_16x16x32_bf16 v[106:109], v[176:179], v[200:203], v[106:109]
	v_mfma_f32_16x16x32_bf16 v[98:101], v[180:183], v[196:199], v[98:101]
	v_mfma_f32_16x16x32_bf16 v[98:101], v[184:187], v[200:203], v[98:101]
	v_mfma_f32_16x16x32_bf16 v[90:93], v[172:175], v[204:207], v[90:93]
	v_mfma_f32_16x16x32_bf16 v[90:93], v[176:179], v[208:211], v[90:93]
	v_mfma_f32_16x16x32_bf16 v[82:85], v[180:183], v[204:207], v[82:85]
	v_mfma_f32_16x16x32_bf16 v[82:85], v[184:187], v[208:211], v[82:85]
	v_mfma_f32_16x16x32_bf16 v[74:77], v[172:175], v[212:215], v[74:77]
	v_mfma_f32_16x16x32_bf16 v[74:77], v[176:179], v[216:219], v[74:77]
	v_mfma_f32_16x16x32_bf16 v[66:69], v[180:183], v[212:215], v[66:69]
	v_mfma_f32_16x16x32_bf16 v[66:69], v[184:187], v[216:219], v[66:69]
	s_setprio 0
	s_barrier
	s_add_i32 s0, s45, s35
	v_lshl_add_u64 v[220:221], s[2:3], 0, v[134:135]
	s_mov_b32 m0, s0
	ds_read_b128 v[188:191], v169 offset:16384
	ds_read_b128 v[192:195], v169 offset:17408
	ds_read_b128 v[196:199], v169 offset:18432
	ds_read_b128 v[200:203], v169 offset:19456
	ds_read_b128 v[204:207], v169 offset:20480
	ds_read_b128 v[208:211], v169 offset:21504
	ds_read_b128 v[212:215], v169 offset:22528
	ds_read_b128 v[216:219], v169 offset:23552
	global_load_lds_dwordx4 v[220:221], off
	s_add_i32 m0, s0, 0x2000
	s_add_u32 s0, s2, 0x40000
	v_lshl_add_u64 v[222:223], s[2:3], 0, v[130:131]
	s_addc_u32 s1, s3, 0
	s_add_i32 s54, s46, s35
	global_load_lds_dwordx4 v[222:223], off
	v_lshl_add_u64 v[224:225], s[0:1], 0, v[134:135]
	s_mov_b32 m0, s54
	v_lshl_add_u64 v[226:227], s[30:31], 0, v[132:133]
	global_load_lds_dwordx4 v[224:225], off
	v_lshl_add_u64 v[224:225], s[0:1], 0, v[130:131]
	s_add_i32 m0, s54, 0x2000
	s_nop 0
	global_load_lds_dwordx4 v[224:225], off
	v_lshl_add_u64 v[224:225], s[30:31], 0, v[136:137]
	s_mov_b32 m0, s38
	s_nop 0
	global_load_lds_dwordx4 v[224:225], off
	s_mov_b32 m0, s39
	s_nop 0
	global_load_lds_dwordx4 v[226:227], off
	s_waitcnt vmcnt(8)
	s_waitcnt lgkmcnt(0)
	s_barrier
	s_setprio 1
	s_waitcnt lgkmcnt(0)
	v_mfma_f32_16x16x32_bf16 v[62:65], v[148:151], v[188:191], v[62:65]
	v_mfma_f32_16x16x32_bf16 v[62:65], v[152:155], v[192:195], v[62:65]
	v_mfma_f32_16x16x32_bf16 v[54:57], v[156:159], v[188:191], v[54:57]
	v_mfma_f32_16x16x32_bf16 v[54:57], v[160:163], v[192:195], v[54:57]
	v_mfma_f32_16x16x32_bf16 v[46:49], v[148:151], v[196:199], v[46:49]
	v_mfma_f32_16x16x32_bf16 v[46:49], v[152:155], v[200:203], v[46:49]
	v_mfma_f32_16x16x32_bf16 v[38:41], v[156:159], v[196:199], v[38:41]
	v_mfma_f32_16x16x32_bf16 v[38:41], v[160:163], v[200:203], v[38:41]
	v_mfma_f32_16x16x32_bf16 v[30:33], v[148:151], v[204:207], v[30:33]
	v_mfma_f32_16x16x32_bf16 v[30:33], v[152:155], v[208:211], v[30:33]
	v_mfma_f32_16x16x32_bf16 v[22:25], v[156:159], v[204:207], v[22:25]
	v_mfma_f32_16x16x32_bf16 v[22:25], v[160:163], v[208:211], v[22:25]
	v_mfma_f32_16x16x32_bf16 v[14:17], v[148:151], v[212:215], v[14:17]
	v_mfma_f32_16x16x32_bf16 v[14:17], v[152:155], v[216:219], v[14:17]
	v_mfma_f32_16x16x32_bf16 v[6:9], v[156:159], v[212:215], v[6:9]
	v_mfma_f32_16x16x32_bf16 v[6:9], v[160:163], v[216:219], v[6:9]
	s_setprio 0
	s_setprio 1
	v_mfma_f32_16x16x32_bf16 v[58:61], v[172:175], v[188:191], v[58:61]
	v_mfma_f32_16x16x32_bf16 v[58:61], v[176:179], v[192:195], v[58:61]
	v_mfma_f32_16x16x32_bf16 v[50:53], v[180:183], v[188:191], v[50:53]
	v_mfma_f32_16x16x32_bf16 v[50:53], v[184:187], v[192:195], v[50:53]
	v_mfma_f32_16x16x32_bf16 v[42:45], v[172:175], v[196:199], v[42:45]
	v_mfma_f32_16x16x32_bf16 v[42:45], v[176:179], v[200:203], v[42:45]
	v_mfma_f32_16x16x32_bf16 v[34:37], v[180:183], v[196:199], v[34:37]
	v_mfma_f32_16x16x32_bf16 v[34:37], v[184:187], v[200:203], v[34:37]
	v_mfma_f32_16x16x32_bf16 v[26:29], v[172:175], v[204:207], v[26:29]
	v_mfma_f32_16x16x32_bf16 v[26:29], v[176:179], v[208:211], v[26:29]
	v_mfma_f32_16x16x32_bf16 v[18:21], v[180:183], v[204:207], v[18:21]
	v_mfma_f32_16x16x32_bf16 v[18:21], v[184:187], v[208:211], v[18:21]
	v_mfma_f32_16x16x32_bf16 v[10:13], v[172:175], v[212:215], v[10:13]
	v_mfma_f32_16x16x32_bf16 v[10:13], v[176:179], v[216:219], v[10:13]
	v_mfma_f32_16x16x32_bf16 v[2:5], v[180:183], v[212:215], v[2:5]
	v_mfma_f32_16x16x32_bf16 v[2:5], v[184:187], v[216:219], v[2:5]
	s_setprio 0
	s_barrier
	s_add_i32 s54, 0, 0x18000
	s_add_i32 s55, 0, 0x1c000
	v_add_u32_e32 v160, s54, v166
	v_add_u32_e32 v171, s55, v166
	ds_read_b128 v[148:151], v160
	ds_read_b128 v[152:155], v160 offset:1024
	ds_read_b128 v[156:159], v160 offset:2048
	ds_read_b128 v[160:163], v160 offset:3072
	ds_read_b128 v[172:175], v171
	ds_read_b128 v[176:179], v171 offset:1024
	ds_read_b128 v[180:183], v171 offset:2048
	ds_read_b128 v[184:187], v171 offset:3072
	s_add_u32 s0, s30, 0x40000
	s_addc_u32 s1, s31, 0
	s_mov_b32 m0, s40
	v_lshl_add_u64 v[228:229], s[0:1], 0, v[136:137]
	ds_read_b128 v[188:191], v169 offset:32768
	ds_read_b128 v[192:195], v169 offset:33792
	ds_read_b128 v[196:199], v169 offset:34816
	ds_read_b128 v[200:203], v169 offset:35840
	ds_read_b128 v[204:207], v169 offset:36864
	ds_read_b128 v[208:211], v169 offset:37888
	ds_read_b128 v[212:215], v169 offset:38912
	ds_read_b128 v[216:219], v169 offset:39936
	global_load_lds_dwordx4 v[228:229], off
	v_lshl_add_u64 v[228:229], s[0:1], 0, v[132:133]
	s_mov_b32 m0, s41
	s_nop 0
	global_load_lds_dwordx4 v[228:229], off
	s_waitcnt vmcnt(8)
	s_waitcnt lgkmcnt(0)
	s_barrier
	s_setprio 1
	s_waitcnt lgkmcnt(0)
	v_mfma_f32_16x16x32_bf16 v[126:129], v[148:151], v[188:191], v[126:129]
	v_mfma_f32_16x16x32_bf16 v[126:129], v[152:155], v[192:195], v[126:129]
	v_mfma_f32_16x16x32_bf16 v[118:121], v[156:159], v[188:191], v[118:121]
	v_mfma_f32_16x16x32_bf16 v[118:121], v[160:163], v[192:195], v[118:121]
	v_mfma_f32_16x16x32_bf16 v[110:113], v[148:151], v[196:199], v[110:113]
	v_mfma_f32_16x16x32_bf16 v[110:113], v[152:155], v[200:203], v[110:113]
	v_mfma_f32_16x16x32_bf16 v[102:105], v[156:159], v[196:199], v[102:105]
	v_mfma_f32_16x16x32_bf16 v[102:105], v[160:163], v[200:203], v[102:105]
	v_mfma_f32_16x16x32_bf16 v[94:97], v[148:151], v[204:207], v[94:97]
	v_mfma_f32_16x16x32_bf16 v[94:97], v[152:155], v[208:211], v[94:97]
	v_mfma_f32_16x16x32_bf16 v[86:89], v[156:159], v[204:207], v[86:89]
	v_mfma_f32_16x16x32_bf16 v[86:89], v[160:163], v[208:211], v[86:89]
	v_mfma_f32_16x16x32_bf16 v[78:81], v[148:151], v[212:215], v[78:81]
	v_mfma_f32_16x16x32_bf16 v[78:81], v[152:155], v[216:219], v[78:81]
	v_mfma_f32_16x16x32_bf16 v[70:73], v[156:159], v[212:215], v[70:73]
	v_mfma_f32_16x16x32_bf16 v[70:73], v[160:163], v[216:219], v[70:73]
	s_setprio 0
	s_setprio 1
	v_mfma_f32_16x16x32_bf16 v[122:125], v[172:175], v[188:191], v[122:125]
	v_mfma_f32_16x16x32_bf16 v[122:125], v[176:179], v[192:195], v[122:125]
	v_mfma_f32_16x16x32_bf16 v[114:117], v[180:183], v[188:191], v[114:117]
	v_mfma_f32_16x16x32_bf16 v[114:117], v[184:187], v[192:195], v[114:117]
	v_mfma_f32_16x16x32_bf16 v[106:109], v[172:175], v[196:199], v[106:109]
	v_mfma_f32_16x16x32_bf16 v[106:109], v[176:179], v[200:203], v[106:109]
	v_mfma_f32_16x16x32_bf16 v[98:101], v[180:183], v[196:199], v[98:101]
	v_mfma_f32_16x16x32_bf16 v[98:101], v[184:187], v[200:203], v[98:101]
	v_mfma_f32_16x16x32_bf16 v[90:93], v[172:175], v[204:207], v[90:93]
	v_mfma_f32_16x16x32_bf16 v[90:93], v[176:179], v[208:211], v[90:93]
	v_mfma_f32_16x16x32_bf16 v[82:85], v[180:183], v[204:207], v[82:85]
	v_mfma_f32_16x16x32_bf16 v[82:85], v[184:187], v[208:211], v[82:85]
	v_mfma_f32_16x16x32_bf16 v[74:77], v[172:175], v[212:215], v[74:77]
	v_mfma_f32_16x16x32_bf16 v[74:77], v[176:179], v[216:219], v[74:77]
	v_mfma_f32_16x16x32_bf16 v[66:69], v[180:183], v[212:215], v[66:69]
	v_mfma_f32_16x16x32_bf16 v[66:69], v[184:187], v[216:219], v[66:69]
	s_setprio 0
	s_barrier
	s_add_i32 s0, s54, s35
	v_lshl_add_u64 v[220:221], v[220:221], 0, s[14:15]
	s_mov_b32 m0, s0
	ds_read_b128 v[188:191], v169 offset:49152
	ds_read_b128 v[192:195], v169 offset:50176
	ds_read_b128 v[196:199], v169 offset:51200
	ds_read_b128 v[200:203], v169 offset:52224
	ds_read_b128 v[204:207], v169 offset:53248
	ds_read_b128 v[208:211], v169 offset:54272
	ds_read_b128 v[212:215], v169 offset:55296
	ds_read_b128 v[216:219], v169 offset:56320
	global_load_lds_dwordx4 v[220:221], off
	s_add_i32 m0, s0, 0x2000
	s_add_u32 s0, s2, 0x40080
	v_lshl_add_u64 v[220:221], v[222:223], 0, s[14:15]
	s_addc_u32 s1, s3, 0
	s_add_i32 s2, s55, s35
	global_load_lds_dwordx4 v[220:221], off
	v_lshl_add_u64 v[220:221], s[0:1], 0, v[134:135]
	s_mov_b32 m0, s2
	s_nop 0
	global_load_lds_dwordx4 v[220:221], off
	v_lshl_add_u64 v[220:221], s[0:1], 0, v[130:131]
	s_add_i32 m0, s2, 0x2000
	s_nop 0
	global_load_lds_dwordx4 v[220:221], off
	v_lshl_add_u64 v[220:221], v[224:225], 0, s[14:15]
	s_mov_b32 m0, s42
	s_nop 0
	global_load_lds_dwordx4 v[220:221], off
	v_lshl_add_u64 v[220:221], v[226:227], 0, s[14:15]
	s_mov_b32 m0, s43
	s_nop 0
	global_load_lds_dwordx4 v[220:221], off
	s_waitcnt vmcnt(8)
	s_waitcnt lgkmcnt(0)
	s_barrier
	s_setprio 1
	s_waitcnt lgkmcnt(0)
	v_mfma_f32_16x16x32_bf16 v[62:65], v[148:151], v[188:191], v[62:65]
	v_mfma_f32_16x16x32_bf16 v[62:65], v[152:155], v[192:195], v[62:65]
	v_mfma_f32_16x16x32_bf16 v[54:57], v[156:159], v[188:191], v[54:57]
	v_mfma_f32_16x16x32_bf16 v[54:57], v[160:163], v[192:195], v[54:57]
	v_mfma_f32_16x16x32_bf16 v[46:49], v[148:151], v[196:199], v[46:49]
	v_mfma_f32_16x16x32_bf16 v[46:49], v[152:155], v[200:203], v[46:49]
	v_mfma_f32_16x16x32_bf16 v[38:41], v[156:159], v[196:199], v[38:41]
	v_mfma_f32_16x16x32_bf16 v[38:41], v[160:163], v[200:203], v[38:41]
	v_mfma_f32_16x16x32_bf16 v[30:33], v[148:151], v[204:207], v[30:33]
	v_mfma_f32_16x16x32_bf16 v[30:33], v[152:155], v[208:211], v[30:33]
	v_mfma_f32_16x16x32_bf16 v[22:25], v[156:159], v[204:207], v[22:25]
	v_mfma_f32_16x16x32_bf16 v[22:25], v[160:163], v[208:211], v[22:25]
	v_mfma_f32_16x16x32_bf16 v[14:17], v[148:151], v[212:215], v[14:17]
	v_mfma_f32_16x16x32_bf16 v[14:17], v[152:155], v[216:219], v[14:17]
	v_mfma_f32_16x16x32_bf16 v[6:9], v[156:159], v[212:215], v[6:9]
	v_mfma_f32_16x16x32_bf16 v[6:9], v[160:163], v[216:219], v[6:9]
	s_setprio 0
	s_setprio 1
	v_mfma_f32_16x16x32_bf16 v[58:61], v[172:175], v[188:191], v[58:61]
	v_mfma_f32_16x16x32_bf16 v[58:61], v[176:179], v[192:195], v[58:61]
	v_mfma_f32_16x16x32_bf16 v[50:53], v[180:183], v[188:191], v[50:53]
	v_mfma_f32_16x16x32_bf16 v[50:53], v[184:187], v[192:195], v[50:53]
	v_mfma_f32_16x16x32_bf16 v[42:45], v[172:175], v[196:199], v[42:45]
	v_mfma_f32_16x16x32_bf16 v[42:45], v[176:179], v[200:203], v[42:45]
	v_mfma_f32_16x16x32_bf16 v[34:37], v[180:183], v[196:199], v[34:37]
	v_mfma_f32_16x16x32_bf16 v[34:37], v[184:187], v[200:203], v[34:37]
	v_mfma_f32_16x16x32_bf16 v[26:29], v[172:175], v[204:207], v[26:29]
	v_mfma_f32_16x16x32_bf16 v[26:29], v[176:179], v[208:211], v[26:29]
	v_mfma_f32_16x16x32_bf16 v[18:21], v[180:183], v[204:207], v[18:21]
	v_mfma_f32_16x16x32_bf16 v[18:21], v[184:187], v[208:211], v[18:21]
	v_mfma_f32_16x16x32_bf16 v[10:13], v[172:175], v[212:215], v[10:13]
	v_mfma_f32_16x16x32_bf16 v[10:13], v[176:179], v[216:219], v[10:13]
	v_mfma_f32_16x16x32_bf16 v[2:5], v[180:183], v[212:215], v[2:5]
	v_mfma_f32_16x16x32_bf16 v[2:5], v[184:187], v[216:219], v[2:5]
	s_setprio 0
	s_barrier
	s_add_i32 s53, s53, 2
	s_add_u32 s28, s28, 0x100
	s_addc_u32 s29, s29, 0
	s_add_u32 s51, s51, 0x100
	s_addc_u32 s52, s52, 0
	s_cmp_gt_u32 s53, 13
	s_cbranch_scc0 .LBB0_471
	s_and_b64 vcc, exec, s[16:17]
	s_cbranch_vccz .LBB0_474
	s_barrier

.LBB0_584:
	ds_read_b128 v[130:133], v187
	ds_read_b128 v[134:137], v187 offset:1024
	ds_read_b128 v[138:141], v187 offset:2048
	ds_read_b128 v[142:145], v187 offset:3072
	ds_read_b128 v[146:149], v188
	ds_read_b128 v[150:153], v188 offset:1024
	ds_read_b128 v[170:173], v188 offset:2048
	ds_read_b128 v[174:177], v188 offset:3072
	s_add_u32 s0, s22, 0xfff50080
	s_addc_u32 s1, s23, -1
	s_cmp_eq_u32 s47, 40
	s_cselect_b32 s25, s9, s1
	s_cselect_b32 s24, s8, s0
	s_cselect_b32 s3, s21, s46
	s_cselect_b32 s2, s20, s45
	v_lshl_add_u64 v[220:221], s[22:23], 0, v[162:163]
	s_add_i32 m0, s31, 0xc000
	ds_read_b128 v[178:181], v189
	ds_read_b128 v[192:195], v189 offset:1024
	ds_read_b128 v[196:199], v189 offset:2048
	ds_read_b128 v[200:203], v189 offset:3072
	ds_read_b128 v[204:207], v189 offset:4096
	ds_read_b128 v[208:211], v189 offset:5120
	ds_read_b128 v[212:215], v189 offset:6144
	ds_read_b128 v[216:219], v189 offset:7168
	global_load_lds_dwordx4 v[220:221], off
	v_lshl_add_u64 v[220:221], s[22:23], 0, v[164:165]
	s_add_i32 m0, s31, 0xe000
	s_nop 0
	global_load_lds_dwordx4 v[220:221], off
	s_waitcnt vmcnt(8)
	s_waitcnt lgkmcnt(0)
	s_barrier
	s_setprio 1
	s_waitcnt lgkmcnt(0)
	v_mfma_f32_16x16x32_bf16 v[126:129], v[130:133], v[178:181], v[126:129]
	v_mfma_f32_16x16x32_bf16 v[126:129], v[134:137], v[192:195], v[126:129]
	v_mfma_f32_16x16x32_bf16 v[122:125], v[138:141], v[178:181], v[122:125]
	v_mfma_f32_16x16x32_bf16 v[122:125], v[142:145], v[192:195], v[122:125]
	v_mfma_f32_16x16x32_bf16 v[110:113], v[130:133], v[196:199], v[110:113]
	v_mfma_f32_16x16x32_bf16 v[110:113], v[134:137], v[200:203], v[110:113]
	v_mfma_f32_16x16x32_bf16 v[106:109], v[138:141], v[196:199], v[106:109]
	v_mfma_f32_16x16x32_bf16 v[106:109], v[142:145], v[200:203], v[106:109]
	v_mfma_f32_16x16x32_bf16 v[94:97], v[130:133], v[204:207], v[94:97]
	v_mfma_f32_16x16x32_bf16 v[94:97], v[134:137], v[208:211], v[94:97]
	v_mfma_f32_16x16x32_bf16 v[90:93], v[138:141], v[204:207], v[90:93]
	v_mfma_f32_16x16x32_bf16 v[90:93], v[142:145], v[208:211], v[90:93]
	v_mfma_f32_16x16x32_bf16 v[78:81], v[130:133], v[212:215], v[78:81]
	v_mfma_f32_16x16x32_bf16 v[78:81], v[134:137], v[216:219], v[78:81]
	v_mfma_f32_16x16x32_bf16 v[74:77], v[138:141], v[212:215], v[74:77]
	v_mfma_f32_16x16x32_bf16 v[74:77], v[142:145], v[216:219], v[74:77]
	s_setprio 0
	s_setprio 1
	v_mfma_f32_16x16x32_bf16 v[118:121], v[146:149], v[178:181], v[118:121]
	v_mfma_f32_16x16x32_bf16 v[118:121], v[150:153], v[192:195], v[118:121]
	v_mfma_f32_16x16x32_bf16 v[114:117], v[170:173], v[178:181], v[114:117]
	v_mfma_f32_16x16x32_bf16 v[114:117], v[174:177], v[192:195], v[114:117]
	v_mfma_f32_16x16x32_bf16 v[102:105], v[146:149], v[196:199], v[102:105]
	v_mfma_f32_16x16x32_bf16 v[102:105], v[150:153], v[200:203], v[102:105]
	v_mfma_f32_16x16x32_bf16 v[98:101], v[170:173], v[196:199], v[98:101]
	v_mfma_f32_16x16x32_bf16 v[98:101], v[174:177], v[200:203], v[98:101]
	v_mfma_f32_16x16x32_bf16 v[86:89], v[146:149], v[204:207], v[86:89]
	v_mfma_f32_16x16x32_bf16 v[86:89], v[150:153], v[208:211], v[86:89]
	v_mfma_f32_16x16x32_bf16 v[82:85], v[170:173], v[204:207], v[82:85]
	v_mfma_f32_16x16x32_bf16 v[82:85], v[174:177], v[208:211], v[82:85]
	v_mfma_f32_16x16x32_bf16 v[70:73], v[146:149], v[212:215], v[70:73]
	v_mfma_f32_16x16x32_bf16 v[70:73], v[150:153], v[216:219], v[70:73]
	v_mfma_f32_16x16x32_bf16 v[66:69], v[170:173], v[212:215], v[66:69]
	v_mfma_f32_16x16x32_bf16 v[66:69], v[174:177], v[216:219], v[66:69]
	s_setprio 0
	s_barrier
	s_add_i32 s0, s41, s30
	v_lshl_add_u64 v[220:221], s[2:3], 0, v[156:157]
	s_mov_b32 m0, s0
	ds_read_b128 v[178:181], v189 offset:16384
	ds_read_b128 v[192:195], v189 offset:17408
	ds_read_b128 v[196:199], v189 offset:18432
	ds_read_b128 v[200:203], v189 offset:19456
	ds_read_b128 v[204:207], v189 offset:20480
	ds_read_b128 v[208:211], v189 offset:21504
	ds_read_b128 v[212:215], v189 offset:22528
	ds_read_b128 v[216:219], v189 offset:23552
	global_load_lds_dwordx4 v[220:221], off
	s_add_i32 m0, s0, 0x2000
	s_add_u32 s0, s2, 0xb0000
	v_lshl_add_u64 v[222:223], s[2:3], 0, v[160:161]
	s_addc_u32 s1, s3, 0
	s_add_i32 s48, s42, s30
	global_load_lds_dwordx4 v[222:223], off
	v_lshl_add_u64 v[224:225], s[0:1], 0, v[156:157]
	s_mov_b32 m0, s48
	v_lshl_add_u64 v[226:227], s[24:25], 0, v[158:159]
	global_load_lds_dwordx4 v[224:225], off
	v_lshl_add_u64 v[224:225], s[0:1], 0, v[160:161]
	s_add_i32 m0, s48, 0x2000
	s_nop 0
	global_load_lds_dwordx4 v[224:225], off
	v_lshl_add_u64 v[224:225], s[24:25], 0, v[154:155]
	s_mov_b32 m0, s31
	s_nop 0
	global_load_lds_dwordx4 v[224:225], off
	s_mov_b32 m0, s33
	s_nop 0
	global_load_lds_dwordx4 v[226:227], off
	s_waitcnt vmcnt(8)
	s_waitcnt lgkmcnt(0)
	s_barrier
	s_setprio 1
	s_waitcnt lgkmcnt(0)
	v_mfma_f32_16x16x32_bf16 v[62:65], v[130:133], v[178:181], v[62:65]
	v_mfma_f32_16x16x32_bf16 v[62:65], v[134:137], v[192:195], v[62:65]
	v_mfma_f32_16x16x32_bf16 v[58:61], v[138:141], v[178:181], v[58:61]
	v_mfma_f32_16x16x32_bf16 v[58:61], v[142:145], v[192:195], v[58:61]
	v_mfma_f32_16x16x32_bf16 v[46:49], v[130:133], v[196:199], v[46:49]
	v_mfma_f32_16x16x32_bf16 v[46:49], v[134:137], v[200:203], v[46:49]
	v_mfma_f32_16x16x32_bf16 v[42:45], v[138:141], v[196:199], v[42:45]
	v_mfma_f32_16x16x32_bf16 v[42:45], v[142:145], v[200:203], v[42:45]
	v_mfma_f32_16x16x32_bf16 v[30:33], v[130:133], v[204:207], v[30:33]
	v_mfma_f32_16x16x32_bf16 v[30:33], v[134:137], v[208:211], v[30:33]
	v_mfma_f32_16x16x32_bf16 v[26:29], v[138:141], v[204:207], v[26:29]
	v_mfma_f32_16x16x32_bf16 v[26:29], v[142:145], v[208:211], v[26:29]
	v_mfma_f32_16x16x32_bf16 v[14:17], v[130:133], v[212:215], v[14:17]
	v_mfma_f32_16x16x32_bf16 v[14:17], v[134:137], v[216:219], v[14:17]
	v_mfma_f32_16x16x32_bf16 v[10:13], v[138:141], v[212:215], v[10:13]
	v_mfma_f32_16x16x32_bf16 v[10:13], v[142:145], v[216:219], v[10:13]
	s_setprio 0
	s_setprio 1
	v_mfma_f32_16x16x32_bf16 v[54:57], v[146:149], v[178:181], v[54:57]
	v_mfma_f32_16x16x32_bf16 v[54:57], v[150:153], v[192:195], v[54:57]
	v_mfma_f32_16x16x32_bf16 v[50:53], v[170:173], v[178:181], v[50:53]
	v_mfma_f32_16x16x32_bf16 v[50:53], v[174:177], v[192:195], v[50:53]
	v_mfma_f32_16x16x32_bf16 v[38:41], v[146:149], v[196:199], v[38:41]
	v_mfma_f32_16x16x32_bf16 v[38:41], v[150:153], v[200:203], v[38:41]
	v_mfma_f32_16x16x32_bf16 v[34:37], v[170:173], v[196:199], v[34:37]
	v_mfma_f32_16x16x32_bf16 v[34:37], v[174:177], v[200:203], v[34:37]
	v_mfma_f32_16x16x32_bf16 v[22:25], v[146:149], v[204:207], v[22:25]
	v_mfma_f32_16x16x32_bf16 v[22:25], v[150:153], v[208:211], v[22:25]
	v_mfma_f32_16x16x32_bf16 v[18:21], v[170:173], v[204:207], v[18:21]
	v_mfma_f32_16x16x32_bf16 v[18:21], v[174:177], v[208:211], v[18:21]
	v_mfma_f32_16x16x32_bf16 v[6:9], v[146:149], v[212:215], v[6:9]
	v_mfma_f32_16x16x32_bf16 v[6:9], v[150:153], v[216:219], v[6:9]
	v_mfma_f32_16x16x32_bf16 v[2:5], v[170:173], v[212:215], v[2:5]
	v_mfma_f32_16x16x32_bf16 v[2:5], v[174:177], v[216:219], v[2:5]
	s_setprio 0
	s_barrier
	s_add_i32 s48, 0, 0x18000
	s_add_i32 s49, 0, 0x1c000
	v_add_u32_e32 v142, s48, v183
	v_add_u32_e32 v174, s49, v183
	ds_read_b128 v[130:133], v142
	ds_read_b128 v[134:137], v142 offset:1024
	ds_read_b128 v[138:141], v142 offset:2048
	ds_read_b128 v[142:145], v142 offset:3072
	ds_read_b128 v[146:149], v174
	ds_read_b128 v[150:153], v174 offset:1024
	ds_read_b128 v[170:173], v174 offset:2048
	ds_read_b128 v[174:177], v174 offset:3072
	s_add_u32 s0, s24, 0xb0000
	s_addc_u32 s1, s25, 0
	s_mov_b32 m0, s34
	v_lshl_add_u64 v[228:229], s[0:1], 0, v[154:155]
	ds_read_b128 v[178:181], v189 offset:32768
	ds_read_b128 v[192:195], v189 offset:33792
	ds_read_b128 v[196:199], v189 offset:34816
	ds_read_b128 v[200:203], v189 offset:35840
	ds_read_b128 v[204:207], v189 offset:36864
	ds_read_b128 v[208:211], v189 offset:37888
	ds_read_b128 v[212:215], v189 offset:38912
	ds_read_b128 v[216:219], v189 offset:39936
	global_load_lds_dwordx4 v[228:229], off
	v_lshl_add_u64 v[228:229], s[0:1], 0, v[158:159]
	s_mov_b32 m0, s35
	s_nop 0
	global_load_lds_dwordx4 v[228:229], off
	s_waitcnt vmcnt(8)
	s_waitcnt lgkmcnt(0)
	s_barrier
	s_setprio 1
	s_waitcnt lgkmcnt(0)
	v_mfma_f32_16x16x32_bf16 v[126:129], v[130:133], v[178:181], v[126:129]
	v_mfma_f32_16x16x32_bf16 v[126:129], v[134:137], v[192:195], v[126:129]
	v_mfma_f32_16x16x32_bf16 v[122:125], v[138:141], v[178:181], v[122:125]
	v_mfma_f32_16x16x32_bf16 v[122:125], v[142:145], v[192:195], v[122:125]
	v_mfma_f32_16x16x32_bf16 v[110:113], v[130:133], v[196:199], v[110:113]
	v_mfma_f32_16x16x32_bf16 v[110:113], v[134:137], v[200:203], v[110:113]
	v_mfma_f32_16x16x32_bf16 v[106:109], v[138:141], v[196:199], v[106:109]
	v_mfma_f32_16x16x32_bf16 v[106:109], v[142:145], v[200:203], v[106:109]
	v_mfma_f32_16x16x32_bf16 v[94:97], v[130:133], v[204:207], v[94:97]
	v_mfma_f32_16x16x32_bf16 v[94:97], v[134:137], v[208:211], v[94:97]
	v_mfma_f32_16x16x32_bf16 v[90:93], v[138:141], v[204:207], v[90:93]
	v_mfma_f32_16x16x32_bf16 v[90:93], v[142:145], v[208:211], v[90:93]
	v_mfma_f32_16x16x32_bf16 v[78:81], v[130:133], v[212:215], v[78:81]
	v_mfma_f32_16x16x32_bf16 v[78:81], v[134:137], v[216:219], v[78:81]
	v_mfma_f32_16x16x32_bf16 v[74:77], v[138:141], v[212:215], v[74:77]
	v_mfma_f32_16x16x32_bf16 v[74:77], v[142:145], v[216:219], v[74:77]
	s_setprio 0
	s_setprio 1
	v_mfma_f32_16x16x32_bf16 v[118:121], v[146:149], v[178:181], v[118:121]
	v_mfma_f32_16x16x32_bf16 v[118:121], v[150:153], v[192:195], v[118:121]
	v_mfma_f32_16x16x32_bf16 v[114:117], v[170:173], v[178:181], v[114:117]
	v_mfma_f32_16x16x32_bf16 v[114:117], v[174:177], v[192:195], v[114:117]
	v_mfma_f32_16x16x32_bf16 v[102:105], v[146:149], v[196:199], v[102:105]
	v_mfma_f32_16x16x32_bf16 v[102:105], v[150:153], v[200:203], v[102:105]
	v_mfma_f32_16x16x32_bf16 v[98:101], v[170:173], v[196:199], v[98:101]
	v_mfma_f32_16x16x32_bf16 v[98:101], v[174:177], v[200:203], v[98:101]
	v_mfma_f32_16x16x32_bf16 v[86:89], v[146:149], v[204:207], v[86:89]
	v_mfma_f32_16x16x32_bf16 v[86:89], v[150:153], v[208:211], v[86:89]
	v_mfma_f32_16x16x32_bf16 v[82:85], v[170:173], v[204:207], v[82:85]
	v_mfma_f32_16x16x32_bf16 v[82:85], v[174:177], v[208:211], v[82:85]
	v_mfma_f32_16x16x32_bf16 v[70:73], v[146:149], v[212:215], v[70:73]
	v_mfma_f32_16x16x32_bf16 v[70:73], v[150:153], v[216:219], v[70:73]
	v_mfma_f32_16x16x32_bf16 v[66:69], v[170:173], v[212:215], v[66:69]
	v_mfma_f32_16x16x32_bf16 v[66:69], v[174:177], v[216:219], v[66:69]
	s_setprio 0
	s_barrier
	s_add_i32 s0, s48, s30
	v_lshl_add_u64 v[220:221], v[220:221], 0, s[16:17]
	s_mov_b32 m0, s0
	ds_read_b128 v[178:181], v189 offset:49152
	ds_read_b128 v[192:195], v189 offset:50176
	ds_read_b128 v[196:199], v189 offset:51200
	ds_read_b128 v[200:203], v189 offset:52224
	ds_read_b128 v[204:207], v189 offset:53248
	ds_read_b128 v[208:211], v189 offset:54272
	ds_read_b128 v[212:215], v189 offset:55296
	ds_read_b128 v[216:219], v189 offset:56320
	global_load_lds_dwordx4 v[220:221], off
	s_add_i32 m0, s0, 0x2000
	s_add_u32 s0, s2, 0xb0080
	v_lshl_add_u64 v[220:221], v[222:223], 0, s[16:17]
	s_addc_u32 s1, s3, 0
	s_add_i32 s2, s49, s30
	global_load_lds_dwordx4 v[220:221], off
	v_lshl_add_u64 v[220:221], s[0:1], 0, v[156:157]
	s_mov_b32 m0, s2
	s_nop 0
	global_load_lds_dwordx4 v[220:221], off
	v_lshl_add_u64 v[220:221], s[0:1], 0, v[160:161]
	s_add_i32 m0, s2, 0x2000
	s_nop 0
	global_load_lds_dwordx4 v[220:221], off
	v_lshl_add_u64 v[220:221], v[224:225], 0, s[16:17]
	s_mov_b32 m0, s37
	s_nop 0
	global_load_lds_dwordx4 v[220:221], off
	v_lshl_add_u64 v[220:221], v[226:227], 0, s[16:17]
	s_mov_b32 m0, s38
	s_nop 0
	global_load_lds_dwordx4 v[220:221], off
	s_waitcnt vmcnt(8)
	s_waitcnt lgkmcnt(0)
	s_barrier
	s_setprio 1
	s_waitcnt lgkmcnt(0)
	v_mfma_f32_16x16x32_bf16 v[62:65], v[130:133], v[178:181], v[62:65]
	v_mfma_f32_16x16x32_bf16 v[62:65], v[134:137], v[192:195], v[62:65]
	v_mfma_f32_16x16x32_bf16 v[58:61], v[138:141], v[178:181], v[58:61]
	v_mfma_f32_16x16x32_bf16 v[58:61], v[142:145], v[192:195], v[58:61]
	v_mfma_f32_16x16x32_bf16 v[46:49], v[130:133], v[196:199], v[46:49]
	v_mfma_f32_16x16x32_bf16 v[46:49], v[134:137], v[200:203], v[46:49]
	v_mfma_f32_16x16x32_bf16 v[42:45], v[138:141], v[196:199], v[42:45]
	v_mfma_f32_16x16x32_bf16 v[42:45], v[142:145], v[200:203], v[42:45]
	v_mfma_f32_16x16x32_bf16 v[30:33], v[130:133], v[204:207], v[30:33]
	v_mfma_f32_16x16x32_bf16 v[30:33], v[134:137], v[208:211], v[30:33]
	v_mfma_f32_16x16x32_bf16 v[26:29], v[138:141], v[204:207], v[26:29]
	v_mfma_f32_16x16x32_bf16 v[26:29], v[142:145], v[208:211], v[26:29]
	v_mfma_f32_16x16x32_bf16 v[14:17], v[130:133], v[212:215], v[14:17]
	v_mfma_f32_16x16x32_bf16 v[14:17], v[134:137], v[216:219], v[14:17]
	v_mfma_f32_16x16x32_bf16 v[10:13], v[138:141], v[212:215], v[10:13]
	v_mfma_f32_16x16x32_bf16 v[10:13], v[142:145], v[216:219], v[10:13]
	s_setprio 0
	s_setprio 1
	v_mfma_f32_16x16x32_bf16 v[54:57], v[146:149], v[178:181], v[54:57]
	v_mfma_f32_16x16x32_bf16 v[54:57], v[150:153], v[192:195], v[54:57]
	v_mfma_f32_16x16x32_bf16 v[50:53], v[170:173], v[178:181], v[50:53]
	v_mfma_f32_16x16x32_bf16 v[50:53], v[174:177], v[192:195], v[50:53]
	v_mfma_f32_16x16x32_bf16 v[38:41], v[146:149], v[196:199], v[38:41]
	v_mfma_f32_16x16x32_bf16 v[38:41], v[150:153], v[200:203], v[38:41]
	v_mfma_f32_16x16x32_bf16 v[34:37], v[170:173], v[196:199], v[34:37]
	v_mfma_f32_16x16x32_bf16 v[34:37], v[174:177], v[200:203], v[34:37]
	v_mfma_f32_16x16x32_bf16 v[22:25], v[146:149], v[204:207], v[22:25]
	v_mfma_f32_16x16x32_bf16 v[22:25], v[150:153], v[208:211], v[22:25]
	v_mfma_f32_16x16x32_bf16 v[18:21], v[170:173], v[204:207], v[18:21]
	v_mfma_f32_16x16x32_bf16 v[18:21], v[174:177], v[208:211], v[18:21]
	v_mfma_f32_16x16x32_bf16 v[6:9], v[146:149], v[212:215], v[6:9]
	v_mfma_f32_16x16x32_bf16 v[6:9], v[150:153], v[216:219], v[6:9]
	v_mfma_f32_16x16x32_bf16 v[2:5], v[170:173], v[212:215], v[2:5]
	v_mfma_f32_16x16x32_bf16 v[2:5], v[174:177], v[216:219], v[2:5]
	s_setprio 0
	s_barrier
	s_add_i32 s47, s47, 2
	s_add_u32 s22, s22, 0x100
	s_addc_u32 s23, s23, 0
	s_add_u32 s45, s45, 0x100
	s_addc_u32 s46, s46, 0
	s_cmp_gt_u32 s47, 41
	s_cbranch_scc0 .LBB0_584
	s_and_b64 vcc, exec, s[18:19]
	s_cbranch_vccz .LBB0_587
	s_barrier

.LBB0_675:
	ds_read_b128 v[82:85], v219
	ds_read_b128 v[86:89], v219 offset:1024
	ds_read_b128 v[94:97], v219 offset:2048
	ds_read_b128 v[102:105], v219 offset:3072
	ds_read_b128 v[110:113], v220
	ds_read_b128 v[118:121], v220 offset:1024
	ds_read_b128 v[138:141], v220 offset:2048
	ds_read_b128 v[158:161], v220 offset:3072
	s_add_u32 s0, s8, 0xfffc0080
	s_addc_u32 s1, s9, -1
	s_cmp_eq_u32 s51, 12
	s_cselect_b32 s31, s7, s1
	s_cselect_b32 s30, s23, s0
	s_cselect_b32 s3, s21, s50
	s_cselect_b32 s2, s34, s35
	v_lshl_add_u64 v[224:225], s[8:9], 0, v[190:191]
	s_add_i32 m0, s29, 0xc000
	ds_read_b128 v[162:165], v221
	ds_read_b128 v[166:169], v221 offset:1024
	ds_read_b128 v[170:173], v221 offset:2048
	ds_read_b128 v[174:177], v221 offset:3072
	ds_read_b128 v[198:201], v221 offset:4096
	ds_read_b128 v[202:205], v221 offset:5120
	ds_read_b128 v[206:209], v221 offset:6144
	ds_read_b128 v[210:213], v221 offset:7168
	global_load_lds_dwordx4 v[224:225], off
	v_lshl_add_u64 v[224:225], s[8:9], 0, v[192:193]
	s_add_i32 m0, s29, 0xe000
	s_nop 0
	global_load_lds_dwordx4 v[224:225], off
	s_waitcnt vmcnt(8)
	s_waitcnt lgkmcnt(0)
	s_barrier
	s_setprio 1
	s_waitcnt lgkmcnt(0)
	v_mfma_f32_16x16x32_bf16 v[154:157], v[82:85], v[162:165], v[154:157]
	v_mfma_f32_16x16x32_bf16 v[154:157], v[86:89], v[166:169], v[154:157]
	v_mfma_f32_16x16x32_bf16 v[150:153], v[94:97], v[162:165], v[150:153]
	v_mfma_f32_16x16x32_bf16 v[150:153], v[102:105], v[166:169], v[150:153]
	v_mfma_f32_16x16x32_bf16 v[134:137], v[82:85], v[170:173], v[134:137]
	v_mfma_f32_16x16x32_bf16 v[134:137], v[86:89], v[174:177], v[134:137]
	v_mfma_f32_16x16x32_bf16 v[130:133], v[94:97], v[170:173], v[130:133]
	v_mfma_f32_16x16x32_bf16 v[130:133], v[102:105], v[174:177], v[130:133]
	v_mfma_f32_16x16x32_bf16 v[114:117], v[82:85], v[198:201], v[114:117]
	v_mfma_f32_16x16x32_bf16 v[114:117], v[86:89], v[202:205], v[114:117]
	v_mfma_f32_16x16x32_bf16 v[106:109], v[94:97], v[198:201], v[106:109]
	v_mfma_f32_16x16x32_bf16 v[106:109], v[102:105], v[202:205], v[106:109]
	v_mfma_f32_16x16x32_bf16 v[78:81], v[82:85], v[206:209], v[78:81]
	v_mfma_f32_16x16x32_bf16 v[78:81], v[86:89], v[210:213], v[78:81]
	v_mfma_f32_16x16x32_bf16 v[74:77], v[94:97], v[206:209], v[74:77]
	v_mfma_f32_16x16x32_bf16 v[74:77], v[102:105], v[210:213], v[74:77]
	s_setprio 0
	s_setprio 1
	v_mfma_f32_16x16x32_bf16 v[146:149], v[110:113], v[162:165], v[146:149]
	v_mfma_f32_16x16x32_bf16 v[146:149], v[118:121], v[166:169], v[146:149]
	v_mfma_f32_16x16x32_bf16 v[142:145], v[138:141], v[162:165], v[142:145]
	v_mfma_f32_16x16x32_bf16 v[142:145], v[158:161], v[166:169], v[142:145]
	v_mfma_f32_16x16x32_bf16 v[126:129], v[110:113], v[170:173], v[126:129]
	v_mfma_f32_16x16x32_bf16 v[126:129], v[118:121], v[174:177], v[126:129]
	v_mfma_f32_16x16x32_bf16 v[122:125], v[138:141], v[170:173], v[122:125]
	v_mfma_f32_16x16x32_bf16 v[122:125], v[158:161], v[174:177], v[122:125]
	v_mfma_f32_16x16x32_bf16 v[98:101], v[110:113], v[198:201], v[98:101]
	v_mfma_f32_16x16x32_bf16 v[98:101], v[118:121], v[202:205], v[98:101]
	v_mfma_f32_16x16x32_bf16 v[90:93], v[138:141], v[198:201], v[90:93]
	v_mfma_f32_16x16x32_bf16 v[90:93], v[158:161], v[202:205], v[90:93]
	v_mfma_f32_16x16x32_bf16 v[70:73], v[110:113], v[206:209], v[70:73]
	v_mfma_f32_16x16x32_bf16 v[70:73], v[118:121], v[210:213], v[70:73]
	v_mfma_f32_16x16x32_bf16 v[66:69], v[138:141], v[206:209], v[66:69]
	v_mfma_f32_16x16x32_bf16 v[66:69], v[158:161], v[210:213], v[66:69]
	s_setprio 0
	s_barrier
	s_add_i32 s0, s48, s36
	v_lshl_add_u64 v[224:225], s[2:3], 0, v[182:183]
	s_mov_b32 m0, s0
	ds_read_b128 v[162:165], v221 offset:16384
	ds_read_b128 v[166:169], v221 offset:17408
	ds_read_b128 v[170:173], v221 offset:18432
	ds_read_b128 v[174:177], v221 offset:19456
	ds_read_b128 v[198:201], v221 offset:20480
	ds_read_b128 v[202:205], v221 offset:21504
	ds_read_b128 v[206:209], v221 offset:22528
	ds_read_b128 v[210:213], v221 offset:23552
	global_load_lds_dwordx4 v[224:225], off
	s_add_i32 m0, s0, 0x2000
	s_add_u32 s0, s2, 0x40000
	v_lshl_add_u64 v[226:227], s[2:3], 0, v[186:187]
	s_addc_u32 s1, s3, 0
	s_add_i32 s52, s49, s36
	global_load_lds_dwordx4 v[226:227], off
	v_lshl_add_u64 v[228:229], s[0:1], 0, v[182:183]
	s_mov_b32 m0, s52
	v_lshl_add_u64 v[230:231], s[30:31], 0, v[184:185]
	global_load_lds_dwordx4 v[228:229], off
	v_lshl_add_u64 v[228:229], s[0:1], 0, v[186:187]
	s_add_i32 m0, s52, 0x2000
	s_nop 0
	global_load_lds_dwordx4 v[228:229], off
	v_lshl_add_u64 v[228:229], s[30:31], 0, v[180:181]
	s_mov_b32 m0, s29
	s_nop 0
	global_load_lds_dwordx4 v[228:229], off
	s_mov_b32 m0, s37
	s_nop 0
	global_load_lds_dwordx4 v[230:231], off
	s_waitcnt vmcnt(8)
	s_waitcnt lgkmcnt(0)
	s_barrier
	s_setprio 1
	s_waitcnt lgkmcnt(0)
	v_mfma_f32_16x16x32_bf16 v[62:65], v[82:85], v[162:165], v[62:65]
	v_mfma_f32_16x16x32_bf16 v[62:65], v[86:89], v[166:169], v[62:65]
	v_mfma_f32_16x16x32_bf16 v[58:61], v[94:97], v[162:165], v[58:61]
	v_mfma_f32_16x16x32_bf16 v[58:61], v[102:105], v[166:169], v[58:61]
	v_mfma_f32_16x16x32_bf16 v[46:49], v[82:85], v[170:173], v[46:49]
	v_mfma_f32_16x16x32_bf16 v[46:49], v[86:89], v[174:177], v[46:49]
	v_mfma_f32_16x16x32_bf16 v[42:45], v[94:97], v[170:173], v[42:45]
	v_mfma_f32_16x16x32_bf16 v[42:45], v[102:105], v[174:177], v[42:45]
	v_mfma_f32_16x16x32_bf16 v[30:33], v[82:85], v[198:201], v[30:33]
	v_mfma_f32_16x16x32_bf16 v[30:33], v[86:89], v[202:205], v[30:33]
	v_mfma_f32_16x16x32_bf16 v[26:29], v[94:97], v[198:201], v[26:29]
	v_mfma_f32_16x16x32_bf16 v[26:29], v[102:105], v[202:205], v[26:29]
	v_mfma_f32_16x16x32_bf16 v[14:17], v[82:85], v[206:209], v[14:17]
	v_mfma_f32_16x16x32_bf16 v[14:17], v[86:89], v[210:213], v[14:17]
	v_mfma_f32_16x16x32_bf16 v[10:13], v[94:97], v[206:209], v[10:13]
	v_mfma_f32_16x16x32_bf16 v[10:13], v[102:105], v[210:213], v[10:13]
	s_setprio 0
	s_setprio 1
	v_mfma_f32_16x16x32_bf16 v[54:57], v[110:113], v[162:165], v[54:57]
	v_mfma_f32_16x16x32_bf16 v[54:57], v[118:121], v[166:169], v[54:57]
	v_mfma_f32_16x16x32_bf16 v[50:53], v[138:141], v[162:165], v[50:53]
	v_mfma_f32_16x16x32_bf16 v[50:53], v[158:161], v[166:169], v[50:53]
	v_mfma_f32_16x16x32_bf16 v[38:41], v[110:113], v[170:173], v[38:41]
	v_mfma_f32_16x16x32_bf16 v[38:41], v[118:121], v[174:177], v[38:41]
	v_mfma_f32_16x16x32_bf16 v[34:37], v[138:141], v[170:173], v[34:37]
	v_mfma_f32_16x16x32_bf16 v[34:37], v[158:161], v[174:177], v[34:37]
	v_mfma_f32_16x16x32_bf16 v[22:25], v[110:113], v[198:201], v[22:25]
	v_mfma_f32_16x16x32_bf16 v[22:25], v[118:121], v[202:205], v[22:25]
	v_mfma_f32_16x16x32_bf16 v[18:21], v[138:141], v[198:201], v[18:21]
	v_mfma_f32_16x16x32_bf16 v[18:21], v[158:161], v[202:205], v[18:21]
	v_mfma_f32_16x16x32_bf16 v[6:9], v[110:113], v[206:209], v[6:9]
	v_mfma_f32_16x16x32_bf16 v[6:9], v[118:121], v[210:213], v[6:9]
	v_mfma_f32_16x16x32_bf16 v[2:5], v[138:141], v[206:209], v[2:5]
	v_mfma_f32_16x16x32_bf16 v[2:5], v[158:161], v[210:213], v[2:5]
	s_setprio 0
	s_barrier
	s_add_i32 s52, 0, 0x18000
	s_add_i32 s53, 0, 0x1c000
	v_add_u32_e32 v102, s52, v218
	v_add_u32_e32 v158, s53, v218
	ds_read_b128 v[82:85], v102
	ds_read_b128 v[86:89], v102 offset:1024
	ds_read_b128 v[94:97], v102 offset:2048
	ds_read_b128 v[102:105], v102 offset:3072
	ds_read_b128 v[110:113], v158
	ds_read_b128 v[118:121], v158 offset:1024
	ds_read_b128 v[138:141], v158 offset:2048
	ds_read_b128 v[158:161], v158 offset:3072
	s_add_u32 s0, s30, 0x40000
	s_addc_u32 s1, s31, 0
	s_mov_b32 m0, s38
	v_lshl_add_u64 v[232:233], s[0:1], 0, v[180:181]
	ds_read_b128 v[162:165], v221 offset:32768
	ds_read_b128 v[166:169], v221 offset:33792
	ds_read_b128 v[170:173], v221 offset:34816
	ds_read_b128 v[174:177], v221 offset:35840
	ds_read_b128 v[198:201], v221 offset:36864
	ds_read_b128 v[202:205], v221 offset:37888
	ds_read_b128 v[206:209], v221 offset:38912
	ds_read_b128 v[210:213], v221 offset:39936
	global_load_lds_dwordx4 v[232:233], off
	v_lshl_add_u64 v[232:233], s[0:1], 0, v[184:185]
	s_mov_b32 m0, s39
	s_nop 0
	global_load_lds_dwordx4 v[232:233], off
	s_waitcnt vmcnt(8)
	s_waitcnt lgkmcnt(0)
	s_barrier
	s_setprio 1
	s_waitcnt lgkmcnt(0)
	v_mfma_f32_16x16x32_bf16 v[154:157], v[82:85], v[162:165], v[154:157]
	v_mfma_f32_16x16x32_bf16 v[154:157], v[86:89], v[166:169], v[154:157]
	v_mfma_f32_16x16x32_bf16 v[150:153], v[94:97], v[162:165], v[150:153]
	v_mfma_f32_16x16x32_bf16 v[150:153], v[102:105], v[166:169], v[150:153]
	v_mfma_f32_16x16x32_bf16 v[134:137], v[82:85], v[170:173], v[134:137]
	v_mfma_f32_16x16x32_bf16 v[134:137], v[86:89], v[174:177], v[134:137]
	v_mfma_f32_16x16x32_bf16 v[130:133], v[94:97], v[170:173], v[130:133]
	v_mfma_f32_16x16x32_bf16 v[130:133], v[102:105], v[174:177], v[130:133]
	v_mfma_f32_16x16x32_bf16 v[114:117], v[82:85], v[198:201], v[114:117]
	v_mfma_f32_16x16x32_bf16 v[114:117], v[86:89], v[202:205], v[114:117]
	v_mfma_f32_16x16x32_bf16 v[106:109], v[94:97], v[198:201], v[106:109]
	v_mfma_f32_16x16x32_bf16 v[106:109], v[102:105], v[202:205], v[106:109]
	v_mfma_f32_16x16x32_bf16 v[78:81], v[82:85], v[206:209], v[78:81]
	v_mfma_f32_16x16x32_bf16 v[78:81], v[86:89], v[210:213], v[78:81]
	v_mfma_f32_16x16x32_bf16 v[74:77], v[94:97], v[206:209], v[74:77]
	v_mfma_f32_16x16x32_bf16 v[74:77], v[102:105], v[210:213], v[74:77]
	s_setprio 0
	s_setprio 1
	v_mfma_f32_16x16x32_bf16 v[146:149], v[110:113], v[162:165], v[146:149]
	v_mfma_f32_16x16x32_bf16 v[146:149], v[118:121], v[166:169], v[146:149]
	v_mfma_f32_16x16x32_bf16 v[142:145], v[138:141], v[162:165], v[142:145]
	v_mfma_f32_16x16x32_bf16 v[142:145], v[158:161], v[166:169], v[142:145]
	v_mfma_f32_16x16x32_bf16 v[126:129], v[110:113], v[170:173], v[126:129]
	v_mfma_f32_16x16x32_bf16 v[126:129], v[118:121], v[174:177], v[126:129]
	v_mfma_f32_16x16x32_bf16 v[122:125], v[138:141], v[170:173], v[122:125]
	v_mfma_f32_16x16x32_bf16 v[122:125], v[158:161], v[174:177], v[122:125]
	v_mfma_f32_16x16x32_bf16 v[98:101], v[110:113], v[198:201], v[98:101]
	v_mfma_f32_16x16x32_bf16 v[98:101], v[118:121], v[202:205], v[98:101]
	v_mfma_f32_16x16x32_bf16 v[90:93], v[138:141], v[198:201], v[90:93]
	v_mfma_f32_16x16x32_bf16 v[90:93], v[158:161], v[202:205], v[90:93]
	v_mfma_f32_16x16x32_bf16 v[70:73], v[110:113], v[206:209], v[70:73]
	v_mfma_f32_16x16x32_bf16 v[70:73], v[118:121], v[210:213], v[70:73]
	v_mfma_f32_16x16x32_bf16 v[66:69], v[138:141], v[206:209], v[66:69]
	v_mfma_f32_16x16x32_bf16 v[66:69], v[158:161], v[210:213], v[66:69]
	s_setprio 0
	s_barrier
	s_add_i32 s0, s52, s36
	v_lshl_add_u64 v[224:225], v[224:225], 0, s[12:13]
	s_mov_b32 m0, s0
	ds_read_b128 v[162:165], v221 offset:49152
	ds_read_b128 v[166:169], v221 offset:50176
	ds_read_b128 v[170:173], v221 offset:51200
	ds_read_b128 v[174:177], v221 offset:52224
	ds_read_b128 v[198:201], v221 offset:53248
	ds_read_b128 v[202:205], v221 offset:54272
	ds_read_b128 v[206:209], v221 offset:55296
	ds_read_b128 v[210:213], v221 offset:56320
	global_load_lds_dwordx4 v[224:225], off
	s_add_i32 m0, s0, 0x2000
	s_add_u32 s0, s2, 0x40080
	v_lshl_add_u64 v[224:225], v[226:227], 0, s[12:13]
	s_addc_u32 s1, s3, 0
	s_add_i32 s2, s53, s36
	global_load_lds_dwordx4 v[224:225], off
	v_lshl_add_u64 v[224:225], s[0:1], 0, v[182:183]
	s_mov_b32 m0, s2
	s_nop 0
	global_load_lds_dwordx4 v[224:225], off
	v_lshl_add_u64 v[224:225], s[0:1], 0, v[186:187]
	s_add_i32 m0, s2, 0x2000
	s_nop 0
	global_load_lds_dwordx4 v[224:225], off
	v_lshl_add_u64 v[224:225], v[228:229], 0, s[12:13]
	s_mov_b32 m0, s44
	s_nop 0
	global_load_lds_dwordx4 v[224:225], off
	v_lshl_add_u64 v[224:225], v[230:231], 0, s[12:13]
	s_mov_b32 m0, s45
	s_nop 0
	global_load_lds_dwordx4 v[224:225], off
	s_waitcnt vmcnt(8)
	s_waitcnt lgkmcnt(0)
	s_barrier
	s_setprio 1
	s_waitcnt lgkmcnt(0)
	v_mfma_f32_16x16x32_bf16 v[62:65], v[82:85], v[162:165], v[62:65]
	v_mfma_f32_16x16x32_bf16 v[62:65], v[86:89], v[166:169], v[62:65]
	v_mfma_f32_16x16x32_bf16 v[58:61], v[94:97], v[162:165], v[58:61]
	v_mfma_f32_16x16x32_bf16 v[58:61], v[102:105], v[166:169], v[58:61]
	v_mfma_f32_16x16x32_bf16 v[46:49], v[82:85], v[170:173], v[46:49]
	v_mfma_f32_16x16x32_bf16 v[46:49], v[86:89], v[174:177], v[46:49]
	v_mfma_f32_16x16x32_bf16 v[42:45], v[94:97], v[170:173], v[42:45]
	v_mfma_f32_16x16x32_bf16 v[42:45], v[102:105], v[174:177], v[42:45]
	v_mfma_f32_16x16x32_bf16 v[30:33], v[82:85], v[198:201], v[30:33]
	v_mfma_f32_16x16x32_bf16 v[30:33], v[86:89], v[202:205], v[30:33]
	v_mfma_f32_16x16x32_bf16 v[26:29], v[94:97], v[198:201], v[26:29]
	v_mfma_f32_16x16x32_bf16 v[26:29], v[102:105], v[202:205], v[26:29]
	v_mfma_f32_16x16x32_bf16 v[14:17], v[82:85], v[206:209], v[14:17]
	v_mfma_f32_16x16x32_bf16 v[14:17], v[86:89], v[210:213], v[14:17]
	v_mfma_f32_16x16x32_bf16 v[10:13], v[94:97], v[206:209], v[10:13]
	v_mfma_f32_16x16x32_bf16 v[10:13], v[102:105], v[210:213], v[10:13]
	s_setprio 0
	s_setprio 1
	v_mfma_f32_16x16x32_bf16 v[54:57], v[110:113], v[162:165], v[54:57]
	v_mfma_f32_16x16x32_bf16 v[54:57], v[118:121], v[166:169], v[54:57]
	v_mfma_f32_16x16x32_bf16 v[50:53], v[138:141], v[162:165], v[50:53]
	v_mfma_f32_16x16x32_bf16 v[50:53], v[158:161], v[166:169], v[50:53]
	v_mfma_f32_16x16x32_bf16 v[38:41], v[110:113], v[170:173], v[38:41]
	v_mfma_f32_16x16x32_bf16 v[38:41], v[118:121], v[174:177], v[38:41]
	v_mfma_f32_16x16x32_bf16 v[34:37], v[138:141], v[170:173], v[34:37]
	v_mfma_f32_16x16x32_bf16 v[34:37], v[158:161], v[174:177], v[34:37]
	v_mfma_f32_16x16x32_bf16 v[22:25], v[110:113], v[198:201], v[22:25]
	v_mfma_f32_16x16x32_bf16 v[22:25], v[118:121], v[202:205], v[22:25]
	v_mfma_f32_16x16x32_bf16 v[18:21], v[138:141], v[198:201], v[18:21]
	v_mfma_f32_16x16x32_bf16 v[18:21], v[158:161], v[202:205], v[18:21]
	v_mfma_f32_16x16x32_bf16 v[6:9], v[110:113], v[206:209], v[6:9]
	v_mfma_f32_16x16x32_bf16 v[6:9], v[118:121], v[210:213], v[6:9]
	v_mfma_f32_16x16x32_bf16 v[2:5], v[138:141], v[206:209], v[2:5]
	v_mfma_f32_16x16x32_bf16 v[2:5], v[158:161], v[210:213], v[2:5]
	s_setprio 0
	s_barrier
	s_add_i32 s51, s51, 2
	s_add_u32 s8, s8, 0x100
	s_addc_u32 s9, s9, 0
	s_add_u32 s35, s35, 0x100
	s_addc_u32 s50, s50, 0
	s_cmp_gt_u32 s51, 13
	s_cbranch_scc0 .LBB0_675
	s_and_b64 vcc, exec, s[14:15]
	s_cbranch_vccz .LBB0_678
	s_barrier

.LBB0_920:
	ds_read_b128 v[130:133], v187
	ds_read_b128 v[134:137], v187 offset:1024
	ds_read_b128 v[138:141], v187 offset:2048
	ds_read_b128 v[142:145], v187 offset:3072
	ds_read_b128 v[146:149], v188
	ds_read_b128 v[150:153], v188 offset:1024
	ds_read_b128 v[170:173], v188 offset:2048
	ds_read_b128 v[174:177], v188 offset:3072
	s_add_u32 s0, s28, 0xfffc0080
	s_addc_u32 s1, s29, -1
	s_cmp_eq_u32 s51, 12
	s_cselect_b32 s31, s11, s1
	s_cselect_b32 s30, s21, s0
	s_cselect_b32 s3, s19, s50
	s_cselect_b32 s2, s48, s49
	v_lshl_add_u64 v[220:221], s[28:29], 0, v[162:163]
	s_add_i32 m0, s27, 0xc000
	ds_read_b128 v[178:181], v189
	ds_read_b128 v[192:195], v189 offset:1024
	ds_read_b128 v[196:199], v189 offset:2048
	ds_read_b128 v[200:203], v189 offset:3072
	ds_read_b128 v[204:207], v189 offset:4096
	ds_read_b128 v[208:211], v189 offset:5120
	ds_read_b128 v[212:215], v189 offset:6144
	ds_read_b128 v[216:219], v189 offset:7168
	global_load_lds_dwordx4 v[220:221], off
	v_lshl_add_u64 v[220:221], s[28:29], 0, v[164:165]
	s_add_i32 m0, s27, 0xe000
	s_nop 0
	global_load_lds_dwordx4 v[220:221], off
	s_waitcnt vmcnt(8)
	s_waitcnt lgkmcnt(0)
	s_barrier
	s_setprio 1
	s_waitcnt lgkmcnt(0)
	v_mfma_f32_16x16x32_bf16 v[126:129], v[130:133], v[178:181], v[126:129]
	v_mfma_f32_16x16x32_bf16 v[126:129], v[134:137], v[192:195], v[126:129]
	v_mfma_f32_16x16x32_bf16 v[122:125], v[138:141], v[178:181], v[122:125]
	v_mfma_f32_16x16x32_bf16 v[122:125], v[142:145], v[192:195], v[122:125]
	v_mfma_f32_16x16x32_bf16 v[110:113], v[130:133], v[196:199], v[110:113]
	v_mfma_f32_16x16x32_bf16 v[110:113], v[134:137], v[200:203], v[110:113]
	v_mfma_f32_16x16x32_bf16 v[106:109], v[138:141], v[196:199], v[106:109]
	v_mfma_f32_16x16x32_bf16 v[106:109], v[142:145], v[200:203], v[106:109]
	v_mfma_f32_16x16x32_bf16 v[94:97], v[130:133], v[204:207], v[94:97]
	v_mfma_f32_16x16x32_bf16 v[94:97], v[134:137], v[208:211], v[94:97]
	v_mfma_f32_16x16x32_bf16 v[90:93], v[138:141], v[204:207], v[90:93]
	v_mfma_f32_16x16x32_bf16 v[90:93], v[142:145], v[208:211], v[90:93]
	v_mfma_f32_16x16x32_bf16 v[78:81], v[130:133], v[212:215], v[78:81]
	v_mfma_f32_16x16x32_bf16 v[78:81], v[134:137], v[216:219], v[78:81]
	v_mfma_f32_16x16x32_bf16 v[74:77], v[138:141], v[212:215], v[74:77]
	v_mfma_f32_16x16x32_bf16 v[74:77], v[142:145], v[216:219], v[74:77]
	s_setprio 0
	s_setprio 1
	v_mfma_f32_16x16x32_bf16 v[118:121], v[146:149], v[178:181], v[118:121]
	v_mfma_f32_16x16x32_bf16 v[118:121], v[150:153], v[192:195], v[118:121]
	v_mfma_f32_16x16x32_bf16 v[114:117], v[170:173], v[178:181], v[114:117]
	v_mfma_f32_16x16x32_bf16 v[114:117], v[174:177], v[192:195], v[114:117]
	v_mfma_f32_16x16x32_bf16 v[102:105], v[146:149], v[196:199], v[102:105]
	v_mfma_f32_16x16x32_bf16 v[102:105], v[150:153], v[200:203], v[102:105]
	v_mfma_f32_16x16x32_bf16 v[98:101], v[170:173], v[196:199], v[98:101]
	v_mfma_f32_16x16x32_bf16 v[98:101], v[174:177], v[200:203], v[98:101]
	v_mfma_f32_16x16x32_bf16 v[86:89], v[146:149], v[204:207], v[86:89]
	v_mfma_f32_16x16x32_bf16 v[86:89], v[150:153], v[208:211], v[86:89]
	v_mfma_f32_16x16x32_bf16 v[82:85], v[170:173], v[204:207], v[82:85]
	v_mfma_f32_16x16x32_bf16 v[82:85], v[174:177], v[208:211], v[82:85]
	v_mfma_f32_16x16x32_bf16 v[70:73], v[146:149], v[212:215], v[70:73]
	v_mfma_f32_16x16x32_bf16 v[70:73], v[150:153], v[216:219], v[70:73]
	v_mfma_f32_16x16x32_bf16 v[66:69], v[170:173], v[212:215], v[66:69]
	v_mfma_f32_16x16x32_bf16 v[66:69], v[174:177], v[216:219], v[66:69]
	s_setprio 0
	s_barrier
	s_add_i32 s0, s46, s37
	v_lshl_add_u64 v[220:221], s[2:3], 0, v[156:157]
	s_mov_b32 m0, s0
	ds_read_b128 v[178:181], v189 offset:16384
	ds_read_b128 v[192:195], v189 offset:17408
	ds_read_b128 v[196:199], v189 offset:18432
	ds_read_b128 v[200:203], v189 offset:19456
	ds_read_b128 v[204:207], v189 offset:20480
	ds_read_b128 v[208:211], v189 offset:21504
	ds_read_b128 v[212:215], v189 offset:22528
	ds_read_b128 v[216:219], v189 offset:23552
	global_load_lds_dwordx4 v[220:221], off
	s_add_i32 m0, s0, 0x2000
	s_add_u32 s0, s2, 0x40000
	v_lshl_add_u64 v[222:223], s[2:3], 0, v[160:161]
	s_addc_u32 s1, s3, 0
	s_add_i32 s52, s47, s37
	global_load_lds_dwordx4 v[222:223], off
	v_lshl_add_u64 v[224:225], s[0:1], 0, v[156:157]
	s_mov_b32 m0, s52
	v_lshl_add_u64 v[226:227], s[30:31], 0, v[158:159]
	global_load_lds_dwordx4 v[224:225], off
	v_lshl_add_u64 v[224:225], s[0:1], 0, v[160:161]
	s_add_i32 m0, s52, 0x2000
	s_nop 0
	global_load_lds_dwordx4 v[224:225], off
	v_lshl_add_u64 v[224:225], s[30:31], 0, v[154:155]
	s_mov_b32 m0, s27
	s_nop 0
	global_load_lds_dwordx4 v[224:225], off
	s_mov_b32 m0, s38
	s_nop 0
	global_load_lds_dwordx4 v[226:227], off
	s_waitcnt vmcnt(8)
	s_waitcnt lgkmcnt(0)
	s_barrier
	s_setprio 1
	s_waitcnt lgkmcnt(0)
	v_mfma_f32_16x16x32_bf16 v[62:65], v[130:133], v[178:181], v[62:65]
	v_mfma_f32_16x16x32_bf16 v[62:65], v[134:137], v[192:195], v[62:65]
	v_mfma_f32_16x16x32_bf16 v[58:61], v[138:141], v[178:181], v[58:61]
	v_mfma_f32_16x16x32_bf16 v[58:61], v[142:145], v[192:195], v[58:61]
	v_mfma_f32_16x16x32_bf16 v[46:49], v[130:133], v[196:199], v[46:49]
	v_mfma_f32_16x16x32_bf16 v[46:49], v[134:137], v[200:203], v[46:49]
	v_mfma_f32_16x16x32_bf16 v[42:45], v[138:141], v[196:199], v[42:45]
	v_mfma_f32_16x16x32_bf16 v[42:45], v[142:145], v[200:203], v[42:45]
	v_mfma_f32_16x16x32_bf16 v[30:33], v[130:133], v[204:207], v[30:33]
	v_mfma_f32_16x16x32_bf16 v[30:33], v[134:137], v[208:211], v[30:33]
	v_mfma_f32_16x16x32_bf16 v[26:29], v[138:141], v[204:207], v[26:29]
	v_mfma_f32_16x16x32_bf16 v[26:29], v[142:145], v[208:211], v[26:29]
	v_mfma_f32_16x16x32_bf16 v[14:17], v[130:133], v[212:215], v[14:17]
	v_mfma_f32_16x16x32_bf16 v[14:17], v[134:137], v[216:219], v[14:17]
	v_mfma_f32_16x16x32_bf16 v[10:13], v[138:141], v[212:215], v[10:13]
	v_mfma_f32_16x16x32_bf16 v[10:13], v[142:145], v[216:219], v[10:13]
	s_setprio 0
	s_setprio 1
	v_mfma_f32_16x16x32_bf16 v[54:57], v[146:149], v[178:181], v[54:57]
	v_mfma_f32_16x16x32_bf16 v[54:57], v[150:153], v[192:195], v[54:57]
	v_mfma_f32_16x16x32_bf16 v[50:53], v[170:173], v[178:181], v[50:53]
	v_mfma_f32_16x16x32_bf16 v[50:53], v[174:177], v[192:195], v[50:53]
	v_mfma_f32_16x16x32_bf16 v[38:41], v[146:149], v[196:199], v[38:41]
	v_mfma_f32_16x16x32_bf16 v[38:41], v[150:153], v[200:203], v[38:41]
	v_mfma_f32_16x16x32_bf16 v[34:37], v[170:173], v[196:199], v[34:37]
	v_mfma_f32_16x16x32_bf16 v[34:37], v[174:177], v[200:203], v[34:37]
	v_mfma_f32_16x16x32_bf16 v[22:25], v[146:149], v[204:207], v[22:25]
	v_mfma_f32_16x16x32_bf16 v[22:25], v[150:153], v[208:211], v[22:25]
	v_mfma_f32_16x16x32_bf16 v[18:21], v[170:173], v[204:207], v[18:21]
	v_mfma_f32_16x16x32_bf16 v[18:21], v[174:177], v[208:211], v[18:21]
	v_mfma_f32_16x16x32_bf16 v[6:9], v[146:149], v[212:215], v[6:9]
	v_mfma_f32_16x16x32_bf16 v[6:9], v[150:153], v[216:219], v[6:9]
	v_mfma_f32_16x16x32_bf16 v[2:5], v[170:173], v[212:215], v[2:5]
	v_mfma_f32_16x16x32_bf16 v[2:5], v[174:177], v[216:219], v[2:5]
	s_setprio 0
	s_barrier
	s_add_i32 s52, 0, 0x18000
	s_add_i32 s53, 0, 0x1c000
	v_add_u32_e32 v142, s52, v183
	v_add_u32_e32 v174, s53, v183
	ds_read_b128 v[130:133], v142
	ds_read_b128 v[134:137], v142 offset:1024
	ds_read_b128 v[138:141], v142 offset:2048
	ds_read_b128 v[142:145], v142 offset:3072
	ds_read_b128 v[146:149], v174
	ds_read_b128 v[150:153], v174 offset:1024
	ds_read_b128 v[170:173], v174 offset:2048
	ds_read_b128 v[174:177], v174 offset:3072
	s_add_u32 s0, s30, 0x40000
	s_addc_u32 s1, s31, 0
	s_mov_b32 m0, s39
	v_lshl_add_u64 v[228:229], s[0:1], 0, v[154:155]
	ds_read_b128 v[178:181], v189 offset:32768
	ds_read_b128 v[192:195], v189 offset:33792
	ds_read_b128 v[196:199], v189 offset:34816
	ds_read_b128 v[200:203], v189 offset:35840
	ds_read_b128 v[204:207], v189 offset:36864
	ds_read_b128 v[208:211], v189 offset:37888
	ds_read_b128 v[212:215], v189 offset:38912
	ds_read_b128 v[216:219], v189 offset:39936
	global_load_lds_dwordx4 v[228:229], off
	v_lshl_add_u64 v[228:229], s[0:1], 0, v[158:159]
	s_mov_b32 m0, s40
	s_nop 0
	global_load_lds_dwordx4 v[228:229], off
	s_waitcnt vmcnt(8)
	s_waitcnt lgkmcnt(0)
	s_barrier
	s_setprio 1
	s_waitcnt lgkmcnt(0)
	v_mfma_f32_16x16x32_bf16 v[126:129], v[130:133], v[178:181], v[126:129]
	v_mfma_f32_16x16x32_bf16 v[126:129], v[134:137], v[192:195], v[126:129]
	v_mfma_f32_16x16x32_bf16 v[122:125], v[138:141], v[178:181], v[122:125]
	v_mfma_f32_16x16x32_bf16 v[122:125], v[142:145], v[192:195], v[122:125]
	v_mfma_f32_16x16x32_bf16 v[110:113], v[130:133], v[196:199], v[110:113]
	v_mfma_f32_16x16x32_bf16 v[110:113], v[134:137], v[200:203], v[110:113]
	v_mfma_f32_16x16x32_bf16 v[106:109], v[138:141], v[196:199], v[106:109]
	v_mfma_f32_16x16x32_bf16 v[106:109], v[142:145], v[200:203], v[106:109]
	v_mfma_f32_16x16x32_bf16 v[94:97], v[130:133], v[204:207], v[94:97]
	v_mfma_f32_16x16x32_bf16 v[94:97], v[134:137], v[208:211], v[94:97]
	v_mfma_f32_16x16x32_bf16 v[90:93], v[138:141], v[204:207], v[90:93]
	v_mfma_f32_16x16x32_bf16 v[90:93], v[142:145], v[208:211], v[90:93]
	v_mfma_f32_16x16x32_bf16 v[78:81], v[130:133], v[212:215], v[78:81]
	v_mfma_f32_16x16x32_bf16 v[78:81], v[134:137], v[216:219], v[78:81]
	v_mfma_f32_16x16x32_bf16 v[74:77], v[138:141], v[212:215], v[74:77]
	v_mfma_f32_16x16x32_bf16 v[74:77], v[142:145], v[216:219], v[74:77]
	s_setprio 0
	s_setprio 1
	v_mfma_f32_16x16x32_bf16 v[118:121], v[146:149], v[178:181], v[118:121]
	v_mfma_f32_16x16x32_bf16 v[118:121], v[150:153], v[192:195], v[118:121]
	v_mfma_f32_16x16x32_bf16 v[114:117], v[170:173], v[178:181], v[114:117]
	v_mfma_f32_16x16x32_bf16 v[114:117], v[174:177], v[192:195], v[114:117]
	v_mfma_f32_16x16x32_bf16 v[102:105], v[146:149], v[196:199], v[102:105]
	v_mfma_f32_16x16x32_bf16 v[102:105], v[150:153], v[200:203], v[102:105]
	v_mfma_f32_16x16x32_bf16 v[98:101], v[170:173], v[196:199], v[98:101]
	v_mfma_f32_16x16x32_bf16 v[98:101], v[174:177], v[200:203], v[98:101]
	v_mfma_f32_16x16x32_bf16 v[86:89], v[146:149], v[204:207], v[86:89]
	v_mfma_f32_16x16x32_bf16 v[86:89], v[150:153], v[208:211], v[86:89]
	v_mfma_f32_16x16x32_bf16 v[82:85], v[170:173], v[204:207], v[82:85]
	v_mfma_f32_16x16x32_bf16 v[82:85], v[174:177], v[208:211], v[82:85]
	v_mfma_f32_16x16x32_bf16 v[70:73], v[146:149], v[212:215], v[70:73]
	v_mfma_f32_16x16x32_bf16 v[70:73], v[150:153], v[216:219], v[70:73]
	v_mfma_f32_16x16x32_bf16 v[66:69], v[170:173], v[212:215], v[66:69]
	v_mfma_f32_16x16x32_bf16 v[66:69], v[174:177], v[216:219], v[66:69]
	s_setprio 0
	s_barrier
	s_add_i32 s0, s52, s37
	v_lshl_add_u64 v[220:221], v[220:221], 0, s[14:15]
	s_mov_b32 m0, s0
	ds_read_b128 v[178:181], v189 offset:49152
	ds_read_b128 v[192:195], v189 offset:50176
	ds_read_b128 v[196:199], v189 offset:51200
	ds_read_b128 v[200:203], v189 offset:52224
	ds_read_b128 v[204:207], v189 offset:53248
	ds_read_b128 v[208:211], v189 offset:54272
	ds_read_b128 v[212:215], v189 offset:55296
	ds_read_b128 v[216:219], v189 offset:56320
	global_load_lds_dwordx4 v[220:221], off
	s_add_i32 m0, s0, 0x2000
	s_add_u32 s0, s2, 0x40080
	v_lshl_add_u64 v[220:221], v[222:223], 0, s[14:15]
	s_addc_u32 s1, s3, 0
	s_add_i32 s2, s53, s37
	global_load_lds_dwordx4 v[220:221], off
	v_lshl_add_u64 v[220:221], s[0:1], 0, v[156:157]
	s_mov_b32 m0, s2
	s_nop 0
	global_load_lds_dwordx4 v[220:221], off
	v_lshl_add_u64 v[220:221], s[0:1], 0, v[160:161]
	s_add_i32 m0, s2, 0x2000
	s_nop 0
	global_load_lds_dwordx4 v[220:221], off
	v_lshl_add_u64 v[220:221], v[224:225], 0, s[14:15]
	s_mov_b32 m0, s42
	s_nop 0
	global_load_lds_dwordx4 v[220:221], off
	v_lshl_add_u64 v[220:221], v[226:227], 0, s[14:15]
	s_mov_b32 m0, s43
	s_nop 0
	global_load_lds_dwordx4 v[220:221], off
	s_waitcnt vmcnt(8)
	s_waitcnt lgkmcnt(0)
	s_barrier
	s_setprio 1
	s_waitcnt lgkmcnt(0)
	v_mfma_f32_16x16x32_bf16 v[62:65], v[130:133], v[178:181], v[62:65]
	v_mfma_f32_16x16x32_bf16 v[62:65], v[134:137], v[192:195], v[62:65]
	v_mfma_f32_16x16x32_bf16 v[58:61], v[138:141], v[178:181], v[58:61]
	v_mfma_f32_16x16x32_bf16 v[58:61], v[142:145], v[192:195], v[58:61]
	v_mfma_f32_16x16x32_bf16 v[46:49], v[130:133], v[196:199], v[46:49]
	v_mfma_f32_16x16x32_bf16 v[46:49], v[134:137], v[200:203], v[46:49]
	v_mfma_f32_16x16x32_bf16 v[42:45], v[138:141], v[196:199], v[42:45]
	v_mfma_f32_16x16x32_bf16 v[42:45], v[142:145], v[200:203], v[42:45]
	v_mfma_f32_16x16x32_bf16 v[30:33], v[130:133], v[204:207], v[30:33]
	v_mfma_f32_16x16x32_bf16 v[30:33], v[134:137], v[208:211], v[30:33]
	v_mfma_f32_16x16x32_bf16 v[26:29], v[138:141], v[204:207], v[26:29]
	v_mfma_f32_16x16x32_bf16 v[26:29], v[142:145], v[208:211], v[26:29]
	v_mfma_f32_16x16x32_bf16 v[14:17], v[130:133], v[212:215], v[14:17]
	v_mfma_f32_16x16x32_bf16 v[14:17], v[134:137], v[216:219], v[14:17]
	v_mfma_f32_16x16x32_bf16 v[10:13], v[138:141], v[212:215], v[10:13]
	v_mfma_f32_16x16x32_bf16 v[10:13], v[142:145], v[216:219], v[10:13]
	s_setprio 0
	s_setprio 1
	v_mfma_f32_16x16x32_bf16 v[54:57], v[146:149], v[178:181], v[54:57]
	v_mfma_f32_16x16x32_bf16 v[54:57], v[150:153], v[192:195], v[54:57]
	v_mfma_f32_16x16x32_bf16 v[50:53], v[170:173], v[178:181], v[50:53]
	v_mfma_f32_16x16x32_bf16 v[50:53], v[174:177], v[192:195], v[50:53]
	v_mfma_f32_16x16x32_bf16 v[38:41], v[146:149], v[196:199], v[38:41]
	v_mfma_f32_16x16x32_bf16 v[38:41], v[150:153], v[200:203], v[38:41]
	v_mfma_f32_16x16x32_bf16 v[34:37], v[170:173], v[196:199], v[34:37]
	v_mfma_f32_16x16x32_bf16 v[34:37], v[174:177], v[200:203], v[34:37]
	v_mfma_f32_16x16x32_bf16 v[22:25], v[146:149], v[204:207], v[22:25]
	v_mfma_f32_16x16x32_bf16 v[22:25], v[150:153], v[208:211], v[22:25]
	v_mfma_f32_16x16x32_bf16 v[18:21], v[170:173], v[204:207], v[18:21]
	v_mfma_f32_16x16x32_bf16 v[18:21], v[174:177], v[208:211], v[18:21]
	v_mfma_f32_16x16x32_bf16 v[6:9], v[146:149], v[212:215], v[6:9]
	v_mfma_f32_16x16x32_bf16 v[6:9], v[150:153], v[216:219], v[6:9]
	v_mfma_f32_16x16x32_bf16 v[2:5], v[170:173], v[212:215], v[2:5]
	v_mfma_f32_16x16x32_bf16 v[2:5], v[174:177], v[216:219], v[2:5]
	s_setprio 0
	s_barrier
	s_add_i32 s51, s51, 2
	s_add_u32 s28, s28, 0x100
	s_addc_u32 s29, s29, 0
	s_add_u32 s49, s49, 0x100
	s_addc_u32 s50, s50, 0
	s_cmp_gt_u32 s51, 13
	s_cbranch_scc0 .LBB0_920
	s_and_b64 vcc, exec, s[16:17]
	s_cbranch_vccz .LBB0_923
	s_barrier

.LBB0_1009:
	ds_read_b128 v[148:151], v167
	ds_read_b128 v[152:155], v167 offset:1024
	ds_read_b128 v[156:159], v167 offset:2048
	ds_read_b128 v[160:163], v167 offset:3072
	ds_read_b128 v[172:175], v168
	ds_read_b128 v[176:179], v168 offset:1024
	ds_read_b128 v[180:183], v168 offset:2048
	ds_read_b128 v[184:187], v168 offset:3072
	s_add_u32 s0, s28, 0xfffc0080
	s_addc_u32 s1, s29, -1
	s_cmp_eq_u32 s53, 12
	s_cselect_b32 s31, s21, s1
	s_cselect_b32 s30, s49, s0
	s_cselect_b32 s3, s19, s52
	s_cselect_b32 s2, s50, s51
	v_lshl_add_u64 v[220:221], s[28:29], 0, v[140:141]
	s_add_i32 m0, s27, 0xc000
	ds_read_b128 v[188:191], v169
	ds_read_b128 v[192:195], v169 offset:1024
	ds_read_b128 v[196:199], v169 offset:2048
	ds_read_b128 v[200:203], v169 offset:3072
	ds_read_b128 v[204:207], v169 offset:4096
	ds_read_b128 v[208:211], v169 offset:5120
	ds_read_b128 v[212:215], v169 offset:6144
	ds_read_b128 v[216:219], v169 offset:7168
	global_load_lds_dwordx4 v[220:221], off
	v_lshl_add_u64 v[220:221], s[28:29], 0, v[142:143]
	s_add_i32 m0, s27, 0xe000
	s_nop 0
	global_load_lds_dwordx4 v[220:221], off
	s_waitcnt vmcnt(8)
	s_waitcnt lgkmcnt(0)
	s_barrier
	s_setprio 1
	s_waitcnt lgkmcnt(0)
	v_mfma_f32_16x16x32_bf16 v[126:129], v[148:151], v[188:191], v[126:129]
	v_mfma_f32_16x16x32_bf16 v[126:129], v[152:155], v[192:195], v[126:129]
	v_mfma_f32_16x16x32_bf16 v[118:121], v[156:159], v[188:191], v[118:121]
	v_mfma_f32_16x16x32_bf16 v[118:121], v[160:163], v[192:195], v[118:121]
	v_mfma_f32_16x16x32_bf16 v[110:113], v[148:151], v[196:199], v[110:113]
	v_mfma_f32_16x16x32_bf16 v[110:113], v[152:155], v[200:203], v[110:113]
	v_mfma_f32_16x16x32_bf16 v[102:105], v[156:159], v[196:199], v[102:105]
	v_mfma_f32_16x16x32_bf16 v[102:105], v[160:163], v[200:203], v[102:105]
	v_mfma_f32_16x16x32_bf16 v[94:97], v[148:151], v[204:207], v[94:97]
	v_mfma_f32_16x16x32_bf16 v[94:97], v[152:155], v[208:211], v[94:97]
	v_mfma_f32_16x16x32_bf16 v[86:89], v[156:159], v[204:207], v[86:89]
	v_mfma_f32_16x16x32_bf16 v[86:89], v[160:163], v[208:211], v[86:89]
	v_mfma_f32_16x16x32_bf16 v[78:81], v[148:151], v[212:215], v[78:81]
	v_mfma_f32_16x16x32_bf16 v[78:81], v[152:155], v[216:219], v[78:81]
	v_mfma_f32_16x16x32_bf16 v[70:73], v[156:159], v[212:215], v[70:73]
	v_mfma_f32_16x16x32_bf16 v[70:73], v[160:163], v[216:219], v[70:73]
	s_setprio 0
	s_setprio 1
	v_mfma_f32_16x16x32_bf16 v[122:125], v[172:175], v[188:191], v[122:125]
	v_mfma_f32_16x16x32_bf16 v[122:125], v[176:179], v[192:195], v[122:125]
	v_mfma_f32_16x16x32_bf16 v[114:117], v[180:183], v[188:191], v[114:117]
	v_mfma_f32_16x16x32_bf16 v[114:117], v[184:187], v[192:195], v[114:117]
	v_mfma_f32_16x16x32_bf16 v[106:109], v[172:175], v[196:199], v[106:109]
	v_mfma_f32_16x16x32_bf16 v[106:109], v[176:179], v[200:203], v[106:109]
	v_mfma_f32_16x16x32_bf16 v[98:101], v[180:183], v[196:199], v[98:101]
	v_mfma_f32_16x16x32_bf16 v[98:101], v[184:187], v[200:203], v[98:101]
	v_mfma_f32_16x16x32_bf16 v[90:93], v[172:175], v[204:207], v[90:93]
	v_mfma_f32_16x16x32_bf16 v[90:93], v[176:179], v[208:211], v[90:93]
	v_mfma_f32_16x16x32_bf16 v[82:85], v[180:183], v[204:207], v[82:85]
	v_mfma_f32_16x16x32_bf16 v[82:85], v[184:187], v[208:211], v[82:85]
	v_mfma_f32_16x16x32_bf16 v[74:77], v[172:175], v[212:215], v[74:77]
	v_mfma_f32_16x16x32_bf16 v[74:77], v[176:179], v[216:219], v[74:77]
	v_mfma_f32_16x16x32_bf16 v[66:69], v[180:183], v[212:215], v[66:69]
	v_mfma_f32_16x16x32_bf16 v[66:69], v[184:187], v[216:219], v[66:69]
	s_setprio 0
	s_barrier
	s_add_i32 s0, s44, s35
	v_lshl_add_u64 v[220:221], s[2:3], 0, v[134:135]
	s_mov_b32 m0, s0
	ds_read_b128 v[188:191], v169 offset:16384
	ds_read_b128 v[192:195], v169 offset:17408
	ds_read_b128 v[196:199], v169 offset:18432
	ds_read_b128 v[200:203], v169 offset:19456
	ds_read_b128 v[204:207], v169 offset:20480
	ds_read_b128 v[208:211], v169 offset:21504
	ds_read_b128 v[212:215], v169 offset:22528
	ds_read_b128 v[216:219], v169 offset:23552
	global_load_lds_dwordx4 v[220:221], off
	s_add_i32 m0, s0, 0x2000
	s_add_u32 s0, s2, 0x40000
	v_lshl_add_u64 v[222:223], s[2:3], 0, v[130:131]
	s_addc_u32 s1, s3, 0
	s_add_i32 s54, s45, s35
	global_load_lds_dwordx4 v[222:223], off
	v_lshl_add_u64 v[224:225], s[0:1], 0, v[134:135]
	s_mov_b32 m0, s54
	v_lshl_add_u64 v[226:227], s[30:31], 0, v[132:133]
	global_load_lds_dwordx4 v[224:225], off
	v_lshl_add_u64 v[224:225], s[0:1], 0, v[130:131]
	s_add_i32 m0, s54, 0x2000
	s_nop 0
	global_load_lds_dwordx4 v[224:225], off
	v_lshl_add_u64 v[224:225], s[30:31], 0, v[136:137]
	s_mov_b32 m0, s27
	s_nop 0
	global_load_lds_dwordx4 v[224:225], off
	s_mov_b32 m0, s38
	s_nop 0
	global_load_lds_dwordx4 v[226:227], off
	s_waitcnt vmcnt(8)
	s_waitcnt lgkmcnt(0)
	s_barrier
	s_setprio 1
	s_waitcnt lgkmcnt(0)
	v_mfma_f32_16x16x32_bf16 v[62:65], v[148:151], v[188:191], v[62:65]
	v_mfma_f32_16x16x32_bf16 v[62:65], v[152:155], v[192:195], v[62:65]
	v_mfma_f32_16x16x32_bf16 v[54:57], v[156:159], v[188:191], v[54:57]
	v_mfma_f32_16x16x32_bf16 v[54:57], v[160:163], v[192:195], v[54:57]
	v_mfma_f32_16x16x32_bf16 v[46:49], v[148:151], v[196:199], v[46:49]
	v_mfma_f32_16x16x32_bf16 v[46:49], v[152:155], v[200:203], v[46:49]
	v_mfma_f32_16x16x32_bf16 v[38:41], v[156:159], v[196:199], v[38:41]
	v_mfma_f32_16x16x32_bf16 v[38:41], v[160:163], v[200:203], v[38:41]
	v_mfma_f32_16x16x32_bf16 v[30:33], v[148:151], v[204:207], v[30:33]
	v_mfma_f32_16x16x32_bf16 v[30:33], v[152:155], v[208:211], v[30:33]
	v_mfma_f32_16x16x32_bf16 v[22:25], v[156:159], v[204:207], v[22:25]
	v_mfma_f32_16x16x32_bf16 v[22:25], v[160:163], v[208:211], v[22:25]
	v_mfma_f32_16x16x32_bf16 v[14:17], v[148:151], v[212:215], v[14:17]
	v_mfma_f32_16x16x32_bf16 v[14:17], v[152:155], v[216:219], v[14:17]
	v_mfma_f32_16x16x32_bf16 v[6:9], v[156:159], v[212:215], v[6:9]
	v_mfma_f32_16x16x32_bf16 v[6:9], v[160:163], v[216:219], v[6:9]
	s_setprio 0
	s_setprio 1
	v_mfma_f32_16x16x32_bf16 v[58:61], v[172:175], v[188:191], v[58:61]
	v_mfma_f32_16x16x32_bf16 v[58:61], v[176:179], v[192:195], v[58:61]
	v_mfma_f32_16x16x32_bf16 v[50:53], v[180:183], v[188:191], v[50:53]
	v_mfma_f32_16x16x32_bf16 v[50:53], v[184:187], v[192:195], v[50:53]
	v_mfma_f32_16x16x32_bf16 v[42:45], v[172:175], v[196:199], v[42:45]
	v_mfma_f32_16x16x32_bf16 v[42:45], v[176:179], v[200:203], v[42:45]
	v_mfma_f32_16x16x32_bf16 v[34:37], v[180:183], v[196:199], v[34:37]
	v_mfma_f32_16x16x32_bf16 v[34:37], v[184:187], v[200:203], v[34:37]
	v_mfma_f32_16x16x32_bf16 v[26:29], v[172:175], v[204:207], v[26:29]
	v_mfma_f32_16x16x32_bf16 v[26:29], v[176:179], v[208:211], v[26:29]
	v_mfma_f32_16x16x32_bf16 v[18:21], v[180:183], v[204:207], v[18:21]
	v_mfma_f32_16x16x32_bf16 v[18:21], v[184:187], v[208:211], v[18:21]
	v_mfma_f32_16x16x32_bf16 v[10:13], v[172:175], v[212:215], v[10:13]
	v_mfma_f32_16x16x32_bf16 v[10:13], v[176:179], v[216:219], v[10:13]
	v_mfma_f32_16x16x32_bf16 v[2:5], v[180:183], v[212:215], v[2:5]
	v_mfma_f32_16x16x32_bf16 v[2:5], v[184:187], v[216:219], v[2:5]
	s_setprio 0
	s_barrier
	s_add_i32 s54, 0, 0x18000
	s_add_i32 s55, 0, 0x1c000
	v_add_u32_e32 v160, s54, v166
	v_add_u32_e32 v171, s55, v166
	ds_read_b128 v[148:151], v160
	ds_read_b128 v[152:155], v160 offset:1024
	ds_read_b128 v[156:159], v160 offset:2048
	ds_read_b128 v[160:163], v160 offset:3072
	ds_read_b128 v[172:175], v171
	ds_read_b128 v[176:179], v171 offset:1024
	ds_read_b128 v[180:183], v171 offset:2048
	ds_read_b128 v[184:187], v171 offset:3072
	s_add_u32 s0, s30, 0x40000
	s_addc_u32 s1, s31, 0
	s_mov_b32 m0, s39
	v_lshl_add_u64 v[228:229], s[0:1], 0, v[136:137]
	ds_read_b128 v[188:191], v169 offset:32768
	ds_read_b128 v[192:195], v169 offset:33792
	ds_read_b128 v[196:199], v169 offset:34816
	ds_read_b128 v[200:203], v169 offset:35840
	ds_read_b128 v[204:207], v169 offset:36864
	ds_read_b128 v[208:211], v169 offset:37888
	ds_read_b128 v[212:215], v169 offset:38912
	ds_read_b128 v[216:219], v169 offset:39936
	global_load_lds_dwordx4 v[228:229], off
	v_lshl_add_u64 v[228:229], s[0:1], 0, v[132:133]
	s_mov_b32 m0, s40
	s_nop 0
	global_load_lds_dwordx4 v[228:229], off
	s_waitcnt vmcnt(8)
	s_waitcnt lgkmcnt(0)
	s_barrier
	s_setprio 1
	s_waitcnt lgkmcnt(0)
	v_mfma_f32_16x16x32_bf16 v[126:129], v[148:151], v[188:191], v[126:129]
	v_mfma_f32_16x16x32_bf16 v[126:129], v[152:155], v[192:195], v[126:129]
	v_mfma_f32_16x16x32_bf16 v[118:121], v[156:159], v[188:191], v[118:121]
	v_mfma_f32_16x16x32_bf16 v[118:121], v[160:163], v[192:195], v[118:121]
	v_mfma_f32_16x16x32_bf16 v[110:113], v[148:151], v[196:199], v[110:113]
	v_mfma_f32_16x16x32_bf16 v[110:113], v[152:155], v[200:203], v[110:113]
	v_mfma_f32_16x16x32_bf16 v[102:105], v[156:159], v[196:199], v[102:105]
	v_mfma_f32_16x16x32_bf16 v[102:105], v[160:163], v[200:203], v[102:105]
	v_mfma_f32_16x16x32_bf16 v[94:97], v[148:151], v[204:207], v[94:97]
	v_mfma_f32_16x16x32_bf16 v[94:97], v[152:155], v[208:211], v[94:97]
	v_mfma_f32_16x16x32_bf16 v[86:89], v[156:159], v[204:207], v[86:89]
	v_mfma_f32_16x16x32_bf16 v[86:89], v[160:163], v[208:211], v[86:89]
	v_mfma_f32_16x16x32_bf16 v[78:81], v[148:151], v[212:215], v[78:81]
	v_mfma_f32_16x16x32_bf16 v[78:81], v[152:155], v[216:219], v[78:81]
	v_mfma_f32_16x16x32_bf16 v[70:73], v[156:159], v[212:215], v[70:73]
	v_mfma_f32_16x16x32_bf16 v[70:73], v[160:163], v[216:219], v[70:73]
	s_setprio 0
	s_setprio 1
	v_mfma_f32_16x16x32_bf16 v[122:125], v[172:175], v[188:191], v[122:125]
	v_mfma_f32_16x16x32_bf16 v[122:125], v[176:179], v[192:195], v[122:125]
	v_mfma_f32_16x16x32_bf16 v[114:117], v[180:183], v[188:191], v[114:117]
	v_mfma_f32_16x16x32_bf16 v[114:117], v[184:187], v[192:195], v[114:117]
	v_mfma_f32_16x16x32_bf16 v[106:109], v[172:175], v[196:199], v[106:109]
	v_mfma_f32_16x16x32_bf16 v[106:109], v[176:179], v[200:203], v[106:109]
	v_mfma_f32_16x16x32_bf16 v[98:101], v[180:183], v[196:199], v[98:101]
	v_mfma_f32_16x16x32_bf16 v[98:101], v[184:187], v[200:203], v[98:101]
	v_mfma_f32_16x16x32_bf16 v[90:93], v[172:175], v[204:207], v[90:93]
	v_mfma_f32_16x16x32_bf16 v[90:93], v[176:179], v[208:211], v[90:93]
	v_mfma_f32_16x16x32_bf16 v[82:85], v[180:183], v[204:207], v[82:85]
	v_mfma_f32_16x16x32_bf16 v[82:85], v[184:187], v[208:211], v[82:85]
	v_mfma_f32_16x16x32_bf16 v[74:77], v[172:175], v[212:215], v[74:77]
	v_mfma_f32_16x16x32_bf16 v[74:77], v[176:179], v[216:219], v[74:77]
	v_mfma_f32_16x16x32_bf16 v[66:69], v[180:183], v[212:215], v[66:69]
	v_mfma_f32_16x16x32_bf16 v[66:69], v[184:187], v[216:219], v[66:69]
	s_setprio 0
	s_barrier
	s_add_i32 s0, s54, s35
	v_lshl_add_u64 v[220:221], v[220:221], 0, s[14:15]
	s_mov_b32 m0, s0
	ds_read_b128 v[188:191], v169 offset:49152
	ds_read_b128 v[192:195], v169 offset:50176
	ds_read_b128 v[196:199], v169 offset:51200
	ds_read_b128 v[200:203], v169 offset:52224
	ds_read_b128 v[204:207], v169 offset:53248
	ds_read_b128 v[208:211], v169 offset:54272
	ds_read_b128 v[212:215], v169 offset:55296
	ds_read_b128 v[216:219], v169 offset:56320
	global_load_lds_dwordx4 v[220:221], off
	s_add_i32 m0, s0, 0x2000
	s_add_u32 s0, s2, 0x40080
	v_lshl_add_u64 v[220:221], v[222:223], 0, s[14:15]
	s_addc_u32 s1, s3, 0
	s_add_i32 s2, s55, s35
	global_load_lds_dwordx4 v[220:221], off
	v_lshl_add_u64 v[220:221], s[0:1], 0, v[134:135]
	s_mov_b32 m0, s2
	s_nop 0
	global_load_lds_dwordx4 v[220:221], off
	v_lshl_add_u64 v[220:221], s[0:1], 0, v[130:131]
	s_add_i32 m0, s2, 0x2000
	s_nop 0
	global_load_lds_dwordx4 v[220:221], off
	v_lshl_add_u64 v[220:221], v[224:225], 0, s[14:15]
	s_mov_b32 m0, s41
	s_nop 0
	global_load_lds_dwordx4 v[220:221], off
	v_lshl_add_u64 v[220:221], v[226:227], 0, s[14:15]
	s_mov_b32 m0, s42
	s_nop 0
	global_load_lds_dwordx4 v[220:221], off
	s_waitcnt vmcnt(8)
	s_waitcnt lgkmcnt(0)
	s_barrier
	s_setprio 1
	s_waitcnt lgkmcnt(0)
	v_mfma_f32_16x16x32_bf16 v[62:65], v[148:151], v[188:191], v[62:65]
	v_mfma_f32_16x16x32_bf16 v[62:65], v[152:155], v[192:195], v[62:65]
	v_mfma_f32_16x16x32_bf16 v[54:57], v[156:159], v[188:191], v[54:57]
	v_mfma_f32_16x16x32_bf16 v[54:57], v[160:163], v[192:195], v[54:57]
	v_mfma_f32_16x16x32_bf16 v[46:49], v[148:151], v[196:199], v[46:49]
	v_mfma_f32_16x16x32_bf16 v[46:49], v[152:155], v[200:203], v[46:49]
	v_mfma_f32_16x16x32_bf16 v[38:41], v[156:159], v[196:199], v[38:41]
	v_mfma_f32_16x16x32_bf16 v[38:41], v[160:163], v[200:203], v[38:41]
	v_mfma_f32_16x16x32_bf16 v[30:33], v[148:151], v[204:207], v[30:33]
	v_mfma_f32_16x16x32_bf16 v[30:33], v[152:155], v[208:211], v[30:33]
	v_mfma_f32_16x16x32_bf16 v[22:25], v[156:159], v[204:207], v[22:25]
	v_mfma_f32_16x16x32_bf16 v[22:25], v[160:163], v[208:211], v[22:25]
	v_mfma_f32_16x16x32_bf16 v[14:17], v[148:151], v[212:215], v[14:17]
	v_mfma_f32_16x16x32_bf16 v[14:17], v[152:155], v[216:219], v[14:17]
	v_mfma_f32_16x16x32_bf16 v[6:9], v[156:159], v[212:215], v[6:9]
	v_mfma_f32_16x16x32_bf16 v[6:9], v[160:163], v[216:219], v[6:9]
	s_setprio 0
	s_setprio 1
	v_mfma_f32_16x16x32_bf16 v[58:61], v[172:175], v[188:191], v[58:61]
	v_mfma_f32_16x16x32_bf16 v[58:61], v[176:179], v[192:195], v[58:61]
	v_mfma_f32_16x16x32_bf16 v[50:53], v[180:183], v[188:191], v[50:53]
	v_mfma_f32_16x16x32_bf16 v[50:53], v[184:187], v[192:195], v[50:53]
	v_mfma_f32_16x16x32_bf16 v[42:45], v[172:175], v[196:199], v[42:45]
	v_mfma_f32_16x16x32_bf16 v[42:45], v[176:179], v[200:203], v[42:45]
	v_mfma_f32_16x16x32_bf16 v[34:37], v[180:183], v[196:199], v[34:37]
	v_mfma_f32_16x16x32_bf16 v[34:37], v[184:187], v[200:203], v[34:37]
	v_mfma_f32_16x16x32_bf16 v[26:29], v[172:175], v[204:207], v[26:29]
	v_mfma_f32_16x16x32_bf16 v[26:29], v[176:179], v[208:211], v[26:29]
	v_mfma_f32_16x16x32_bf16 v[18:21], v[180:183], v[204:207], v[18:21]
	v_mfma_f32_16x16x32_bf16 v[18:21], v[184:187], v[208:211], v[18:21]
	v_mfma_f32_16x16x32_bf16 v[10:13], v[172:175], v[212:215], v[10:13]
	v_mfma_f32_16x16x32_bf16 v[10:13], v[176:179], v[216:219], v[10:13]
	v_mfma_f32_16x16x32_bf16 v[2:5], v[180:183], v[212:215], v[2:5]
	v_mfma_f32_16x16x32_bf16 v[2:5], v[184:187], v[216:219], v[2:5]
	s_setprio 0
	s_barrier
	s_add_i32 s53, s53, 2
	s_add_u32 s28, s28, 0x100
	s_addc_u32 s29, s29, 0
	s_add_u32 s51, s51, 0x100
	s_addc_u32 s52, s52, 0
	s_cmp_gt_u32 s53, 13
	s_cbranch_scc0 .LBB0_1009
	s_and_b64 vcc, exec, s[16:17]
	s_cbranch_vccz .LBB0_1012
	s_barrier

.LBB0_1123:
	ds_read_b128 v[130:133], v187
	ds_read_b128 v[134:137], v187 offset:1024
	ds_read_b128 v[138:141], v187 offset:2048
	ds_read_b128 v[142:145], v187 offset:3072
	ds_read_b128 v[146:149], v188
	ds_read_b128 v[150:153], v188 offset:1024
	ds_read_b128 v[170:173], v188 offset:2048
	ds_read_b128 v[174:177], v188 offset:3072
	s_add_u32 s0, s24, 0xfff50080
	s_addc_u32 s1, s25, -1
	s_cmp_eq_u32 s49, 40
	s_cselect_b32 s27, s9, s1
	s_cselect_b32 s26, s8, s0
	s_cselect_b32 s3, s23, s48
	s_cselect_b32 s2, s22, s47
	v_lshl_add_u64 v[220:221], s[24:25], 0, v[162:163]
	s_add_i32 m0, s34, 0xc000
	ds_read_b128 v[178:181], v189
	ds_read_b128 v[192:195], v189 offset:1024
	ds_read_b128 v[196:199], v189 offset:2048
	ds_read_b128 v[200:203], v189 offset:3072
	ds_read_b128 v[204:207], v189 offset:4096
	ds_read_b128 v[208:211], v189 offset:5120
	ds_read_b128 v[212:215], v189 offset:6144
	ds_read_b128 v[216:219], v189 offset:7168
	global_load_lds_dwordx4 v[220:221], off
	v_lshl_add_u64 v[220:221], s[24:25], 0, v[164:165]
	s_add_i32 m0, s34, 0xe000
	s_nop 0
	global_load_lds_dwordx4 v[220:221], off
	s_waitcnt vmcnt(8)
	s_waitcnt lgkmcnt(0)
	s_barrier
	s_setprio 1
	s_waitcnt lgkmcnt(0)
	v_mfma_f32_16x16x32_bf16 v[126:129], v[130:133], v[178:181], v[126:129]
	v_mfma_f32_16x16x32_bf16 v[126:129], v[134:137], v[192:195], v[126:129]
	v_mfma_f32_16x16x32_bf16 v[122:125], v[138:141], v[178:181], v[122:125]
	v_mfma_f32_16x16x32_bf16 v[122:125], v[142:145], v[192:195], v[122:125]
	v_mfma_f32_16x16x32_bf16 v[110:113], v[130:133], v[196:199], v[110:113]
	v_mfma_f32_16x16x32_bf16 v[110:113], v[134:137], v[200:203], v[110:113]
	v_mfma_f32_16x16x32_bf16 v[106:109], v[138:141], v[196:199], v[106:109]
	v_mfma_f32_16x16x32_bf16 v[106:109], v[142:145], v[200:203], v[106:109]
	v_mfma_f32_16x16x32_bf16 v[94:97], v[130:133], v[204:207], v[94:97]
	v_mfma_f32_16x16x32_bf16 v[94:97], v[134:137], v[208:211], v[94:97]
	v_mfma_f32_16x16x32_bf16 v[90:93], v[138:141], v[204:207], v[90:93]
	v_mfma_f32_16x16x32_bf16 v[90:93], v[142:145], v[208:211], v[90:93]
	v_mfma_f32_16x16x32_bf16 v[78:81], v[130:133], v[212:215], v[78:81]
	v_mfma_f32_16x16x32_bf16 v[78:81], v[134:137], v[216:219], v[78:81]
	v_mfma_f32_16x16x32_bf16 v[74:77], v[138:141], v[212:215], v[74:77]
	v_mfma_f32_16x16x32_bf16 v[74:77], v[142:145], v[216:219], v[74:77]
	s_setprio 0
	s_setprio 1
	v_mfma_f32_16x16x32_bf16 v[118:121], v[146:149], v[178:181], v[118:121]
	v_mfma_f32_16x16x32_bf16 v[118:121], v[150:153], v[192:195], v[118:121]
	v_mfma_f32_16x16x32_bf16 v[114:117], v[170:173], v[178:181], v[114:117]
	v_mfma_f32_16x16x32_bf16 v[114:117], v[174:177], v[192:195], v[114:117]
	v_mfma_f32_16x16x32_bf16 v[102:105], v[146:149], v[196:199], v[102:105]
	v_mfma_f32_16x16x32_bf16 v[102:105], v[150:153], v[200:203], v[102:105]
	v_mfma_f32_16x16x32_bf16 v[98:101], v[170:173], v[196:199], v[98:101]
	v_mfma_f32_16x16x32_bf16 v[98:101], v[174:177], v[200:203], v[98:101]
	v_mfma_f32_16x16x32_bf16 v[86:89], v[146:149], v[204:207], v[86:89]
	v_mfma_f32_16x16x32_bf16 v[86:89], v[150:153], v[208:211], v[86:89]
	v_mfma_f32_16x16x32_bf16 v[82:85], v[170:173], v[204:207], v[82:85]
	v_mfma_f32_16x16x32_bf16 v[82:85], v[174:177], v[208:211], v[82:85]
	v_mfma_f32_16x16x32_bf16 v[70:73], v[146:149], v[212:215], v[70:73]
	v_mfma_f32_16x16x32_bf16 v[70:73], v[150:153], v[216:219], v[70:73]
	v_mfma_f32_16x16x32_bf16 v[66:69], v[170:173], v[212:215], v[66:69]
	v_mfma_f32_16x16x32_bf16 v[66:69], v[174:177], v[216:219], v[66:69]
	s_setprio 0
	s_barrier
	s_add_i32 s0, s43, s33
	v_lshl_add_u64 v[220:221], s[2:3], 0, v[156:157]
	s_mov_b32 m0, s0
	ds_read_b128 v[178:181], v189 offset:16384
	ds_read_b128 v[192:195], v189 offset:17408
	ds_read_b128 v[196:199], v189 offset:18432
	ds_read_b128 v[200:203], v189 offset:19456
	ds_read_b128 v[204:207], v189 offset:20480
	ds_read_b128 v[208:211], v189 offset:21504
	ds_read_b128 v[212:215], v189 offset:22528
	ds_read_b128 v[216:219], v189 offset:23552
	global_load_lds_dwordx4 v[220:221], off
	s_add_i32 m0, s0, 0x2000
	s_add_u32 s0, s2, 0xb0000
	v_lshl_add_u64 v[222:223], s[2:3], 0, v[160:161]
	s_addc_u32 s1, s3, 0
	s_add_i32 s50, s44, s33
	global_load_lds_dwordx4 v[222:223], off
	v_lshl_add_u64 v[224:225], s[0:1], 0, v[156:157]
	s_mov_b32 m0, s50
	v_lshl_add_u64 v[226:227], s[26:27], 0, v[158:159]
	global_load_lds_dwordx4 v[224:225], off
	v_lshl_add_u64 v[224:225], s[0:1], 0, v[160:161]
	s_add_i32 m0, s50, 0x2000
	s_nop 0
	global_load_lds_dwordx4 v[224:225], off
	v_lshl_add_u64 v[224:225], s[26:27], 0, v[154:155]
	s_mov_b32 m0, s34
	s_nop 0
	global_load_lds_dwordx4 v[224:225], off
	s_mov_b32 m0, s35
	s_nop 0
	global_load_lds_dwordx4 v[226:227], off
	s_waitcnt vmcnt(8)
	s_waitcnt lgkmcnt(0)
	s_barrier
	s_setprio 1
	s_waitcnt lgkmcnt(0)
	v_mfma_f32_16x16x32_bf16 v[62:65], v[130:133], v[178:181], v[62:65]
	v_mfma_f32_16x16x32_bf16 v[62:65], v[134:137], v[192:195], v[62:65]
	v_mfma_f32_16x16x32_bf16 v[58:61], v[138:141], v[178:181], v[58:61]
	v_mfma_f32_16x16x32_bf16 v[58:61], v[142:145], v[192:195], v[58:61]
	v_mfma_f32_16x16x32_bf16 v[46:49], v[130:133], v[196:199], v[46:49]
	v_mfma_f32_16x16x32_bf16 v[46:49], v[134:137], v[200:203], v[46:49]
	v_mfma_f32_16x16x32_bf16 v[42:45], v[138:141], v[196:199], v[42:45]
	v_mfma_f32_16x16x32_bf16 v[42:45], v[142:145], v[200:203], v[42:45]
	v_mfma_f32_16x16x32_bf16 v[30:33], v[130:133], v[204:207], v[30:33]
	v_mfma_f32_16x16x32_bf16 v[30:33], v[134:137], v[208:211], v[30:33]
	v_mfma_f32_16x16x32_bf16 v[26:29], v[138:141], v[204:207], v[26:29]
	v_mfma_f32_16x16x32_bf16 v[26:29], v[142:145], v[208:211], v[26:29]
	v_mfma_f32_16x16x32_bf16 v[14:17], v[130:133], v[212:215], v[14:17]
	v_mfma_f32_16x16x32_bf16 v[14:17], v[134:137], v[216:219], v[14:17]
	v_mfma_f32_16x16x32_bf16 v[10:13], v[138:141], v[212:215], v[10:13]
	v_mfma_f32_16x16x32_bf16 v[10:13], v[142:145], v[216:219], v[10:13]
	s_setprio 0
	s_setprio 1
	v_mfma_f32_16x16x32_bf16 v[54:57], v[146:149], v[178:181], v[54:57]
	v_mfma_f32_16x16x32_bf16 v[54:57], v[150:153], v[192:195], v[54:57]
	v_mfma_f32_16x16x32_bf16 v[50:53], v[170:173], v[178:181], v[50:53]
	v_mfma_f32_16x16x32_bf16 v[50:53], v[174:177], v[192:195], v[50:53]
	v_mfma_f32_16x16x32_bf16 v[38:41], v[146:149], v[196:199], v[38:41]
	v_mfma_f32_16x16x32_bf16 v[38:41], v[150:153], v[200:203], v[38:41]
	v_mfma_f32_16x16x32_bf16 v[34:37], v[170:173], v[196:199], v[34:37]
	v_mfma_f32_16x16x32_bf16 v[34:37], v[174:177], v[200:203], v[34:37]
	v_mfma_f32_16x16x32_bf16 v[22:25], v[146:149], v[204:207], v[22:25]
	v_mfma_f32_16x16x32_bf16 v[22:25], v[150:153], v[208:211], v[22:25]
	v_mfma_f32_16x16x32_bf16 v[18:21], v[170:173], v[204:207], v[18:21]
	v_mfma_f32_16x16x32_bf16 v[18:21], v[174:177], v[208:211], v[18:21]
	v_mfma_f32_16x16x32_bf16 v[6:9], v[146:149], v[212:215], v[6:9]
	v_mfma_f32_16x16x32_bf16 v[6:9], v[150:153], v[216:219], v[6:9]
	v_mfma_f32_16x16x32_bf16 v[2:5], v[170:173], v[212:215], v[2:5]
	v_mfma_f32_16x16x32_bf16 v[2:5], v[174:177], v[216:219], v[2:5]
	s_setprio 0
	s_barrier
	s_add_i32 s50, 0, 0x18000
	s_add_i32 s51, 0, 0x1c000
	v_add_u32_e32 v142, s50, v183
	v_add_u32_e32 v174, s51, v183
	ds_read_b128 v[130:133], v142
	ds_read_b128 v[134:137], v142 offset:1024
	ds_read_b128 v[138:141], v142 offset:2048
	ds_read_b128 v[142:145], v142 offset:3072
	ds_read_b128 v[146:149], v174
	ds_read_b128 v[150:153], v174 offset:1024
	ds_read_b128 v[170:173], v174 offset:2048
	ds_read_b128 v[174:177], v174 offset:3072
	s_add_u32 s0, s26, 0xb0000
	s_addc_u32 s1, s27, 0
	s_mov_b32 m0, s36
	v_lshl_add_u64 v[228:229], s[0:1], 0, v[154:155]
	ds_read_b128 v[178:181], v189 offset:32768
	ds_read_b128 v[192:195], v189 offset:33792
	ds_read_b128 v[196:199], v189 offset:34816
	ds_read_b128 v[200:203], v189 offset:35840
	ds_read_b128 v[204:207], v189 offset:36864
	ds_read_b128 v[208:211], v189 offset:37888
	ds_read_b128 v[212:215], v189 offset:38912
	ds_read_b128 v[216:219], v189 offset:39936
	global_load_lds_dwordx4 v[228:229], off
	v_lshl_add_u64 v[228:229], s[0:1], 0, v[158:159]
	s_mov_b32 m0, s37
	s_nop 0
	global_load_lds_dwordx4 v[228:229], off
	s_waitcnt vmcnt(8)
	s_waitcnt lgkmcnt(0)
	s_barrier
	s_setprio 1
	s_waitcnt lgkmcnt(0)
	v_mfma_f32_16x16x32_bf16 v[126:129], v[130:133], v[178:181], v[126:129]
	v_mfma_f32_16x16x32_bf16 v[126:129], v[134:137], v[192:195], v[126:129]
	v_mfma_f32_16x16x32_bf16 v[122:125], v[138:141], v[178:181], v[122:125]
	v_mfma_f32_16x16x32_bf16 v[122:125], v[142:145], v[192:195], v[122:125]
	v_mfma_f32_16x16x32_bf16 v[110:113], v[130:133], v[196:199], v[110:113]
	v_mfma_f32_16x16x32_bf16 v[110:113], v[134:137], v[200:203], v[110:113]
	v_mfma_f32_16x16x32_bf16 v[106:109], v[138:141], v[196:199], v[106:109]
	v_mfma_f32_16x16x32_bf16 v[106:109], v[142:145], v[200:203], v[106:109]
	v_mfma_f32_16x16x32_bf16 v[94:97], v[130:133], v[204:207], v[94:97]
	v_mfma_f32_16x16x32_bf16 v[94:97], v[134:137], v[208:211], v[94:97]
	v_mfma_f32_16x16x32_bf16 v[90:93], v[138:141], v[204:207], v[90:93]
	v_mfma_f32_16x16x32_bf16 v[90:93], v[142:145], v[208:211], v[90:93]
	v_mfma_f32_16x16x32_bf16 v[78:81], v[130:133], v[212:215], v[78:81]
	v_mfma_f32_16x16x32_bf16 v[78:81], v[134:137], v[216:219], v[78:81]
	v_mfma_f32_16x16x32_bf16 v[74:77], v[138:141], v[212:215], v[74:77]
	v_mfma_f32_16x16x32_bf16 v[74:77], v[142:145], v[216:219], v[74:77]
	s_setprio 0
	s_setprio 1
	v_mfma_f32_16x16x32_bf16 v[118:121], v[146:149], v[178:181], v[118:121]
	v_mfma_f32_16x16x32_bf16 v[118:121], v[150:153], v[192:195], v[118:121]
	v_mfma_f32_16x16x32_bf16 v[114:117], v[170:173], v[178:181], v[114:117]
	v_mfma_f32_16x16x32_bf16 v[114:117], v[174:177], v[192:195], v[114:117]
	v_mfma_f32_16x16x32_bf16 v[102:105], v[146:149], v[196:199], v[102:105]
	v_mfma_f32_16x16x32_bf16 v[102:105], v[150:153], v[200:203], v[102:105]
	v_mfma_f32_16x16x32_bf16 v[98:101], v[170:173], v[196:199], v[98:101]
	v_mfma_f32_16x16x32_bf16 v[98:101], v[174:177], v[200:203], v[98:101]
	v_mfma_f32_16x16x32_bf16 v[86:89], v[146:149], v[204:207], v[86:89]
	v_mfma_f32_16x16x32_bf16 v[86:89], v[150:153], v[208:211], v[86:89]
	v_mfma_f32_16x16x32_bf16 v[82:85], v[170:173], v[204:207], v[82:85]
	v_mfma_f32_16x16x32_bf16 v[82:85], v[174:177], v[208:211], v[82:85]
	v_mfma_f32_16x16x32_bf16 v[70:73], v[146:149], v[212:215], v[70:73]
	v_mfma_f32_16x16x32_bf16 v[70:73], v[150:153], v[216:219], v[70:73]
	v_mfma_f32_16x16x32_bf16 v[66:69], v[170:173], v[212:215], v[66:69]
	v_mfma_f32_16x16x32_bf16 v[66:69], v[174:177], v[216:219], v[66:69]
	s_setprio 0
	s_barrier
	s_add_i32 s0, s50, s33
	v_lshl_add_u64 v[220:221], v[220:221], 0, s[16:17]
	s_mov_b32 m0, s0
	ds_read_b128 v[178:181], v189 offset:49152
	ds_read_b128 v[192:195], v189 offset:50176
	ds_read_b128 v[196:199], v189 offset:51200
	ds_read_b128 v[200:203], v189 offset:52224
	ds_read_b128 v[204:207], v189 offset:53248
	ds_read_b128 v[208:211], v189 offset:54272
	ds_read_b128 v[212:215], v189 offset:55296
	ds_read_b128 v[216:219], v189 offset:56320
	global_load_lds_dwordx4 v[220:221], off
	s_add_i32 m0, s0, 0x2000
	s_add_u32 s0, s2, 0xb0080
	v_lshl_add_u64 v[220:221], v[222:223], 0, s[16:17]
	s_addc_u32 s1, s3, 0
	s_add_i32 s2, s51, s33
	global_load_lds_dwordx4 v[220:221], off
	v_lshl_add_u64 v[220:221], s[0:1], 0, v[156:157]
	s_mov_b32 m0, s2
	s_nop 0
	global_load_lds_dwordx4 v[220:221], off
	v_lshl_add_u64 v[220:221], s[0:1], 0, v[160:161]
	s_add_i32 m0, s2, 0x2000
	s_nop 0
	global_load_lds_dwordx4 v[220:221], off
	v_lshl_add_u64 v[220:221], v[224:225], 0, s[16:17]
	s_mov_b32 m0, s39
	s_nop 0
	global_load_lds_dwordx4 v[220:221], off
	v_lshl_add_u64 v[220:221], v[226:227], 0, s[16:17]
	s_mov_b32 m0, s40
	s_nop 0
	global_load_lds_dwordx4 v[220:221], off
	s_waitcnt vmcnt(8)
	s_waitcnt lgkmcnt(0)
	s_barrier
	s_setprio 1
	s_waitcnt lgkmcnt(0)
	v_mfma_f32_16x16x32_bf16 v[62:65], v[130:133], v[178:181], v[62:65]
	v_mfma_f32_16x16x32_bf16 v[62:65], v[134:137], v[192:195], v[62:65]
	v_mfma_f32_16x16x32_bf16 v[58:61], v[138:141], v[178:181], v[58:61]
	v_mfma_f32_16x16x32_bf16 v[58:61], v[142:145], v[192:195], v[58:61]
	v_mfma_f32_16x16x32_bf16 v[46:49], v[130:133], v[196:199], v[46:49]
	v_mfma_f32_16x16x32_bf16 v[46:49], v[134:137], v[200:203], v[46:49]
	v_mfma_f32_16x16x32_bf16 v[42:45], v[138:141], v[196:199], v[42:45]
	v_mfma_f32_16x16x32_bf16 v[42:45], v[142:145], v[200:203], v[42:45]
	v_mfma_f32_16x16x32_bf16 v[30:33], v[130:133], v[204:207], v[30:33]
	v_mfma_f32_16x16x32_bf16 v[30:33], v[134:137], v[208:211], v[30:33]
	v_mfma_f32_16x16x32_bf16 v[26:29], v[138:141], v[204:207], v[26:29]
	v_mfma_f32_16x16x32_bf16 v[26:29], v[142:145], v[208:211], v[26:29]
	v_mfma_f32_16x16x32_bf16 v[14:17], v[130:133], v[212:215], v[14:17]
	v_mfma_f32_16x16x32_bf16 v[14:17], v[134:137], v[216:219], v[14:17]
	v_mfma_f32_16x16x32_bf16 v[10:13], v[138:141], v[212:215], v[10:13]
	v_mfma_f32_16x16x32_bf16 v[10:13], v[142:145], v[216:219], v[10:13]
	s_setprio 0
	s_setprio 1
	v_mfma_f32_16x16x32_bf16 v[54:57], v[146:149], v[178:181], v[54:57]
	v_mfma_f32_16x16x32_bf16 v[54:57], v[150:153], v[192:195], v[54:57]
	v_mfma_f32_16x16x32_bf16 v[50:53], v[170:173], v[178:181], v[50:53]
	v_mfma_f32_16x16x32_bf16 v[50:53], v[174:177], v[192:195], v[50:53]
	v_mfma_f32_16x16x32_bf16 v[38:41], v[146:149], v[196:199], v[38:41]
	v_mfma_f32_16x16x32_bf16 v[38:41], v[150:153], v[200:203], v[38:41]
	v_mfma_f32_16x16x32_bf16 v[34:37], v[170:173], v[196:199], v[34:37]
	v_mfma_f32_16x16x32_bf16 v[34:37], v[174:177], v[200:203], v[34:37]
	v_mfma_f32_16x16x32_bf16 v[22:25], v[146:149], v[204:207], v[22:25]
	v_mfma_f32_16x16x32_bf16 v[22:25], v[150:153], v[208:211], v[22:25]
	v_mfma_f32_16x16x32_bf16 v[18:21], v[170:173], v[204:207], v[18:21]
	v_mfma_f32_16x16x32_bf16 v[18:21], v[174:177], v[208:211], v[18:21]
	v_mfma_f32_16x16x32_bf16 v[6:9], v[146:149], v[212:215], v[6:9]
	v_mfma_f32_16x16x32_bf16 v[6:9], v[150:153], v[216:219], v[6:9]
	v_mfma_f32_16x16x32_bf16 v[2:5], v[170:173], v[212:215], v[2:5]
	v_mfma_f32_16x16x32_bf16 v[2:5], v[174:177], v[216:219], v[2:5]
	s_setprio 0
	s_barrier
	s_add_i32 s49, s49, 2
	s_add_u32 s24, s24, 0x100
	s_addc_u32 s25, s25, 0
	s_add_u32 s47, s47, 0x100
	s_addc_u32 s48, s48, 0
	s_cmp_gt_u32 s49, 41
	s_cbranch_scc0 .LBB0_1123
	s_and_b64 vcc, exec, s[18:19]
	s_cbranch_vccz .LBB0_1126
	s_barrier

.LBB0_1214:
	ds_read_b128 v[62:65], v208
	ds_read_b128 v[78:81], v208 offset:1024
	ds_read_b128 v[98:101], v208 offset:2048
	ds_read_b128 v[118:121], v208 offset:3072
	ds_read_b128 v[138:141], v209
	ds_read_b128 v[150:153], v209 offset:1024
	ds_read_b128 v[154:157], v209 offset:2048
	ds_read_b128 v[178:181], v209 offset:3072
	s_add_u32 s0, s38, 0xfffc0080
	s_addc_u32 s1, s39, -1
	s_cmp_eq_u32 s58, 12
	s_cselect_b32 s41, s7, s1
	s_cselect_b32 s40, s9, s0
	s_cselect_b32 s3, s10, s57
	s_cselect_b32 s2, s29, s31
	v_lshl_add_u64 v[202:203], s[38:39], 0, v[170:171]
	s_add_i32 m0, s43, 0xc000
	ds_read_b128 v[182:185], v210
	ds_read_b128 v[186:189], v210 offset:1024
	ds_read_b128 v[190:193], v210 offset:2048
	ds_read_b128 v[194:197], v210 offset:3072
	ds_read_b128 v[198:201], v210 offset:4096
	ds_read_b128 v[212:215], v210 offset:5120
	ds_read_b128 v[216:219], v210 offset:6144
	ds_read_b128 v[220:223], v210 offset:7168
	global_load_lds_dwordx4 v[202:203], off
	v_lshl_add_u64 v[202:203], s[38:39], 0, v[172:173]
	s_add_i32 m0, s43, 0xe000
	s_nop 0
	global_load_lds_dwordx4 v[202:203], off
	s_waitcnt vmcnt(8)
	s_waitcnt lgkmcnt(0)
	s_barrier
	s_setprio 1
	s_waitcnt lgkmcnt(0)
	v_mfma_f32_16x16x32_bf16 v[146:149], v[62:65], v[182:185], v[146:149]
	v_mfma_f32_16x16x32_bf16 v[146:149], v[78:81], v[186:189], v[146:149]
	v_mfma_f32_16x16x32_bf16 v[142:145], v[98:101], v[182:185], v[142:145]
	v_mfma_f32_16x16x32_bf16 v[142:145], v[118:121], v[186:189], v[142:145]
	v_mfma_f32_16x16x32_bf16 v[126:129], v[62:65], v[190:193], v[126:129]
	v_mfma_f32_16x16x32_bf16 v[126:129], v[78:81], v[194:197], v[126:129]
	v_mfma_f32_16x16x32_bf16 v[122:125], v[98:101], v[190:193], v[122:125]
	v_mfma_f32_16x16x32_bf16 v[122:125], v[118:121], v[194:197], v[122:125]
	v_mfma_f32_16x16x32_bf16 v[106:109], v[62:65], v[198:201], v[106:109]
	v_mfma_f32_16x16x32_bf16 v[106:109], v[78:81], v[212:215], v[106:109]
	v_mfma_f32_16x16x32_bf16 v[102:105], v[98:101], v[198:201], v[102:105]
	v_mfma_f32_16x16x32_bf16 v[102:105], v[118:121], v[212:215], v[102:105]
	v_mfma_f32_16x16x32_bf16 v[86:89], v[62:65], v[216:219], v[86:89]
	v_mfma_f32_16x16x32_bf16 v[86:89], v[78:81], v[220:223], v[86:89]
	v_mfma_f32_16x16x32_bf16 v[82:85], v[98:101], v[216:219], v[82:85]
	v_mfma_f32_16x16x32_bf16 v[82:85], v[118:121], v[220:223], v[82:85]
	s_setprio 0
	s_setprio 1
	v_mfma_f32_16x16x32_bf16 v[134:137], v[138:141], v[182:185], v[134:137]
	v_mfma_f32_16x16x32_bf16 v[134:137], v[150:153], v[186:189], v[134:137]
	v_mfma_f32_16x16x32_bf16 v[130:133], v[154:157], v[182:185], v[130:133]
	v_mfma_f32_16x16x32_bf16 v[130:133], v[178:181], v[186:189], v[130:133]
	v_mfma_f32_16x16x32_bf16 v[114:117], v[138:141], v[190:193], v[114:117]
	v_mfma_f32_16x16x32_bf16 v[114:117], v[150:153], v[194:197], v[114:117]
	v_mfma_f32_16x16x32_bf16 v[110:113], v[154:157], v[190:193], v[110:113]
	v_mfma_f32_16x16x32_bf16 v[110:113], v[178:181], v[194:197], v[110:113]
	v_mfma_f32_16x16x32_bf16 v[94:97], v[138:141], v[198:201], v[94:97]
	v_mfma_f32_16x16x32_bf16 v[94:97], v[150:153], v[212:215], v[94:97]
	v_mfma_f32_16x16x32_bf16 v[90:93], v[154:157], v[198:201], v[90:93]
	v_mfma_f32_16x16x32_bf16 v[90:93], v[178:181], v[212:215], v[90:93]
	v_mfma_f32_16x16x32_bf16 v[74:77], v[138:141], v[216:219], v[74:77]
	v_mfma_f32_16x16x32_bf16 v[74:77], v[150:153], v[220:223], v[74:77]
	v_mfma_f32_16x16x32_bf16 v[70:73], v[154:157], v[216:219], v[70:73]
	v_mfma_f32_16x16x32_bf16 v[70:73], v[178:181], v[220:223], v[70:73]
	s_setprio 0
	s_barrier
	s_add_i32 s0, s53, s42
	v_lshl_add_u64 v[202:203], s[2:3], 0, v[162:163]
	s_mov_b32 m0, s0
	ds_read_b128 v[182:185], v210 offset:16384
	ds_read_b128 v[186:189], v210 offset:17408
	ds_read_b128 v[190:193], v210 offset:18432
	ds_read_b128 v[194:197], v210 offset:19456
	ds_read_b128 v[198:201], v210 offset:20480
	ds_read_b128 v[212:215], v210 offset:21504
	ds_read_b128 v[216:219], v210 offset:22528
	ds_read_b128 v[220:223], v210 offset:23552
	global_load_lds_dwordx4 v[202:203], off
	s_add_i32 m0, s0, 0x2000
	s_add_u32 s0, s2, 0x40000
	v_lshl_add_u64 v[224:225], s[2:3], 0, v[166:167]
	s_addc_u32 s1, s3, 0
	s_add_i32 s59, s54, s42
	global_load_lds_dwordx4 v[224:225], off
	v_lshl_add_u64 v[226:227], s[0:1], 0, v[162:163]
	s_mov_b32 m0, s59
	v_lshl_add_u64 v[228:229], s[40:41], 0, v[164:165]
	global_load_lds_dwordx4 v[226:227], off
	v_lshl_add_u64 v[226:227], s[0:1], 0, v[166:167]
	s_add_i32 m0, s59, 0x2000
	s_nop 0
	global_load_lds_dwordx4 v[226:227], off
	v_lshl_add_u64 v[226:227], s[40:41], 0, v[160:161]
	s_mov_b32 m0, s43
	s_nop 0
	global_load_lds_dwordx4 v[226:227], off
	s_mov_b32 m0, s44
	s_nop 0
	global_load_lds_dwordx4 v[228:229], off
	s_waitcnt vmcnt(8)
	s_waitcnt lgkmcnt(0)
	s_barrier
	s_setprio 1
	s_waitcnt lgkmcnt(0)
	v_mfma_f32_16x16x32_bf16 v[66:69], v[62:65], v[182:185], v[66:69]
	v_mfma_f32_16x16x32_bf16 v[66:69], v[78:81], v[186:189], v[66:69]
	v_mfma_f32_16x16x32_bf16 v[58:61], v[98:101], v[182:185], v[58:61]
	v_mfma_f32_16x16x32_bf16 v[58:61], v[118:121], v[186:189], v[58:61]
	v_mfma_f32_16x16x32_bf16 v[46:49], v[62:65], v[190:193], v[46:49]
	v_mfma_f32_16x16x32_bf16 v[46:49], v[78:81], v[194:197], v[46:49]
	v_mfma_f32_16x16x32_bf16 v[42:45], v[98:101], v[190:193], v[42:45]
	v_mfma_f32_16x16x32_bf16 v[42:45], v[118:121], v[194:197], v[42:45]
	v_mfma_f32_16x16x32_bf16 v[30:33], v[62:65], v[198:201], v[30:33]
	v_mfma_f32_16x16x32_bf16 v[30:33], v[78:81], v[212:215], v[30:33]
	v_mfma_f32_16x16x32_bf16 v[26:29], v[98:101], v[198:201], v[26:29]
	v_mfma_f32_16x16x32_bf16 v[26:29], v[118:121], v[212:215], v[26:29]
	v_mfma_f32_16x16x32_bf16 v[14:17], v[62:65], v[216:219], v[14:17]
	v_mfma_f32_16x16x32_bf16 v[14:17], v[78:81], v[220:223], v[14:17]
	v_mfma_f32_16x16x32_bf16 v[10:13], v[98:101], v[216:219], v[10:13]
	v_mfma_f32_16x16x32_bf16 v[10:13], v[118:121], v[220:223], v[10:13]
	s_setprio 0
	s_setprio 1
	v_mfma_f32_16x16x32_bf16 v[54:57], v[138:141], v[182:185], v[54:57]
	v_mfma_f32_16x16x32_bf16 v[54:57], v[150:153], v[186:189], v[54:57]
	v_mfma_f32_16x16x32_bf16 v[50:53], v[154:157], v[182:185], v[50:53]
	v_mfma_f32_16x16x32_bf16 v[50:53], v[178:181], v[186:189], v[50:53]
	v_mfma_f32_16x16x32_bf16 v[38:41], v[138:141], v[190:193], v[38:41]
	v_mfma_f32_16x16x32_bf16 v[38:41], v[150:153], v[194:197], v[38:41]
	v_mfma_f32_16x16x32_bf16 v[34:37], v[154:157], v[190:193], v[34:37]
	v_mfma_f32_16x16x32_bf16 v[34:37], v[178:181], v[194:197], v[34:37]
	v_mfma_f32_16x16x32_bf16 v[22:25], v[138:141], v[198:201], v[22:25]
	v_mfma_f32_16x16x32_bf16 v[22:25], v[150:153], v[212:215], v[22:25]
	v_mfma_f32_16x16x32_bf16 v[18:21], v[154:157], v[198:201], v[18:21]
	v_mfma_f32_16x16x32_bf16 v[18:21], v[178:181], v[212:215], v[18:21]
	v_mfma_f32_16x16x32_bf16 v[6:9], v[138:141], v[216:219], v[6:9]
	v_mfma_f32_16x16x32_bf16 v[6:9], v[150:153], v[220:223], v[6:9]
	v_mfma_f32_16x16x32_bf16 v[2:5], v[154:157], v[216:219], v[2:5]
	v_mfma_f32_16x16x32_bf16 v[2:5], v[178:181], v[220:223], v[2:5]
	s_setprio 0
	s_barrier
	s_add_i32 s59, 0, 0x18000
	s_add_i32 s60, 0, 0x1c000
	v_add_u32_e32 v118, s59, v206
	v_add_u32_e32 v168, s60, v206
	ds_read_b128 v[62:65], v118
	ds_read_b128 v[78:81], v118 offset:1024
	ds_read_b128 v[98:101], v118 offset:2048
	ds_read_b128 v[118:121], v118 offset:3072
	ds_read_b128 v[138:141], v168
	ds_read_b128 v[150:153], v168 offset:1024
	ds_read_b128 v[154:157], v168 offset:2048
	ds_read_b128 v[178:181], v168 offset:3072
	s_add_u32 s0, s40, 0x40000
	s_addc_u32 s1, s41, 0
	s_mov_b32 m0, s45
	v_lshl_add_u64 v[230:231], s[0:1], 0, v[160:161]
	ds_read_b128 v[182:185], v210 offset:32768
	ds_read_b128 v[186:189], v210 offset:33792
	ds_read_b128 v[190:193], v210 offset:34816
	ds_read_b128 v[194:197], v210 offset:35840
	ds_read_b128 v[198:201], v210 offset:36864
	ds_read_b128 v[212:215], v210 offset:37888
	ds_read_b128 v[216:219], v210 offset:38912
	ds_read_b128 v[220:223], v210 offset:39936
	global_load_lds_dwordx4 v[230:231], off
	v_lshl_add_u64 v[230:231], s[0:1], 0, v[164:165]
	s_mov_b32 m0, s46
	s_nop 0
	global_load_lds_dwordx4 v[230:231], off
	s_waitcnt vmcnt(8)
	s_waitcnt lgkmcnt(0)
	s_barrier
	s_setprio 1
	s_waitcnt lgkmcnt(0)
	v_mfma_f32_16x16x32_bf16 v[146:149], v[62:65], v[182:185], v[146:149]
	v_mfma_f32_16x16x32_bf16 v[146:149], v[78:81], v[186:189], v[146:149]
	v_mfma_f32_16x16x32_bf16 v[142:145], v[98:101], v[182:185], v[142:145]
	v_mfma_f32_16x16x32_bf16 v[142:145], v[118:121], v[186:189], v[142:145]
	v_mfma_f32_16x16x32_bf16 v[126:129], v[62:65], v[190:193], v[126:129]
	v_mfma_f32_16x16x32_bf16 v[126:129], v[78:81], v[194:197], v[126:129]
	v_mfma_f32_16x16x32_bf16 v[122:125], v[98:101], v[190:193], v[122:125]
	v_mfma_f32_16x16x32_bf16 v[122:125], v[118:121], v[194:197], v[122:125]
	v_mfma_f32_16x16x32_bf16 v[106:109], v[62:65], v[198:201], v[106:109]
	v_mfma_f32_16x16x32_bf16 v[106:109], v[78:81], v[212:215], v[106:109]
	v_mfma_f32_16x16x32_bf16 v[102:105], v[98:101], v[198:201], v[102:105]
	v_mfma_f32_16x16x32_bf16 v[102:105], v[118:121], v[212:215], v[102:105]
	v_mfma_f32_16x16x32_bf16 v[86:89], v[62:65], v[216:219], v[86:89]
	v_mfma_f32_16x16x32_bf16 v[86:89], v[78:81], v[220:223], v[86:89]
	v_mfma_f32_16x16x32_bf16 v[82:85], v[98:101], v[216:219], v[82:85]
	v_mfma_f32_16x16x32_bf16 v[82:85], v[118:121], v[220:223], v[82:85]
	s_setprio 0
	s_setprio 1
	v_mfma_f32_16x16x32_bf16 v[134:137], v[138:141], v[182:185], v[134:137]
	v_mfma_f32_16x16x32_bf16 v[134:137], v[150:153], v[186:189], v[134:137]
	v_mfma_f32_16x16x32_bf16 v[130:133], v[154:157], v[182:185], v[130:133]
	v_mfma_f32_16x16x32_bf16 v[130:133], v[178:181], v[186:189], v[130:133]
	v_mfma_f32_16x16x32_bf16 v[114:117], v[138:141], v[190:193], v[114:117]
	v_mfma_f32_16x16x32_bf16 v[114:117], v[150:153], v[194:197], v[114:117]
	v_mfma_f32_16x16x32_bf16 v[110:113], v[154:157], v[190:193], v[110:113]
	v_mfma_f32_16x16x32_bf16 v[110:113], v[178:181], v[194:197], v[110:113]
	v_mfma_f32_16x16x32_bf16 v[94:97], v[138:141], v[198:201], v[94:97]
	v_mfma_f32_16x16x32_bf16 v[94:97], v[150:153], v[212:215], v[94:97]
	v_mfma_f32_16x16x32_bf16 v[90:93], v[154:157], v[198:201], v[90:93]
	v_mfma_f32_16x16x32_bf16 v[90:93], v[178:181], v[212:215], v[90:93]
	v_mfma_f32_16x16x32_bf16 v[74:77], v[138:141], v[216:219], v[74:77]
	v_mfma_f32_16x16x32_bf16 v[74:77], v[150:153], v[220:223], v[74:77]
	v_mfma_f32_16x16x32_bf16 v[70:73], v[154:157], v[216:219], v[70:73]
	v_mfma_f32_16x16x32_bf16 v[70:73], v[178:181], v[220:223], v[70:73]
	s_setprio 0
	s_barrier
	s_add_i32 s0, s59, s42
	v_lshl_add_u64 v[202:203], v[202:203], 0, s[22:23]
	s_mov_b32 m0, s0
	ds_read_b128 v[182:185], v210 offset:49152
	ds_read_b128 v[186:189], v210 offset:50176
	ds_read_b128 v[190:193], v210 offset:51200
	ds_read_b128 v[194:197], v210 offset:52224
	ds_read_b128 v[198:201], v210 offset:53248
	ds_read_b128 v[212:215], v210 offset:54272
	ds_read_b128 v[216:219], v210 offset:55296
	ds_read_b128 v[220:223], v210 offset:56320
	global_load_lds_dwordx4 v[202:203], off
	s_add_i32 m0, s0, 0x2000
	s_add_u32 s0, s2, 0x40080
	v_lshl_add_u64 v[202:203], v[224:225], 0, s[22:23]
	s_addc_u32 s1, s3, 0
	s_add_i32 s2, s60, s42
	global_load_lds_dwordx4 v[202:203], off
	v_lshl_add_u64 v[202:203], s[0:1], 0, v[162:163]
	s_mov_b32 m0, s2
	s_nop 0
	global_load_lds_dwordx4 v[202:203], off
	v_lshl_add_u64 v[202:203], s[0:1], 0, v[166:167]
	s_add_i32 m0, s2, 0x2000
	s_nop 0
	global_load_lds_dwordx4 v[202:203], off
	v_lshl_add_u64 v[202:203], v[226:227], 0, s[22:23]
	s_mov_b32 m0, s49
	s_nop 0
	global_load_lds_dwordx4 v[202:203], off
	v_lshl_add_u64 v[202:203], v[228:229], 0, s[22:23]
	s_mov_b32 m0, s50
	s_nop 0
	global_load_lds_dwordx4 v[202:203], off
	s_waitcnt vmcnt(8)
	s_waitcnt lgkmcnt(0)
	s_barrier
	s_setprio 1
	s_waitcnt lgkmcnt(0)
	v_mfma_f32_16x16x32_bf16 v[66:69], v[62:65], v[182:185], v[66:69]
	v_mfma_f32_16x16x32_bf16 v[66:69], v[78:81], v[186:189], v[66:69]
	v_mfma_f32_16x16x32_bf16 v[58:61], v[98:101], v[182:185], v[58:61]
	v_mfma_f32_16x16x32_bf16 v[58:61], v[118:121], v[186:189], v[58:61]
	v_mfma_f32_16x16x32_bf16 v[46:49], v[62:65], v[190:193], v[46:49]
	v_mfma_f32_16x16x32_bf16 v[46:49], v[78:81], v[194:197], v[46:49]
	v_mfma_f32_16x16x32_bf16 v[42:45], v[98:101], v[190:193], v[42:45]
	v_mfma_f32_16x16x32_bf16 v[42:45], v[118:121], v[194:197], v[42:45]
	v_mfma_f32_16x16x32_bf16 v[30:33], v[62:65], v[198:201], v[30:33]
	v_mfma_f32_16x16x32_bf16 v[30:33], v[78:81], v[212:215], v[30:33]
	v_mfma_f32_16x16x32_bf16 v[26:29], v[98:101], v[198:201], v[26:29]
	v_mfma_f32_16x16x32_bf16 v[26:29], v[118:121], v[212:215], v[26:29]
	v_mfma_f32_16x16x32_bf16 v[14:17], v[62:65], v[216:219], v[14:17]
	v_mfma_f32_16x16x32_bf16 v[14:17], v[78:81], v[220:223], v[14:17]
	v_mfma_f32_16x16x32_bf16 v[10:13], v[98:101], v[216:219], v[10:13]
	v_mfma_f32_16x16x32_bf16 v[10:13], v[118:121], v[220:223], v[10:13]
	s_setprio 0
	s_setprio 1
	v_mfma_f32_16x16x32_bf16 v[54:57], v[138:141], v[182:185], v[54:57]
	v_mfma_f32_16x16x32_bf16 v[54:57], v[150:153], v[186:189], v[54:57]
	v_mfma_f32_16x16x32_bf16 v[50:53], v[154:157], v[182:185], v[50:53]
	v_mfma_f32_16x16x32_bf16 v[50:53], v[178:181], v[186:189], v[50:53]
	v_mfma_f32_16x16x32_bf16 v[38:41], v[138:141], v[190:193], v[38:41]
	v_mfma_f32_16x16x32_bf16 v[38:41], v[150:153], v[194:197], v[38:41]
	v_mfma_f32_16x16x32_bf16 v[34:37], v[154:157], v[190:193], v[34:37]
	v_mfma_f32_16x16x32_bf16 v[34:37], v[178:181], v[194:197], v[34:37]
	v_mfma_f32_16x16x32_bf16 v[22:25], v[138:141], v[198:201], v[22:25]
	v_mfma_f32_16x16x32_bf16 v[22:25], v[150:153], v[212:215], v[22:25]
	v_mfma_f32_16x16x32_bf16 v[18:21], v[154:157], v[198:201], v[18:21]
	v_mfma_f32_16x16x32_bf16 v[18:21], v[178:181], v[212:215], v[18:21]
	v_mfma_f32_16x16x32_bf16 v[6:9], v[138:141], v[216:219], v[6:9]
	v_mfma_f32_16x16x32_bf16 v[6:9], v[150:153], v[220:223], v[6:9]
	v_mfma_f32_16x16x32_bf16 v[2:5], v[154:157], v[216:219], v[2:5]
	v_mfma_f32_16x16x32_bf16 v[2:5], v[178:181], v[220:223], v[2:5]
	s_setprio 0
	s_barrier
	s_add_i32 s58, s58, 2
	s_add_u32 s38, s38, 0x100
	s_addc_u32 s39, s39, 0
	s_add_u32 s31, s31, 0x100
	s_addc_u32 s57, s57, 0
	s_cmp_gt_u32 s58, 13
	s_cbranch_scc0 .LBB0_1214
	s_and_b64 vcc, exec, s[24:25]
	s_cbranch_vccz .LBB0_1217
	s_barrier

.LBB0_1626:
	ds_read_b128 v[130:133], v186
	ds_read_b128 v[134:137], v186 offset:1024
	ds_read_b128 v[138:141], v186 offset:2048
	ds_read_b128 v[142:145], v186 offset:3072
	ds_read_b128 v[146:149], v187
	ds_read_b128 v[150:153], v187 offset:1024
	ds_read_b128 v[170:173], v187 offset:2048
	ds_read_b128 v[174:177], v187 offset:3072
	s_add_u32 s0, s38, 0xfff80080
	s_addc_u32 s1, s39, -1
	s_cmp_eq_u32 s59, 28
	s_cselect_b32 s41, s11, s1
	s_cselect_b32 s40, s29, s0
	s_cselect_b32 s3, s27, s58
	s_cselect_b32 s2, s56, s57
	v_lshl_add_u64 v[218:219], s[38:39], 0, v[162:163]
	s_add_i32 m0, s37, 0xc000
	ds_read_b128 v[178:181], v188
	ds_read_b128 v[190:193], v188 offset:1024
	ds_read_b128 v[194:197], v188 offset:2048
	ds_read_b128 v[198:201], v188 offset:3072
	ds_read_b128 v[202:205], v188 offset:4096
	ds_read_b128 v[206:209], v188 offset:5120
	ds_read_b128 v[210:213], v188 offset:6144
	ds_read_b128 v[214:217], v188 offset:7168
	global_load_lds_dwordx4 v[218:219], off
	v_lshl_add_u64 v[218:219], s[38:39], 0, v[164:165]
	s_add_i32 m0, s37, 0xe000
	s_nop 0
	global_load_lds_dwordx4 v[218:219], off
	s_waitcnt vmcnt(8)
	s_waitcnt lgkmcnt(0)
	s_barrier
	s_setprio 1
	s_waitcnt lgkmcnt(0)
	v_mfma_f32_16x16x32_bf16 v[126:129], v[130:133], v[178:181], v[126:129]
	v_mfma_f32_16x16x32_bf16 v[126:129], v[134:137], v[190:193], v[126:129]
	v_mfma_f32_16x16x32_bf16 v[122:125], v[138:141], v[178:181], v[122:125]
	v_mfma_f32_16x16x32_bf16 v[122:125], v[142:145], v[190:193], v[122:125]
	v_mfma_f32_16x16x32_bf16 v[110:113], v[130:133], v[194:197], v[110:113]
	v_mfma_f32_16x16x32_bf16 v[110:113], v[134:137], v[198:201], v[110:113]
	v_mfma_f32_16x16x32_bf16 v[106:109], v[138:141], v[194:197], v[106:109]
	v_mfma_f32_16x16x32_bf16 v[106:109], v[142:145], v[198:201], v[106:109]
	v_mfma_f32_16x16x32_bf16 v[94:97], v[130:133], v[202:205], v[94:97]
	v_mfma_f32_16x16x32_bf16 v[94:97], v[134:137], v[206:209], v[94:97]
	v_mfma_f32_16x16x32_bf16 v[90:93], v[138:141], v[202:205], v[90:93]
	v_mfma_f32_16x16x32_bf16 v[90:93], v[142:145], v[206:209], v[90:93]
	v_mfma_f32_16x16x32_bf16 v[78:81], v[130:133], v[210:213], v[78:81]
	v_mfma_f32_16x16x32_bf16 v[78:81], v[134:137], v[214:217], v[78:81]
	v_mfma_f32_16x16x32_bf16 v[74:77], v[138:141], v[210:213], v[74:77]
	v_mfma_f32_16x16x32_bf16 v[74:77], v[142:145], v[214:217], v[74:77]
	s_setprio 0
	s_setprio 1
	v_mfma_f32_16x16x32_bf16 v[118:121], v[146:149], v[178:181], v[118:121]
	v_mfma_f32_16x16x32_bf16 v[118:121], v[150:153], v[190:193], v[118:121]
	v_mfma_f32_16x16x32_bf16 v[114:117], v[170:173], v[178:181], v[114:117]
	v_mfma_f32_16x16x32_bf16 v[114:117], v[174:177], v[190:193], v[114:117]
	v_mfma_f32_16x16x32_bf16 v[102:105], v[146:149], v[194:197], v[102:105]
	v_mfma_f32_16x16x32_bf16 v[102:105], v[150:153], v[198:201], v[102:105]
	v_mfma_f32_16x16x32_bf16 v[98:101], v[170:173], v[194:197], v[98:101]
	v_mfma_f32_16x16x32_bf16 v[98:101], v[174:177], v[198:201], v[98:101]
	v_mfma_f32_16x16x32_bf16 v[86:89], v[146:149], v[202:205], v[86:89]
	v_mfma_f32_16x16x32_bf16 v[86:89], v[150:153], v[206:209], v[86:89]
	v_mfma_f32_16x16x32_bf16 v[82:85], v[170:173], v[202:205], v[82:85]
	v_mfma_f32_16x16x32_bf16 v[82:85], v[174:177], v[206:209], v[82:85]
	v_mfma_f32_16x16x32_bf16 v[70:73], v[146:149], v[210:213], v[70:73]
	v_mfma_f32_16x16x32_bf16 v[70:73], v[150:153], v[214:217], v[70:73]
	v_mfma_f32_16x16x32_bf16 v[66:69], v[170:173], v[210:213], v[66:69]
	v_mfma_f32_16x16x32_bf16 v[66:69], v[174:177], v[214:217], v[66:69]
	s_setprio 0
	s_barrier
	s_add_i32 s0, s54, s45
	v_lshl_add_u64 v[218:219], s[2:3], 0, v[156:157]
	s_mov_b32 m0, s0
	ds_read_b128 v[178:181], v188 offset:16384
	ds_read_b128 v[190:193], v188 offset:17408
	ds_read_b128 v[194:197], v188 offset:18432
	ds_read_b128 v[198:201], v188 offset:19456
	ds_read_b128 v[202:205], v188 offset:20480
	ds_read_b128 v[206:209], v188 offset:21504
	ds_read_b128 v[210:213], v188 offset:22528
	ds_read_b128 v[214:217], v188 offset:23552
	global_load_lds_dwordx4 v[218:219], off
	s_add_i32 m0, s0, 0x2000
	s_add_u32 s0, s2, 0x80000
	v_lshl_add_u64 v[220:221], s[2:3], 0, v[160:161]
	s_addc_u32 s1, s3, 0
	s_add_i32 s60, s55, s45
	global_load_lds_dwordx4 v[220:221], off
	v_lshl_add_u64 v[222:223], s[0:1], 0, v[156:157]
	s_mov_b32 m0, s60
	v_lshl_add_u64 v[224:225], s[40:41], 0, v[158:159]
	global_load_lds_dwordx4 v[222:223], off
	v_lshl_add_u64 v[222:223], s[0:1], 0, v[160:161]
	s_add_i32 m0, s60, 0x2000
	s_nop 0
	global_load_lds_dwordx4 v[222:223], off
	v_lshl_add_u64 v[222:223], s[40:41], 0, v[154:155]
	s_mov_b32 m0, s37
	s_nop 0
	global_load_lds_dwordx4 v[222:223], off
	s_mov_b32 m0, s46
	s_nop 0
	global_load_lds_dwordx4 v[224:225], off
	s_waitcnt vmcnt(8)
	s_waitcnt lgkmcnt(0)
	s_barrier
	s_setprio 1
	s_waitcnt lgkmcnt(0)
	v_mfma_f32_16x16x32_bf16 v[62:65], v[130:133], v[178:181], v[62:65]
	v_mfma_f32_16x16x32_bf16 v[62:65], v[134:137], v[190:193], v[62:65]
	v_mfma_f32_16x16x32_bf16 v[58:61], v[138:141], v[178:181], v[58:61]
	v_mfma_f32_16x16x32_bf16 v[58:61], v[142:145], v[190:193], v[58:61]
	v_mfma_f32_16x16x32_bf16 v[46:49], v[130:133], v[194:197], v[46:49]
	v_mfma_f32_16x16x32_bf16 v[46:49], v[134:137], v[198:201], v[46:49]
	v_mfma_f32_16x16x32_bf16 v[42:45], v[138:141], v[194:197], v[42:45]
	v_mfma_f32_16x16x32_bf16 v[42:45], v[142:145], v[198:201], v[42:45]
	v_mfma_f32_16x16x32_bf16 v[30:33], v[130:133], v[202:205], v[30:33]
	v_mfma_f32_16x16x32_bf16 v[30:33], v[134:137], v[206:209], v[30:33]
	v_mfma_f32_16x16x32_bf16 v[26:29], v[138:141], v[202:205], v[26:29]
	v_mfma_f32_16x16x32_bf16 v[26:29], v[142:145], v[206:209], v[26:29]
	v_mfma_f32_16x16x32_bf16 v[14:17], v[130:133], v[210:213], v[14:17]
	v_mfma_f32_16x16x32_bf16 v[14:17], v[134:137], v[214:217], v[14:17]
	v_mfma_f32_16x16x32_bf16 v[10:13], v[138:141], v[210:213], v[10:13]
	v_mfma_f32_16x16x32_bf16 v[10:13], v[142:145], v[214:217], v[10:13]
	s_setprio 0
	s_setprio 1
	v_mfma_f32_16x16x32_bf16 v[54:57], v[146:149], v[178:181], v[54:57]
	v_mfma_f32_16x16x32_bf16 v[54:57], v[150:153], v[190:193], v[54:57]
	v_mfma_f32_16x16x32_bf16 v[50:53], v[170:173], v[178:181], v[50:53]
	v_mfma_f32_16x16x32_bf16 v[50:53], v[174:177], v[190:193], v[50:53]
	v_mfma_f32_16x16x32_bf16 v[38:41], v[146:149], v[194:197], v[38:41]
	v_mfma_f32_16x16x32_bf16 v[38:41], v[150:153], v[198:201], v[38:41]
	v_mfma_f32_16x16x32_bf16 v[34:37], v[170:173], v[194:197], v[34:37]
	v_mfma_f32_16x16x32_bf16 v[34:37], v[174:177], v[198:201], v[34:37]
	v_mfma_f32_16x16x32_bf16 v[22:25], v[146:149], v[202:205], v[22:25]
	v_mfma_f32_16x16x32_bf16 v[22:25], v[150:153], v[206:209], v[22:25]
	v_mfma_f32_16x16x32_bf16 v[18:21], v[170:173], v[202:205], v[18:21]
	v_mfma_f32_16x16x32_bf16 v[18:21], v[174:177], v[206:209], v[18:21]
	v_mfma_f32_16x16x32_bf16 v[6:9], v[146:149], v[210:213], v[6:9]
	v_mfma_f32_16x16x32_bf16 v[6:9], v[150:153], v[214:217], v[6:9]
	v_mfma_f32_16x16x32_bf16 v[2:5], v[170:173], v[210:213], v[2:5]
	v_mfma_f32_16x16x32_bf16 v[2:5], v[174:177], v[214:217], v[2:5]
	s_setprio 0
	s_barrier
	s_add_i32 s60, 0, 0x18000
	s_add_i32 s61, 0, 0x1c000
	v_add_u32_e32 v142, s60, v182
	v_add_u32_e32 v174, s61, v182
	ds_read_b128 v[130:133], v142
	ds_read_b128 v[134:137], v142 offset:1024
	ds_read_b128 v[138:141], v142 offset:2048
	ds_read_b128 v[142:145], v142 offset:3072
	ds_read_b128 v[146:149], v174
	ds_read_b128 v[150:153], v174 offset:1024
	ds_read_b128 v[170:173], v174 offset:2048
	ds_read_b128 v[174:177], v174 offset:3072
	s_add_u32 s0, s40, 0x80000
	s_addc_u32 s1, s41, 0
	s_mov_b32 m0, s47
	v_lshl_add_u64 v[226:227], s[0:1], 0, v[154:155]
	ds_read_b128 v[178:181], v188 offset:32768
	ds_read_b128 v[190:193], v188 offset:33792
	ds_read_b128 v[194:197], v188 offset:34816
	ds_read_b128 v[198:201], v188 offset:35840
	ds_read_b128 v[202:205], v188 offset:36864
	ds_read_b128 v[206:209], v188 offset:37888
	ds_read_b128 v[210:213], v188 offset:38912
	ds_read_b128 v[214:217], v188 offset:39936
	global_load_lds_dwordx4 v[226:227], off
	v_lshl_add_u64 v[226:227], s[0:1], 0, v[158:159]
	s_mov_b32 m0, s48
	s_nop 0
	global_load_lds_dwordx4 v[226:227], off
	s_waitcnt vmcnt(8)
	s_waitcnt lgkmcnt(0)
	s_barrier
	s_setprio 1
	s_waitcnt lgkmcnt(0)
	v_mfma_f32_16x16x32_bf16 v[126:129], v[130:133], v[178:181], v[126:129]
	v_mfma_f32_16x16x32_bf16 v[126:129], v[134:137], v[190:193], v[126:129]
	v_mfma_f32_16x16x32_bf16 v[122:125], v[138:141], v[178:181], v[122:125]
	v_mfma_f32_16x16x32_bf16 v[122:125], v[142:145], v[190:193], v[122:125]
	v_mfma_f32_16x16x32_bf16 v[110:113], v[130:133], v[194:197], v[110:113]
	v_mfma_f32_16x16x32_bf16 v[110:113], v[134:137], v[198:201], v[110:113]
	v_mfma_f32_16x16x32_bf16 v[106:109], v[138:141], v[194:197], v[106:109]
	v_mfma_f32_16x16x32_bf16 v[106:109], v[142:145], v[198:201], v[106:109]
	v_mfma_f32_16x16x32_bf16 v[94:97], v[130:133], v[202:205], v[94:97]
	v_mfma_f32_16x16x32_bf16 v[94:97], v[134:137], v[206:209], v[94:97]
	v_mfma_f32_16x16x32_bf16 v[90:93], v[138:141], v[202:205], v[90:93]
	v_mfma_f32_16x16x32_bf16 v[90:93], v[142:145], v[206:209], v[90:93]
	v_mfma_f32_16x16x32_bf16 v[78:81], v[130:133], v[210:213], v[78:81]
	v_mfma_f32_16x16x32_bf16 v[78:81], v[134:137], v[214:217], v[78:81]
	v_mfma_f32_16x16x32_bf16 v[74:77], v[138:141], v[210:213], v[74:77]
	v_mfma_f32_16x16x32_bf16 v[74:77], v[142:145], v[214:217], v[74:77]
	s_setprio 0
	s_setprio 1
	v_mfma_f32_16x16x32_bf16 v[118:121], v[146:149], v[178:181], v[118:121]
	v_mfma_f32_16x16x32_bf16 v[118:121], v[150:153], v[190:193], v[118:121]
	v_mfma_f32_16x16x32_bf16 v[114:117], v[170:173], v[178:181], v[114:117]
	v_mfma_f32_16x16x32_bf16 v[114:117], v[174:177], v[190:193], v[114:117]
	v_mfma_f32_16x16x32_bf16 v[102:105], v[146:149], v[194:197], v[102:105]
	v_mfma_f32_16x16x32_bf16 v[102:105], v[150:153], v[198:201], v[102:105]
	v_mfma_f32_16x16x32_bf16 v[98:101], v[170:173], v[194:197], v[98:101]
	v_mfma_f32_16x16x32_bf16 v[98:101], v[174:177], v[198:201], v[98:101]
	v_mfma_f32_16x16x32_bf16 v[86:89], v[146:149], v[202:205], v[86:89]
	v_mfma_f32_16x16x32_bf16 v[86:89], v[150:153], v[206:209], v[86:89]
	v_mfma_f32_16x16x32_bf16 v[82:85], v[170:173], v[202:205], v[82:85]
	v_mfma_f32_16x16x32_bf16 v[82:85], v[174:177], v[206:209], v[82:85]
	v_mfma_f32_16x16x32_bf16 v[70:73], v[146:149], v[210:213], v[70:73]
	v_mfma_f32_16x16x32_bf16 v[70:73], v[150:153], v[214:217], v[70:73]
	v_mfma_f32_16x16x32_bf16 v[66:69], v[170:173], v[210:213], v[66:69]
	v_mfma_f32_16x16x32_bf16 v[66:69], v[174:177], v[214:217], v[66:69]
	s_setprio 0
	s_barrier
	s_add_i32 s0, s60, s45
	v_lshl_add_u64 v[218:219], v[218:219], 0, s[14:15]
	s_mov_b32 m0, s0
	ds_read_b128 v[178:181], v188 offset:49152
	ds_read_b128 v[190:193], v188 offset:50176
	ds_read_b128 v[194:197], v188 offset:51200
	ds_read_b128 v[198:201], v188 offset:52224
	ds_read_b128 v[202:205], v188 offset:53248
	ds_read_b128 v[206:209], v188 offset:54272
	ds_read_b128 v[210:213], v188 offset:55296
	ds_read_b128 v[214:217], v188 offset:56320
	global_load_lds_dwordx4 v[218:219], off
	s_add_i32 m0, s0, 0x2000
	s_add_u32 s0, s2, 0x80080
	v_lshl_add_u64 v[218:219], v[220:221], 0, s[14:15]
	s_addc_u32 s1, s3, 0
	s_add_i32 s2, s61, s45
	global_load_lds_dwordx4 v[218:219], off
	v_lshl_add_u64 v[218:219], s[0:1], 0, v[156:157]
	s_mov_b32 m0, s2
	s_nop 0
	global_load_lds_dwordx4 v[218:219], off
	v_lshl_add_u64 v[218:219], s[0:1], 0, v[160:161]
	s_add_i32 m0, s2, 0x2000
	s_nop 0
	global_load_lds_dwordx4 v[218:219], off
	v_lshl_add_u64 v[218:219], v[222:223], 0, s[14:15]
	s_mov_b32 m0, s50
	s_nop 0
	global_load_lds_dwordx4 v[218:219], off
	v_lshl_add_u64 v[218:219], v[224:225], 0, s[14:15]
	s_mov_b32 m0, s51
	s_nop 0
	global_load_lds_dwordx4 v[218:219], off
	s_waitcnt vmcnt(8)
	s_waitcnt lgkmcnt(0)
	s_barrier
	s_setprio 1
	s_waitcnt lgkmcnt(0)
	v_mfma_f32_16x16x32_bf16 v[62:65], v[130:133], v[178:181], v[62:65]
	v_mfma_f32_16x16x32_bf16 v[62:65], v[134:137], v[190:193], v[62:65]
	v_mfma_f32_16x16x32_bf16 v[58:61], v[138:141], v[178:181], v[58:61]
	v_mfma_f32_16x16x32_bf16 v[58:61], v[142:145], v[190:193], v[58:61]
	v_mfma_f32_16x16x32_bf16 v[46:49], v[130:133], v[194:197], v[46:49]
	v_mfma_f32_16x16x32_bf16 v[46:49], v[134:137], v[198:201], v[46:49]
	v_mfma_f32_16x16x32_bf16 v[42:45], v[138:141], v[194:197], v[42:45]
	v_mfma_f32_16x16x32_bf16 v[42:45], v[142:145], v[198:201], v[42:45]
	v_mfma_f32_16x16x32_bf16 v[30:33], v[130:133], v[202:205], v[30:33]
	v_mfma_f32_16x16x32_bf16 v[30:33], v[134:137], v[206:209], v[30:33]
	v_mfma_f32_16x16x32_bf16 v[26:29], v[138:141], v[202:205], v[26:29]
	v_mfma_f32_16x16x32_bf16 v[26:29], v[142:145], v[206:209], v[26:29]
	v_mfma_f32_16x16x32_bf16 v[14:17], v[130:133], v[210:213], v[14:17]
	v_mfma_f32_16x16x32_bf16 v[14:17], v[134:137], v[214:217], v[14:17]
	v_mfma_f32_16x16x32_bf16 v[10:13], v[138:141], v[210:213], v[10:13]
	v_mfma_f32_16x16x32_bf16 v[10:13], v[142:145], v[214:217], v[10:13]
	s_setprio 0
	s_setprio 1
	v_mfma_f32_16x16x32_bf16 v[54:57], v[146:149], v[178:181], v[54:57]
	v_mfma_f32_16x16x32_bf16 v[54:57], v[150:153], v[190:193], v[54:57]
	v_mfma_f32_16x16x32_bf16 v[50:53], v[170:173], v[178:181], v[50:53]
	v_mfma_f32_16x16x32_bf16 v[50:53], v[174:177], v[190:193], v[50:53]
	v_mfma_f32_16x16x32_bf16 v[38:41], v[146:149], v[194:197], v[38:41]
	v_mfma_f32_16x16x32_bf16 v[38:41], v[150:153], v[198:201], v[38:41]
	v_mfma_f32_16x16x32_bf16 v[34:37], v[170:173], v[194:197], v[34:37]
	v_mfma_f32_16x16x32_bf16 v[34:37], v[174:177], v[198:201], v[34:37]
	v_mfma_f32_16x16x32_bf16 v[22:25], v[146:149], v[202:205], v[22:25]
	v_mfma_f32_16x16x32_bf16 v[22:25], v[150:153], v[206:209], v[22:25]
	v_mfma_f32_16x16x32_bf16 v[18:21], v[170:173], v[202:205], v[18:21]
	v_mfma_f32_16x16x32_bf16 v[18:21], v[174:177], v[206:209], v[18:21]
	v_mfma_f32_16x16x32_bf16 v[6:9], v[146:149], v[210:213], v[6:9]
	v_mfma_f32_16x16x32_bf16 v[6:9], v[150:153], v[214:217], v[6:9]
	v_mfma_f32_16x16x32_bf16 v[2:5], v[170:173], v[210:213], v[2:5]
	v_mfma_f32_16x16x32_bf16 v[2:5], v[174:177], v[214:217], v[2:5]
	s_setprio 0
	s_barrier
	s_add_i32 s59, s59, 2
	s_add_u32 s38, s38, 0x100
	s_addc_u32 s39, s39, 0
	s_add_u32 s57, s57, 0x100
	s_addc_u32 s58, s58, 0
	s_cmp_gt_u32 s59, 29
	s_cbranch_scc0 .LBB0_1626
	s_and_b64 vcc, exec, s[16:17]
	s_cbranch_vccz .LBB0_1629
	s_barrier

.LBB0_1715:
	ds_read_b128 v[148:151], v166
	ds_read_b128 v[152:155], v166 offset:1024
	ds_read_b128 v[156:159], v166 offset:2048
	ds_read_b128 v[160:163], v166 offset:3072
	ds_read_b128 v[170:173], v167
	ds_read_b128 v[174:177], v167 offset:1024
	ds_read_b128 v[178:181], v167 offset:2048
	ds_read_b128 v[182:185], v167 offset:3072
	s_add_u32 s0, s28, 0xfffc0080
	s_addc_u32 s1, s29, -1
	s_cmp_eq_u32 s53, 12
	s_cselect_b32 s31, s21, s1
	s_cselect_b32 s30, s49, s0
	s_cselect_b32 s3, s19, s52
	s_cselect_b32 s2, s50, s51
	v_lshl_add_u64 v[218:219], s[28:29], 0, v[140:141]
	s_add_i32 m0, s27, 0xc000
	ds_read_b128 v[186:189], v168
	ds_read_b128 v[190:193], v168 offset:1024
	ds_read_b128 v[194:197], v168 offset:2048
	ds_read_b128 v[198:201], v168 offset:3072
	ds_read_b128 v[202:205], v168 offset:4096
	ds_read_b128 v[206:209], v168 offset:5120
	ds_read_b128 v[210:213], v168 offset:6144
	ds_read_b128 v[214:217], v168 offset:7168
	global_load_lds_dwordx4 v[218:219], off
	v_lshl_add_u64 v[218:219], s[28:29], 0, v[142:143]
	s_add_i32 m0, s27, 0xe000
	s_nop 0
	global_load_lds_dwordx4 v[218:219], off
	s_waitcnt vmcnt(8)
	s_waitcnt lgkmcnt(0)
	s_barrier
	s_setprio 1
	s_waitcnt lgkmcnt(0)
	v_mfma_f32_16x16x32_bf16 v[126:129], v[148:151], v[186:189], v[126:129]
	v_mfma_f32_16x16x32_bf16 v[126:129], v[152:155], v[190:193], v[126:129]
	v_mfma_f32_16x16x32_bf16 v[118:121], v[156:159], v[186:189], v[118:121]
	v_mfma_f32_16x16x32_bf16 v[118:121], v[160:163], v[190:193], v[118:121]
	v_mfma_f32_16x16x32_bf16 v[110:113], v[148:151], v[194:197], v[110:113]
	v_mfma_f32_16x16x32_bf16 v[110:113], v[152:155], v[198:201], v[110:113]
	v_mfma_f32_16x16x32_bf16 v[102:105], v[156:159], v[194:197], v[102:105]
	v_mfma_f32_16x16x32_bf16 v[102:105], v[160:163], v[198:201], v[102:105]
	v_mfma_f32_16x16x32_bf16 v[94:97], v[148:151], v[202:205], v[94:97]
	v_mfma_f32_16x16x32_bf16 v[94:97], v[152:155], v[206:209], v[94:97]
	v_mfma_f32_16x16x32_bf16 v[86:89], v[156:159], v[202:205], v[86:89]
	v_mfma_f32_16x16x32_bf16 v[86:89], v[160:163], v[206:209], v[86:89]
	v_mfma_f32_16x16x32_bf16 v[78:81], v[148:151], v[210:213], v[78:81]
	v_mfma_f32_16x16x32_bf16 v[78:81], v[152:155], v[214:217], v[78:81]
	v_mfma_f32_16x16x32_bf16 v[70:73], v[156:159], v[210:213], v[70:73]
	v_mfma_f32_16x16x32_bf16 v[70:73], v[160:163], v[214:217], v[70:73]
	s_setprio 0
	s_setprio 1
	v_mfma_f32_16x16x32_bf16 v[122:125], v[170:173], v[186:189], v[122:125]
	v_mfma_f32_16x16x32_bf16 v[122:125], v[174:177], v[190:193], v[122:125]
	v_mfma_f32_16x16x32_bf16 v[114:117], v[178:181], v[186:189], v[114:117]
	v_mfma_f32_16x16x32_bf16 v[114:117], v[182:185], v[190:193], v[114:117]
	v_mfma_f32_16x16x32_bf16 v[106:109], v[170:173], v[194:197], v[106:109]
	v_mfma_f32_16x16x32_bf16 v[106:109], v[174:177], v[198:201], v[106:109]
	v_mfma_f32_16x16x32_bf16 v[98:101], v[178:181], v[194:197], v[98:101]
	v_mfma_f32_16x16x32_bf16 v[98:101], v[182:185], v[198:201], v[98:101]
	v_mfma_f32_16x16x32_bf16 v[90:93], v[170:173], v[202:205], v[90:93]
	v_mfma_f32_16x16x32_bf16 v[90:93], v[174:177], v[206:209], v[90:93]
	v_mfma_f32_16x16x32_bf16 v[82:85], v[178:181], v[202:205], v[82:85]
	v_mfma_f32_16x16x32_bf16 v[82:85], v[182:185], v[206:209], v[82:85]
	v_mfma_f32_16x16x32_bf16 v[74:77], v[170:173], v[210:213], v[74:77]
	v_mfma_f32_16x16x32_bf16 v[74:77], v[174:177], v[214:217], v[74:77]
	v_mfma_f32_16x16x32_bf16 v[66:69], v[178:181], v[210:213], v[66:69]
	v_mfma_f32_16x16x32_bf16 v[66:69], v[182:185], v[214:217], v[66:69]
	s_setprio 0
	s_barrier
	s_add_i32 s0, s44, s35
	v_lshl_add_u64 v[218:219], s[2:3], 0, v[134:135]
	s_mov_b32 m0, s0
	ds_read_b128 v[186:189], v168 offset:16384
	ds_read_b128 v[190:193], v168 offset:17408
	ds_read_b128 v[194:197], v168 offset:18432
	ds_read_b128 v[198:201], v168 offset:19456
	ds_read_b128 v[202:205], v168 offset:20480
	ds_read_b128 v[206:209], v168 offset:21504
	ds_read_b128 v[210:213], v168 offset:22528
	ds_read_b128 v[214:217], v168 offset:23552
	global_load_lds_dwordx4 v[218:219], off
	s_add_i32 m0, s0, 0x2000
	s_add_u32 s0, s2, 0x40000
	v_lshl_add_u64 v[220:221], s[2:3], 0, v[130:131]
	s_addc_u32 s1, s3, 0
	s_add_i32 s54, s45, s35
	global_load_lds_dwordx4 v[220:221], off
	v_lshl_add_u64 v[222:223], s[0:1], 0, v[134:135]
	s_mov_b32 m0, s54
	v_lshl_add_u64 v[224:225], s[30:31], 0, v[132:133]
	global_load_lds_dwordx4 v[222:223], off
	v_lshl_add_u64 v[222:223], s[0:1], 0, v[130:131]
	s_add_i32 m0, s54, 0x2000
	s_nop 0
	global_load_lds_dwordx4 v[222:223], off
	v_lshl_add_u64 v[222:223], s[30:31], 0, v[136:137]
	s_mov_b32 m0, s27
	s_nop 0
	global_load_lds_dwordx4 v[222:223], off
	s_mov_b32 m0, s38
	s_nop 0
	global_load_lds_dwordx4 v[224:225], off
	s_waitcnt vmcnt(8)
	s_waitcnt lgkmcnt(0)
	s_barrier
	s_setprio 1
	s_waitcnt lgkmcnt(0)
	v_mfma_f32_16x16x32_bf16 v[62:65], v[148:151], v[186:189], v[62:65]
	v_mfma_f32_16x16x32_bf16 v[62:65], v[152:155], v[190:193], v[62:65]
	v_mfma_f32_16x16x32_bf16 v[54:57], v[156:159], v[186:189], v[54:57]
	v_mfma_f32_16x16x32_bf16 v[54:57], v[160:163], v[190:193], v[54:57]
	v_mfma_f32_16x16x32_bf16 v[46:49], v[148:151], v[194:197], v[46:49]
	v_mfma_f32_16x16x32_bf16 v[46:49], v[152:155], v[198:201], v[46:49]
	v_mfma_f32_16x16x32_bf16 v[38:41], v[156:159], v[194:197], v[38:41]
	v_mfma_f32_16x16x32_bf16 v[38:41], v[160:163], v[198:201], v[38:41]
	v_mfma_f32_16x16x32_bf16 v[30:33], v[148:151], v[202:205], v[30:33]
	v_mfma_f32_16x16x32_bf16 v[30:33], v[152:155], v[206:209], v[30:33]
	v_mfma_f32_16x16x32_bf16 v[22:25], v[156:159], v[202:205], v[22:25]
	v_mfma_f32_16x16x32_bf16 v[22:25], v[160:163], v[206:209], v[22:25]
	v_mfma_f32_16x16x32_bf16 v[14:17], v[148:151], v[210:213], v[14:17]
	v_mfma_f32_16x16x32_bf16 v[14:17], v[152:155], v[214:217], v[14:17]
	v_mfma_f32_16x16x32_bf16 v[6:9], v[156:159], v[210:213], v[6:9]
	v_mfma_f32_16x16x32_bf16 v[6:9], v[160:163], v[214:217], v[6:9]
	s_setprio 0
	s_setprio 1
	v_mfma_f32_16x16x32_bf16 v[58:61], v[170:173], v[186:189], v[58:61]
	v_mfma_f32_16x16x32_bf16 v[58:61], v[174:177], v[190:193], v[58:61]
	v_mfma_f32_16x16x32_bf16 v[50:53], v[178:181], v[186:189], v[50:53]
	v_mfma_f32_16x16x32_bf16 v[50:53], v[182:185], v[190:193], v[50:53]
	v_mfma_f32_16x16x32_bf16 v[42:45], v[170:173], v[194:197], v[42:45]
	v_mfma_f32_16x16x32_bf16 v[42:45], v[174:177], v[198:201], v[42:45]
	v_mfma_f32_16x16x32_bf16 v[34:37], v[178:181], v[194:197], v[34:37]
	v_mfma_f32_16x16x32_bf16 v[34:37], v[182:185], v[198:201], v[34:37]
	v_mfma_f32_16x16x32_bf16 v[26:29], v[170:173], v[202:205], v[26:29]
	v_mfma_f32_16x16x32_bf16 v[26:29], v[174:177], v[206:209], v[26:29]
	v_mfma_f32_16x16x32_bf16 v[18:21], v[178:181], v[202:205], v[18:21]
	v_mfma_f32_16x16x32_bf16 v[18:21], v[182:185], v[206:209], v[18:21]
	v_mfma_f32_16x16x32_bf16 v[10:13], v[170:173], v[210:213], v[10:13]
	v_mfma_f32_16x16x32_bf16 v[10:13], v[174:177], v[214:217], v[10:13]
	v_mfma_f32_16x16x32_bf16 v[2:5], v[178:181], v[210:213], v[2:5]
	v_mfma_f32_16x16x32_bf16 v[2:5], v[182:185], v[214:217], v[2:5]
	s_setprio 0
	s_barrier
	s_add_i32 s54, 0, 0x18000
	s_add_i32 s55, 0, 0x1c000
	v_add_u32_e32 v160, s54, v165
	v_add_u32_e32 v182, s55, v165
	ds_read_b128 v[148:151], v160
	ds_read_b128 v[152:155], v160 offset:1024
	ds_read_b128 v[156:159], v160 offset:2048
	ds_read_b128 v[160:163], v160 offset:3072
	ds_read_b128 v[170:173], v182
	ds_read_b128 v[174:177], v182 offset:1024
	ds_read_b128 v[178:181], v182 offset:2048
	ds_read_b128 v[182:185], v182 offset:3072
	s_add_u32 s0, s30, 0x40000
	s_addc_u32 s1, s31, 0
	s_mov_b32 m0, s39
	v_lshl_add_u64 v[226:227], s[0:1], 0, v[136:137]
	ds_read_b128 v[186:189], v168 offset:32768
	ds_read_b128 v[190:193], v168 offset:33792
	ds_read_b128 v[194:197], v168 offset:34816
	ds_read_b128 v[198:201], v168 offset:35840
	ds_read_b128 v[202:205], v168 offset:36864
	ds_read_b128 v[206:209], v168 offset:37888
	ds_read_b128 v[210:213], v168 offset:38912
	ds_read_b128 v[214:217], v168 offset:39936
	global_load_lds_dwordx4 v[226:227], off
	v_lshl_add_u64 v[226:227], s[0:1], 0, v[132:133]
	s_mov_b32 m0, s40
	s_nop 0
	global_load_lds_dwordx4 v[226:227], off
	s_waitcnt vmcnt(8)
	s_waitcnt lgkmcnt(0)
	s_barrier
	s_setprio 1
	s_waitcnt lgkmcnt(0)
	v_mfma_f32_16x16x32_bf16 v[126:129], v[148:151], v[186:189], v[126:129]
	v_mfma_f32_16x16x32_bf16 v[126:129], v[152:155], v[190:193], v[126:129]
	v_mfma_f32_16x16x32_bf16 v[118:121], v[156:159], v[186:189], v[118:121]
	v_mfma_f32_16x16x32_bf16 v[118:121], v[160:163], v[190:193], v[118:121]
	v_mfma_f32_16x16x32_bf16 v[110:113], v[148:151], v[194:197], v[110:113]
	v_mfma_f32_16x16x32_bf16 v[110:113], v[152:155], v[198:201], v[110:113]
	v_mfma_f32_16x16x32_bf16 v[102:105], v[156:159], v[194:197], v[102:105]
	v_mfma_f32_16x16x32_bf16 v[102:105], v[160:163], v[198:201], v[102:105]
	v_mfma_f32_16x16x32_bf16 v[94:97], v[148:151], v[202:205], v[94:97]
	v_mfma_f32_16x16x32_bf16 v[94:97], v[152:155], v[206:209], v[94:97]
	v_mfma_f32_16x16x32_bf16 v[86:89], v[156:159], v[202:205], v[86:89]
	v_mfma_f32_16x16x32_bf16 v[86:89], v[160:163], v[206:209], v[86:89]
	v_mfma_f32_16x16x32_bf16 v[78:81], v[148:151], v[210:213], v[78:81]
	v_mfma_f32_16x16x32_bf16 v[78:81], v[152:155], v[214:217], v[78:81]
	v_mfma_f32_16x16x32_bf16 v[70:73], v[156:159], v[210:213], v[70:73]
	v_mfma_f32_16x16x32_bf16 v[70:73], v[160:163], v[214:217], v[70:73]
	s_setprio 0
	s_setprio 1
	v_mfma_f32_16x16x32_bf16 v[122:125], v[170:173], v[186:189], v[122:125]
	v_mfma_f32_16x16x32_bf16 v[122:125], v[174:177], v[190:193], v[122:125]
	v_mfma_f32_16x16x32_bf16 v[114:117], v[178:181], v[186:189], v[114:117]
	v_mfma_f32_16x16x32_bf16 v[114:117], v[182:185], v[190:193], v[114:117]
	v_mfma_f32_16x16x32_bf16 v[106:109], v[170:173], v[194:197], v[106:109]
	v_mfma_f32_16x16x32_bf16 v[106:109], v[174:177], v[198:201], v[106:109]
	v_mfma_f32_16x16x32_bf16 v[98:101], v[178:181], v[194:197], v[98:101]
	v_mfma_f32_16x16x32_bf16 v[98:101], v[182:185], v[198:201], v[98:101]
	v_mfma_f32_16x16x32_bf16 v[90:93], v[170:173], v[202:205], v[90:93]
	v_mfma_f32_16x16x32_bf16 v[90:93], v[174:177], v[206:209], v[90:93]
	v_mfma_f32_16x16x32_bf16 v[82:85], v[178:181], v[202:205], v[82:85]
	v_mfma_f32_16x16x32_bf16 v[82:85], v[182:185], v[206:209], v[82:85]
	v_mfma_f32_16x16x32_bf16 v[74:77], v[170:173], v[210:213], v[74:77]
	v_mfma_f32_16x16x32_bf16 v[74:77], v[174:177], v[214:217], v[74:77]
	v_mfma_f32_16x16x32_bf16 v[66:69], v[178:181], v[210:213], v[66:69]
	v_mfma_f32_16x16x32_bf16 v[66:69], v[182:185], v[214:217], v[66:69]
	s_setprio 0
	s_barrier
	s_add_i32 s0, s54, s35
	v_lshl_add_u64 v[218:219], v[218:219], 0, s[14:15]
	s_mov_b32 m0, s0
	ds_read_b128 v[186:189], v168 offset:49152
	ds_read_b128 v[190:193], v168 offset:50176
	ds_read_b128 v[194:197], v168 offset:51200
	ds_read_b128 v[198:201], v168 offset:52224
	ds_read_b128 v[202:205], v168 offset:53248
	ds_read_b128 v[206:209], v168 offset:54272
	ds_read_b128 v[210:213], v168 offset:55296
	ds_read_b128 v[214:217], v168 offset:56320
	global_load_lds_dwordx4 v[218:219], off
	s_add_i32 m0, s0, 0x2000
	s_add_u32 s0, s2, 0x40080
	v_lshl_add_u64 v[218:219], v[220:221], 0, s[14:15]
	s_addc_u32 s1, s3, 0
	s_add_i32 s2, s55, s35
	global_load_lds_dwordx4 v[218:219], off
	v_lshl_add_u64 v[218:219], s[0:1], 0, v[134:135]
	s_mov_b32 m0, s2
	s_nop 0
	global_load_lds_dwordx4 v[218:219], off
	v_lshl_add_u64 v[218:219], s[0:1], 0, v[130:131]
	s_add_i32 m0, s2, 0x2000
	s_nop 0
	global_load_lds_dwordx4 v[218:219], off
	v_lshl_add_u64 v[218:219], v[222:223], 0, s[14:15]
	s_mov_b32 m0, s41
	s_nop 0
	global_load_lds_dwordx4 v[218:219], off
	v_lshl_add_u64 v[218:219], v[224:225], 0, s[14:15]
	s_mov_b32 m0, s42
	s_nop 0
	global_load_lds_dwordx4 v[218:219], off
	s_waitcnt vmcnt(8)
	s_waitcnt lgkmcnt(0)
	s_barrier
	s_setprio 1
	s_waitcnt lgkmcnt(0)
	v_mfma_f32_16x16x32_bf16 v[62:65], v[148:151], v[186:189], v[62:65]
	v_mfma_f32_16x16x32_bf16 v[62:65], v[152:155], v[190:193], v[62:65]
	v_mfma_f32_16x16x32_bf16 v[54:57], v[156:159], v[186:189], v[54:57]
	v_mfma_f32_16x16x32_bf16 v[54:57], v[160:163], v[190:193], v[54:57]
	v_mfma_f32_16x16x32_bf16 v[46:49], v[148:151], v[194:197], v[46:49]
	v_mfma_f32_16x16x32_bf16 v[46:49], v[152:155], v[198:201], v[46:49]
	v_mfma_f32_16x16x32_bf16 v[38:41], v[156:159], v[194:197], v[38:41]
	v_mfma_f32_16x16x32_bf16 v[38:41], v[160:163], v[198:201], v[38:41]
	v_mfma_f32_16x16x32_bf16 v[30:33], v[148:151], v[202:205], v[30:33]
	v_mfma_f32_16x16x32_bf16 v[30:33], v[152:155], v[206:209], v[30:33]
	v_mfma_f32_16x16x32_bf16 v[22:25], v[156:159], v[202:205], v[22:25]
	v_mfma_f32_16x16x32_bf16 v[22:25], v[160:163], v[206:209], v[22:25]
	v_mfma_f32_16x16x32_bf16 v[14:17], v[148:151], v[210:213], v[14:17]
	v_mfma_f32_16x16x32_bf16 v[14:17], v[152:155], v[214:217], v[14:17]
	v_mfma_f32_16x16x32_bf16 v[6:9], v[156:159], v[210:213], v[6:9]
	v_mfma_f32_16x16x32_bf16 v[6:9], v[160:163], v[214:217], v[6:9]
	s_setprio 0
	s_setprio 1
	v_mfma_f32_16x16x32_bf16 v[58:61], v[170:173], v[186:189], v[58:61]
	v_mfma_f32_16x16x32_bf16 v[58:61], v[174:177], v[190:193], v[58:61]
	v_mfma_f32_16x16x32_bf16 v[50:53], v[178:181], v[186:189], v[50:53]
	v_mfma_f32_16x16x32_bf16 v[50:53], v[182:185], v[190:193], v[50:53]
	v_mfma_f32_16x16x32_bf16 v[42:45], v[170:173], v[194:197], v[42:45]
	v_mfma_f32_16x16x32_bf16 v[42:45], v[174:177], v[198:201], v[42:45]
	v_mfma_f32_16x16x32_bf16 v[34:37], v[178:181], v[194:197], v[34:37]
	v_mfma_f32_16x16x32_bf16 v[34:37], v[182:185], v[198:201], v[34:37]
	v_mfma_f32_16x16x32_bf16 v[26:29], v[170:173], v[202:205], v[26:29]
	v_mfma_f32_16x16x32_bf16 v[26:29], v[174:177], v[206:209], v[26:29]
	v_mfma_f32_16x16x32_bf16 v[18:21], v[178:181], v[202:205], v[18:21]
	v_mfma_f32_16x16x32_bf16 v[18:21], v[182:185], v[206:209], v[18:21]
	v_mfma_f32_16x16x32_bf16 v[10:13], v[170:173], v[210:213], v[10:13]
	v_mfma_f32_16x16x32_bf16 v[10:13], v[174:177], v[214:217], v[10:13]
	v_mfma_f32_16x16x32_bf16 v[2:5], v[178:181], v[210:213], v[2:5]
	v_mfma_f32_16x16x32_bf16 v[2:5], v[182:185], v[214:217], v[2:5]
	s_setprio 0
	s_barrier
	s_add_i32 s53, s53, 2
	s_add_u32 s28, s28, 0x100
	s_addc_u32 s29, s29, 0
	s_add_u32 s51, s51, 0x100
	s_addc_u32 s52, s52, 0
	s_cmp_gt_u32 s53, 13
	s_cbranch_scc0 .LBB0_1715
	s_and_b64 vcc, exec, s[16:17]
	s_cbranch_vccz .LBB0_1718
	s_barrier

.LBB0_1841:
	ds_read_b128 v[130:133], v186
	ds_read_b128 v[134:137], v186 offset:1024
	ds_read_b128 v[138:141], v186 offset:2048
	ds_read_b128 v[142:145], v186 offset:3072
	ds_read_b128 v[146:149], v187
	ds_read_b128 v[150:153], v187 offset:1024
	ds_read_b128 v[170:173], v187 offset:2048
	ds_read_b128 v[174:177], v187 offset:3072
	s_add_u32 s0, s30, 0xfff50080
	s_addc_u32 s1, s31, -1
	s_cmp_eq_u32 s55, 40
	s_cselect_b32 s35, s9, s1
	s_cselect_b32 s34, s8, s0
	s_cselect_b32 s3, s29, s54
	s_cselect_b32 s2, s28, s53
	v_lshl_add_u64 v[218:219], s[30:31], 0, v[162:163]
	s_add_i32 m0, s40, 0xc000
	ds_read_b128 v[178:181], v188
	ds_read_b128 v[190:193], v188 offset:1024
	ds_read_b128 v[194:197], v188 offset:2048
	ds_read_b128 v[198:201], v188 offset:3072
	ds_read_b128 v[202:205], v188 offset:4096
	ds_read_b128 v[206:209], v188 offset:5120
	ds_read_b128 v[210:213], v188 offset:6144
	ds_read_b128 v[214:217], v188 offset:7168
	global_load_lds_dwordx4 v[218:219], off
	v_lshl_add_u64 v[218:219], s[30:31], 0, v[164:165]
	s_add_i32 m0, s40, 0xe000
	s_nop 0
	global_load_lds_dwordx4 v[218:219], off
	s_waitcnt vmcnt(8)
	s_waitcnt lgkmcnt(0)
	s_barrier
	s_setprio 1
	s_waitcnt lgkmcnt(0)
	v_mfma_f32_16x16x32_bf16 v[126:129], v[130:133], v[178:181], v[126:129]
	v_mfma_f32_16x16x32_bf16 v[126:129], v[134:137], v[190:193], v[126:129]
	v_mfma_f32_16x16x32_bf16 v[122:125], v[138:141], v[178:181], v[122:125]
	v_mfma_f32_16x16x32_bf16 v[122:125], v[142:145], v[190:193], v[122:125]
	v_mfma_f32_16x16x32_bf16 v[110:113], v[130:133], v[194:197], v[110:113]
	v_mfma_f32_16x16x32_bf16 v[110:113], v[134:137], v[198:201], v[110:113]
	v_mfma_f32_16x16x32_bf16 v[106:109], v[138:141], v[194:197], v[106:109]
	v_mfma_f32_16x16x32_bf16 v[106:109], v[142:145], v[198:201], v[106:109]
	v_mfma_f32_16x16x32_bf16 v[94:97], v[130:133], v[202:205], v[94:97]
	v_mfma_f32_16x16x32_bf16 v[94:97], v[134:137], v[206:209], v[94:97]
	v_mfma_f32_16x16x32_bf16 v[90:93], v[138:141], v[202:205], v[90:93]
	v_mfma_f32_16x16x32_bf16 v[90:93], v[142:145], v[206:209], v[90:93]
	v_mfma_f32_16x16x32_bf16 v[78:81], v[130:133], v[210:213], v[78:81]
	v_mfma_f32_16x16x32_bf16 v[78:81], v[134:137], v[214:217], v[78:81]
	v_mfma_f32_16x16x32_bf16 v[74:77], v[138:141], v[210:213], v[74:77]
	v_mfma_f32_16x16x32_bf16 v[74:77], v[142:145], v[214:217], v[74:77]
	s_setprio 0
	s_setprio 1
	v_mfma_f32_16x16x32_bf16 v[118:121], v[146:149], v[178:181], v[118:121]
	v_mfma_f32_16x16x32_bf16 v[118:121], v[150:153], v[190:193], v[118:121]
	v_mfma_f32_16x16x32_bf16 v[114:117], v[170:173], v[178:181], v[114:117]
	v_mfma_f32_16x16x32_bf16 v[114:117], v[174:177], v[190:193], v[114:117]
	v_mfma_f32_16x16x32_bf16 v[102:105], v[146:149], v[194:197], v[102:105]
	v_mfma_f32_16x16x32_bf16 v[102:105], v[150:153], v[198:201], v[102:105]
	v_mfma_f32_16x16x32_bf16 v[98:101], v[170:173], v[194:197], v[98:101]
	v_mfma_f32_16x16x32_bf16 v[98:101], v[174:177], v[198:201], v[98:101]
	v_mfma_f32_16x16x32_bf16 v[86:89], v[146:149], v[202:205], v[86:89]
	v_mfma_f32_16x16x32_bf16 v[86:89], v[150:153], v[206:209], v[86:89]
	v_mfma_f32_16x16x32_bf16 v[82:85], v[170:173], v[202:205], v[82:85]
	v_mfma_f32_16x16x32_bf16 v[82:85], v[174:177], v[206:209], v[82:85]
	v_mfma_f32_16x16x32_bf16 v[70:73], v[146:149], v[210:213], v[70:73]
	v_mfma_f32_16x16x32_bf16 v[70:73], v[150:153], v[214:217], v[70:73]
	v_mfma_f32_16x16x32_bf16 v[66:69], v[170:173], v[210:213], v[66:69]
	v_mfma_f32_16x16x32_bf16 v[66:69], v[174:177], v[214:217], v[66:69]
	s_setprio 0
	s_barrier
	s_add_i32 s0, s49, s39
	v_lshl_add_u64 v[218:219], s[2:3], 0, v[156:157]
	s_mov_b32 m0, s0
	ds_read_b128 v[178:181], v188 offset:16384
	ds_read_b128 v[190:193], v188 offset:17408
	ds_read_b128 v[194:197], v188 offset:18432
	ds_read_b128 v[198:201], v188 offset:19456
	ds_read_b128 v[202:205], v188 offset:20480
	ds_read_b128 v[206:209], v188 offset:21504
	ds_read_b128 v[210:213], v188 offset:22528
	ds_read_b128 v[214:217], v188 offset:23552
	global_load_lds_dwordx4 v[218:219], off
	s_add_i32 m0, s0, 0x2000
	s_add_u32 s0, s2, 0xb0000
	v_lshl_add_u64 v[220:221], s[2:3], 0, v[160:161]
	s_addc_u32 s1, s3, 0
	s_add_i32 s56, s50, s39
	global_load_lds_dwordx4 v[220:221], off
	v_lshl_add_u64 v[222:223], s[0:1], 0, v[156:157]
	s_mov_b32 m0, s56
	v_lshl_add_u64 v[224:225], s[34:35], 0, v[158:159]
	global_load_lds_dwordx4 v[222:223], off
	v_lshl_add_u64 v[222:223], s[0:1], 0, v[160:161]
	s_add_i32 m0, s56, 0x2000
	s_nop 0
	global_load_lds_dwordx4 v[222:223], off
	v_lshl_add_u64 v[222:223], s[34:35], 0, v[154:155]
	s_mov_b32 m0, s40
	s_nop 0
	global_load_lds_dwordx4 v[222:223], off
	s_mov_b32 m0, s41
	s_nop 0
	global_load_lds_dwordx4 v[224:225], off
	s_waitcnt vmcnt(8)
	s_waitcnt lgkmcnt(0)
	s_barrier
	s_setprio 1
	s_waitcnt lgkmcnt(0)
	v_mfma_f32_16x16x32_bf16 v[62:65], v[130:133], v[178:181], v[62:65]
	v_mfma_f32_16x16x32_bf16 v[62:65], v[134:137], v[190:193], v[62:65]
	v_mfma_f32_16x16x32_bf16 v[58:61], v[138:141], v[178:181], v[58:61]
	v_mfma_f32_16x16x32_bf16 v[58:61], v[142:145], v[190:193], v[58:61]
	v_mfma_f32_16x16x32_bf16 v[46:49], v[130:133], v[194:197], v[46:49]
	v_mfma_f32_16x16x32_bf16 v[46:49], v[134:137], v[198:201], v[46:49]
	v_mfma_f32_16x16x32_bf16 v[42:45], v[138:141], v[194:197], v[42:45]
	v_mfma_f32_16x16x32_bf16 v[42:45], v[142:145], v[198:201], v[42:45]
	v_mfma_f32_16x16x32_bf16 v[30:33], v[130:133], v[202:205], v[30:33]
	v_mfma_f32_16x16x32_bf16 v[30:33], v[134:137], v[206:209], v[30:33]
	v_mfma_f32_16x16x32_bf16 v[26:29], v[138:141], v[202:205], v[26:29]
	v_mfma_f32_16x16x32_bf16 v[26:29], v[142:145], v[206:209], v[26:29]
	v_mfma_f32_16x16x32_bf16 v[14:17], v[130:133], v[210:213], v[14:17]
	v_mfma_f32_16x16x32_bf16 v[14:17], v[134:137], v[214:217], v[14:17]
	v_mfma_f32_16x16x32_bf16 v[10:13], v[138:141], v[210:213], v[10:13]
	v_mfma_f32_16x16x32_bf16 v[10:13], v[142:145], v[214:217], v[10:13]
	s_setprio 0
	s_setprio 1
	v_mfma_f32_16x16x32_bf16 v[54:57], v[146:149], v[178:181], v[54:57]
	v_mfma_f32_16x16x32_bf16 v[54:57], v[150:153], v[190:193], v[54:57]
	v_mfma_f32_16x16x32_bf16 v[50:53], v[170:173], v[178:181], v[50:53]
	v_mfma_f32_16x16x32_bf16 v[50:53], v[174:177], v[190:193], v[50:53]
	v_mfma_f32_16x16x32_bf16 v[38:41], v[146:149], v[194:197], v[38:41]
	v_mfma_f32_16x16x32_bf16 v[38:41], v[150:153], v[198:201], v[38:41]
	v_mfma_f32_16x16x32_bf16 v[34:37], v[170:173], v[194:197], v[34:37]
	v_mfma_f32_16x16x32_bf16 v[34:37], v[174:177], v[198:201], v[34:37]
	v_mfma_f32_16x16x32_bf16 v[22:25], v[146:149], v[202:205], v[22:25]
	v_mfma_f32_16x16x32_bf16 v[22:25], v[150:153], v[206:209], v[22:25]
	v_mfma_f32_16x16x32_bf16 v[18:21], v[170:173], v[202:205], v[18:21]
	v_mfma_f32_16x16x32_bf16 v[18:21], v[174:177], v[206:209], v[18:21]
	v_mfma_f32_16x16x32_bf16 v[6:9], v[146:149], v[210:213], v[6:9]
	v_mfma_f32_16x16x32_bf16 v[6:9], v[150:153], v[214:217], v[6:9]
	v_mfma_f32_16x16x32_bf16 v[2:5], v[170:173], v[210:213], v[2:5]
	v_mfma_f32_16x16x32_bf16 v[2:5], v[174:177], v[214:217], v[2:5]
	s_setprio 0
	s_barrier
	s_add_i32 s56, 0, 0x18000
	s_add_i32 s57, 0, 0x1c000
	v_add_u32_e32 v142, s56, v182
	v_add_u32_e32 v174, s57, v182
	ds_read_b128 v[130:133], v142
	ds_read_b128 v[134:137], v142 offset:1024
	ds_read_b128 v[138:141], v142 offset:2048
	ds_read_b128 v[142:145], v142 offset:3072
	ds_read_b128 v[146:149], v174
	ds_read_b128 v[150:153], v174 offset:1024
	ds_read_b128 v[170:173], v174 offset:2048
	ds_read_b128 v[174:177], v174 offset:3072
	s_add_u32 s0, s34, 0xb0000
	s_addc_u32 s1, s35, 0
	s_mov_b32 m0, s42
	v_lshl_add_u64 v[226:227], s[0:1], 0, v[154:155]
	ds_read_b128 v[178:181], v188 offset:32768
	ds_read_b128 v[190:193], v188 offset:33792
	ds_read_b128 v[194:197], v188 offset:34816
	ds_read_b128 v[198:201], v188 offset:35840
	ds_read_b128 v[202:205], v188 offset:36864
	ds_read_b128 v[206:209], v188 offset:37888
	ds_read_b128 v[210:213], v188 offset:38912
	ds_read_b128 v[214:217], v188 offset:39936
	global_load_lds_dwordx4 v[226:227], off
	v_lshl_add_u64 v[226:227], s[0:1], 0, v[158:159]
	s_mov_b32 m0, s43
	s_nop 0
	global_load_lds_dwordx4 v[226:227], off
	s_waitcnt vmcnt(8)
	s_waitcnt lgkmcnt(0)
	s_barrier
	s_setprio 1
	s_waitcnt lgkmcnt(0)
	v_mfma_f32_16x16x32_bf16 v[126:129], v[130:133], v[178:181], v[126:129]
	v_mfma_f32_16x16x32_bf16 v[126:129], v[134:137], v[190:193], v[126:129]
	v_mfma_f32_16x16x32_bf16 v[122:125], v[138:141], v[178:181], v[122:125]
	v_mfma_f32_16x16x32_bf16 v[122:125], v[142:145], v[190:193], v[122:125]
	v_mfma_f32_16x16x32_bf16 v[110:113], v[130:133], v[194:197], v[110:113]
	v_mfma_f32_16x16x32_bf16 v[110:113], v[134:137], v[198:201], v[110:113]
	v_mfma_f32_16x16x32_bf16 v[106:109], v[138:141], v[194:197], v[106:109]
	v_mfma_f32_16x16x32_bf16 v[106:109], v[142:145], v[198:201], v[106:109]
	v_mfma_f32_16x16x32_bf16 v[94:97], v[130:133], v[202:205], v[94:97]
	v_mfma_f32_16x16x32_bf16 v[94:97], v[134:137], v[206:209], v[94:97]
	v_mfma_f32_16x16x32_bf16 v[90:93], v[138:141], v[202:205], v[90:93]
	v_mfma_f32_16x16x32_bf16 v[90:93], v[142:145], v[206:209], v[90:93]
	v_mfma_f32_16x16x32_bf16 v[78:81], v[130:133], v[210:213], v[78:81]
	v_mfma_f32_16x16x32_bf16 v[78:81], v[134:137], v[214:217], v[78:81]
	v_mfma_f32_16x16x32_bf16 v[74:77], v[138:141], v[210:213], v[74:77]
	v_mfma_f32_16x16x32_bf16 v[74:77], v[142:145], v[214:217], v[74:77]
	s_setprio 0
	s_setprio 1
	v_mfma_f32_16x16x32_bf16 v[118:121], v[146:149], v[178:181], v[118:121]
	v_mfma_f32_16x16x32_bf16 v[118:121], v[150:153], v[190:193], v[118:121]
	v_mfma_f32_16x16x32_bf16 v[114:117], v[170:173], v[178:181], v[114:117]
	v_mfma_f32_16x16x32_bf16 v[114:117], v[174:177], v[190:193], v[114:117]
	v_mfma_f32_16x16x32_bf16 v[102:105], v[146:149], v[194:197], v[102:105]
	v_mfma_f32_16x16x32_bf16 v[102:105], v[150:153], v[198:201], v[102:105]
	v_mfma_f32_16x16x32_bf16 v[98:101], v[170:173], v[194:197], v[98:101]
	v_mfma_f32_16x16x32_bf16 v[98:101], v[174:177], v[198:201], v[98:101]
	v_mfma_f32_16x16x32_bf16 v[86:89], v[146:149], v[202:205], v[86:89]
	v_mfma_f32_16x16x32_bf16 v[86:89], v[150:153], v[206:209], v[86:89]
	v_mfma_f32_16x16x32_bf16 v[82:85], v[170:173], v[202:205], v[82:85]
	v_mfma_f32_16x16x32_bf16 v[82:85], v[174:177], v[206:209], v[82:85]
	v_mfma_f32_16x16x32_bf16 v[70:73], v[146:149], v[210:213], v[70:73]
	v_mfma_f32_16x16x32_bf16 v[70:73], v[150:153], v[214:217], v[70:73]
	v_mfma_f32_16x16x32_bf16 v[66:69], v[170:173], v[210:213], v[66:69]
	v_mfma_f32_16x16x32_bf16 v[66:69], v[174:177], v[214:217], v[66:69]
	s_setprio 0
	s_barrier
	s_add_i32 s0, s56, s39
	v_lshl_add_u64 v[218:219], v[218:219], 0, s[16:17]
	s_mov_b32 m0, s0
	ds_read_b128 v[178:181], v188 offset:49152
	ds_read_b128 v[190:193], v188 offset:50176
	ds_read_b128 v[194:197], v188 offset:51200
	ds_read_b128 v[198:201], v188 offset:52224
	ds_read_b128 v[202:205], v188 offset:53248
	ds_read_b128 v[206:209], v188 offset:54272
	ds_read_b128 v[210:213], v188 offset:55296
	ds_read_b128 v[214:217], v188 offset:56320
	global_load_lds_dwordx4 v[218:219], off
	s_add_i32 m0, s0, 0x2000
	s_add_u32 s0, s2, 0xb0080
	v_lshl_add_u64 v[218:219], v[220:221], 0, s[16:17]
	s_addc_u32 s1, s3, 0
	s_add_i32 s2, s57, s39
	global_load_lds_dwordx4 v[218:219], off
	v_lshl_add_u64 v[218:219], s[0:1], 0, v[156:157]
	s_mov_b32 m0, s2
	s_nop 0
	global_load_lds_dwordx4 v[218:219], off
	v_lshl_add_u64 v[218:219], s[0:1], 0, v[160:161]
	s_add_i32 m0, s2, 0x2000
	s_nop 0
	global_load_lds_dwordx4 v[218:219], off
	v_lshl_add_u64 v[218:219], v[222:223], 0, s[16:17]
	s_mov_b32 m0, s45
	s_nop 0
	global_load_lds_dwordx4 v[218:219], off
	v_lshl_add_u64 v[218:219], v[224:225], 0, s[16:17]
	s_mov_b32 m0, s46
	s_nop 0
	global_load_lds_dwordx4 v[218:219], off
	s_waitcnt vmcnt(8)
	s_waitcnt lgkmcnt(0)
	s_barrier
	s_setprio 1
	s_waitcnt lgkmcnt(0)
	v_mfma_f32_16x16x32_bf16 v[62:65], v[130:133], v[178:181], v[62:65]
	v_mfma_f32_16x16x32_bf16 v[62:65], v[134:137], v[190:193], v[62:65]
	v_mfma_f32_16x16x32_bf16 v[58:61], v[138:141], v[178:181], v[58:61]
	v_mfma_f32_16x16x32_bf16 v[58:61], v[142:145], v[190:193], v[58:61]
	v_mfma_f32_16x16x32_bf16 v[46:49], v[130:133], v[194:197], v[46:49]
	v_mfma_f32_16x16x32_bf16 v[46:49], v[134:137], v[198:201], v[46:49]
	v_mfma_f32_16x16x32_bf16 v[42:45], v[138:141], v[194:197], v[42:45]
	v_mfma_f32_16x16x32_bf16 v[42:45], v[142:145], v[198:201], v[42:45]
	v_mfma_f32_16x16x32_bf16 v[30:33], v[130:133], v[202:205], v[30:33]
	v_mfma_f32_16x16x32_bf16 v[30:33], v[134:137], v[206:209], v[30:33]
	v_mfma_f32_16x16x32_bf16 v[26:29], v[138:141], v[202:205], v[26:29]
	v_mfma_f32_16x16x32_bf16 v[26:29], v[142:145], v[206:209], v[26:29]
	v_mfma_f32_16x16x32_bf16 v[14:17], v[130:133], v[210:213], v[14:17]
	v_mfma_f32_16x16x32_bf16 v[14:17], v[134:137], v[214:217], v[14:17]
	v_mfma_f32_16x16x32_bf16 v[10:13], v[138:141], v[210:213], v[10:13]
	v_mfma_f32_16x16x32_bf16 v[10:13], v[142:145], v[214:217], v[10:13]
	s_setprio 0
	s_setprio 1
	v_mfma_f32_16x16x32_bf16 v[54:57], v[146:149], v[178:181], v[54:57]
	v_mfma_f32_16x16x32_bf16 v[54:57], v[150:153], v[190:193], v[54:57]
	v_mfma_f32_16x16x32_bf16 v[50:53], v[170:173], v[178:181], v[50:53]
	v_mfma_f32_16x16x32_bf16 v[50:53], v[174:177], v[190:193], v[50:53]
	v_mfma_f32_16x16x32_bf16 v[38:41], v[146:149], v[194:197], v[38:41]
	v_mfma_f32_16x16x32_bf16 v[38:41], v[150:153], v[198:201], v[38:41]
	v_mfma_f32_16x16x32_bf16 v[34:37], v[170:173], v[194:197], v[34:37]
	v_mfma_f32_16x16x32_bf16 v[34:37], v[174:177], v[198:201], v[34:37]
	v_mfma_f32_16x16x32_bf16 v[22:25], v[146:149], v[202:205], v[22:25]
	v_mfma_f32_16x16x32_bf16 v[22:25], v[150:153], v[206:209], v[22:25]
	v_mfma_f32_16x16x32_bf16 v[18:21], v[170:173], v[202:205], v[18:21]
	v_mfma_f32_16x16x32_bf16 v[18:21], v[174:177], v[206:209], v[18:21]
	v_mfma_f32_16x16x32_bf16 v[6:9], v[146:149], v[210:213], v[6:9]
	v_mfma_f32_16x16x32_bf16 v[6:9], v[150:153], v[214:217], v[6:9]
	v_mfma_f32_16x16x32_bf16 v[2:5], v[170:173], v[210:213], v[2:5]
	v_mfma_f32_16x16x32_bf16 v[2:5], v[174:177], v[214:217], v[2:5]
	s_setprio 0
	s_barrier
	s_add_i32 s55, s55, 2
	s_add_u32 s30, s30, 0x100
	s_addc_u32 s31, s31, 0
	s_add_u32 s53, s53, 0x100
	s_addc_u32 s54, s54, 0
	s_cmp_gt_u32 s55, 41
	s_cbranch_scc0 .LBB0_1841
	s_and_b64 vcc, exec, s[18:19]
	s_cbranch_vccz .LBB0_1844
	s_barrier

.LBB0_1938:
	ds_read_b128 v[148:151], v161
	ds_read_b128 v[152:155], v161 offset:1024
	ds_read_b128 v[156:159], v161 offset:2048
	ds_read_b128 v[166:169], v161 offset:3072
	ds_read_b128 v[170:173], v162
	ds_read_b128 v[174:177], v162 offset:1024
	ds_read_b128 v[178:181], v162 offset:2048
	ds_read_b128 v[182:185], v162 offset:3072
	s_add_u32 s0, s28, 0xfffc0080
	s_addc_u32 s1, s29, -1
	s_cmp_eq_u32 s51, 12
	s_cselect_b32 s31, s21, s1
	s_cselect_b32 s30, s47, s0
	s_cselect_b32 s3, s19, s50
	s_cselect_b32 s2, s48, s49
	v_lshl_add_u64 v[218:219], s[28:29], 0, v[140:141]
	s_add_i32 m0, s27, 0xc000
	ds_read_b128 v[186:189], v163
	ds_read_b128 v[190:193], v163 offset:1024
	ds_read_b128 v[194:197], v163 offset:2048
	ds_read_b128 v[198:201], v163 offset:3072
	ds_read_b128 v[202:205], v163 offset:4096
	ds_read_b128 v[206:209], v163 offset:5120
	ds_read_b128 v[210:213], v163 offset:6144
	ds_read_b128 v[214:217], v163 offset:7168
	global_load_lds_dwordx4 v[218:219], off
	v_lshl_add_u64 v[218:219], s[28:29], 0, v[142:143]
	s_add_i32 m0, s27, 0xe000
	s_nop 0
	global_load_lds_dwordx4 v[218:219], off
	s_waitcnt vmcnt(8)
	s_waitcnt lgkmcnt(0)
	s_barrier
	s_setprio 1
	s_waitcnt lgkmcnt(0)
	v_mfma_f32_16x16x32_bf16 v[126:129], v[148:151], v[186:189], v[126:129]
	v_mfma_f32_16x16x32_bf16 v[126:129], v[152:155], v[190:193], v[126:129]
	v_mfma_f32_16x16x32_bf16 v[118:121], v[156:159], v[186:189], v[118:121]
	v_mfma_f32_16x16x32_bf16 v[118:121], v[166:169], v[190:193], v[118:121]
	v_mfma_f32_16x16x32_bf16 v[110:113], v[148:151], v[194:197], v[110:113]
	v_mfma_f32_16x16x32_bf16 v[110:113], v[152:155], v[198:201], v[110:113]
	v_mfma_f32_16x16x32_bf16 v[106:109], v[156:159], v[194:197], v[106:109]
	v_mfma_f32_16x16x32_bf16 v[106:109], v[166:169], v[198:201], v[106:109]
	v_mfma_f32_16x16x32_bf16 v[94:97], v[148:151], v[202:205], v[94:97]
	v_mfma_f32_16x16x32_bf16 v[94:97], v[152:155], v[206:209], v[94:97]
	v_mfma_f32_16x16x32_bf16 v[90:93], v[156:159], v[202:205], v[90:93]
	v_mfma_f32_16x16x32_bf16 v[90:93], v[166:169], v[206:209], v[90:93]
	v_mfma_f32_16x16x32_bf16 v[78:81], v[148:151], v[210:213], v[78:81]
	v_mfma_f32_16x16x32_bf16 v[78:81], v[152:155], v[214:217], v[78:81]
	v_mfma_f32_16x16x32_bf16 v[74:77], v[156:159], v[210:213], v[74:77]
	v_mfma_f32_16x16x32_bf16 v[74:77], v[166:169], v[214:217], v[74:77]
	s_setprio 0
	s_setprio 1
	v_mfma_f32_16x16x32_bf16 v[122:125], v[170:173], v[186:189], v[122:125]
	v_mfma_f32_16x16x32_bf16 v[122:125], v[174:177], v[190:193], v[122:125]
	v_mfma_f32_16x16x32_bf16 v[114:117], v[178:181], v[186:189], v[114:117]
	v_mfma_f32_16x16x32_bf16 v[114:117], v[182:185], v[190:193], v[114:117]
	v_mfma_f32_16x16x32_bf16 v[102:105], v[170:173], v[194:197], v[102:105]
	v_mfma_f32_16x16x32_bf16 v[102:105], v[174:177], v[198:201], v[102:105]
	v_mfma_f32_16x16x32_bf16 v[98:101], v[178:181], v[194:197], v[98:101]
	v_mfma_f32_16x16x32_bf16 v[98:101], v[182:185], v[198:201], v[98:101]
	v_mfma_f32_16x16x32_bf16 v[86:89], v[170:173], v[202:205], v[86:89]
	v_mfma_f32_16x16x32_bf16 v[86:89], v[174:177], v[206:209], v[86:89]
	v_mfma_f32_16x16x32_bf16 v[82:85], v[178:181], v[202:205], v[82:85]
	v_mfma_f32_16x16x32_bf16 v[82:85], v[182:185], v[206:209], v[82:85]
	v_mfma_f32_16x16x32_bf16 v[70:73], v[170:173], v[210:213], v[70:73]
	v_mfma_f32_16x16x32_bf16 v[70:73], v[174:177], v[214:217], v[70:73]
	v_mfma_f32_16x16x32_bf16 v[66:69], v[178:181], v[210:213], v[66:69]
	v_mfma_f32_16x16x32_bf16 v[66:69], v[182:185], v[214:217], v[66:69]
	s_setprio 0
	s_barrier
	s_add_i32 s0, s43, s36
	v_lshl_add_u64 v[218:219], s[2:3], 0, v[132:133]
	s_mov_b32 m0, s0
	ds_read_b128 v[186:189], v163 offset:16384
	ds_read_b128 v[190:193], v163 offset:17408
	ds_read_b128 v[194:197], v163 offset:18432
	ds_read_b128 v[198:201], v163 offset:19456
	ds_read_b128 v[202:205], v163 offset:20480
	ds_read_b128 v[206:209], v163 offset:21504
	ds_read_b128 v[210:213], v163 offset:22528
	ds_read_b128 v[214:217], v163 offset:23552
	global_load_lds_dwordx4 v[218:219], off
	s_add_i32 m0, s0, 0x2000
	s_add_u32 s0, s2, 0x40000
	v_lshl_add_u64 v[220:221], s[2:3], 0, v[136:137]
	s_addc_u32 s1, s3, 0
	s_add_i32 s52, s44, s36
	global_load_lds_dwordx4 v[220:221], off
	v_lshl_add_u64 v[222:223], s[0:1], 0, v[132:133]
	s_mov_b32 m0, s52
	v_lshl_add_u64 v[224:225], s[30:31], 0, v[134:135]
	global_load_lds_dwordx4 v[222:223], off
	v_lshl_add_u64 v[222:223], s[0:1], 0, v[136:137]
	s_add_i32 m0, s52, 0x2000
	s_nop 0
	global_load_lds_dwordx4 v[222:223], off
	v_lshl_add_u64 v[222:223], s[30:31], 0, v[130:131]
	s_mov_b32 m0, s27
	s_nop 0
	global_load_lds_dwordx4 v[222:223], off
	s_mov_b32 m0, s37
	s_nop 0
	global_load_lds_dwordx4 v[224:225], off
	s_waitcnt vmcnt(8)
	s_waitcnt lgkmcnt(0)
	s_barrier
	s_setprio 1
	s_waitcnt lgkmcnt(0)
	v_mfma_f32_16x16x32_bf16 v[62:65], v[148:151], v[186:189], v[62:65]
	v_mfma_f32_16x16x32_bf16 v[62:65], v[152:155], v[190:193], v[62:65]
	v_mfma_f32_16x16x32_bf16 v[58:61], v[156:159], v[186:189], v[58:61]
	v_mfma_f32_16x16x32_bf16 v[58:61], v[166:169], v[190:193], v[58:61]
	v_mfma_f32_16x16x32_bf16 v[46:49], v[148:151], v[194:197], v[46:49]
	v_mfma_f32_16x16x32_bf16 v[46:49], v[152:155], v[198:201], v[46:49]
	v_mfma_f32_16x16x32_bf16 v[42:45], v[156:159], v[194:197], v[42:45]
	v_mfma_f32_16x16x32_bf16 v[42:45], v[166:169], v[198:201], v[42:45]
	v_mfma_f32_16x16x32_bf16 v[30:33], v[148:151], v[202:205], v[30:33]
	v_mfma_f32_16x16x32_bf16 v[30:33], v[152:155], v[206:209], v[30:33]
	v_mfma_f32_16x16x32_bf16 v[26:29], v[156:159], v[202:205], v[26:29]
	v_mfma_f32_16x16x32_bf16 v[26:29], v[166:169], v[206:209], v[26:29]
	v_mfma_f32_16x16x32_bf16 v[14:17], v[148:151], v[210:213], v[14:17]
	v_mfma_f32_16x16x32_bf16 v[14:17], v[152:155], v[214:217], v[14:17]
	v_mfma_f32_16x16x32_bf16 v[10:13], v[156:159], v[210:213], v[10:13]
	v_mfma_f32_16x16x32_bf16 v[10:13], v[166:169], v[214:217], v[10:13]
	s_setprio 0
	s_setprio 1
	v_mfma_f32_16x16x32_bf16 v[54:57], v[170:173], v[186:189], v[54:57]
	v_mfma_f32_16x16x32_bf16 v[54:57], v[174:177], v[190:193], v[54:57]
	v_mfma_f32_16x16x32_bf16 v[50:53], v[178:181], v[186:189], v[50:53]
	v_mfma_f32_16x16x32_bf16 v[50:53], v[182:185], v[190:193], v[50:53]
	v_mfma_f32_16x16x32_bf16 v[38:41], v[170:173], v[194:197], v[38:41]
	v_mfma_f32_16x16x32_bf16 v[38:41], v[174:177], v[198:201], v[38:41]
	v_mfma_f32_16x16x32_bf16 v[34:37], v[178:181], v[194:197], v[34:37]
	v_mfma_f32_16x16x32_bf16 v[34:37], v[182:185], v[198:201], v[34:37]
	v_mfma_f32_16x16x32_bf16 v[22:25], v[170:173], v[202:205], v[22:25]
	v_mfma_f32_16x16x32_bf16 v[22:25], v[174:177], v[206:209], v[22:25]
	v_mfma_f32_16x16x32_bf16 v[18:21], v[178:181], v[202:205], v[18:21]
	v_mfma_f32_16x16x32_bf16 v[18:21], v[182:185], v[206:209], v[18:21]
	v_mfma_f32_16x16x32_bf16 v[6:9], v[170:173], v[210:213], v[6:9]
	v_mfma_f32_16x16x32_bf16 v[6:9], v[174:177], v[214:217], v[6:9]
	v_mfma_f32_16x16x32_bf16 v[2:5], v[178:181], v[210:213], v[2:5]
	v_mfma_f32_16x16x32_bf16 v[2:5], v[182:185], v[214:217], v[2:5]
	s_setprio 0
	s_barrier
	s_add_i32 s52, 0, 0x18000
	v_add_u32_e32 v165, s52, v160
	s_add_i32 s53, 0, 0x1c000
	ds_read_b128 v[148:151], v165
	ds_read_b128 v[152:155], v165 offset:1024
	ds_read_b128 v[156:159], v165 offset:2048
	ds_read_b128 v[166:169], v165 offset:3072
	v_add_u32_e32 v165, s53, v160
	ds_read_b128 v[170:173], v165
	ds_read_b128 v[174:177], v165 offset:1024
	ds_read_b128 v[178:181], v165 offset:2048
	ds_read_b128 v[182:185], v165 offset:3072
	s_add_u32 s0, s30, 0x40000
	s_addc_u32 s1, s31, 0
	s_mov_b32 m0, s38
	v_lshl_add_u64 v[226:227], s[0:1], 0, v[130:131]
	ds_read_b128 v[186:189], v163 offset:32768
	ds_read_b128 v[190:193], v163 offset:33792
	ds_read_b128 v[194:197], v163 offset:34816
	ds_read_b128 v[198:201], v163 offset:35840
	ds_read_b128 v[202:205], v163 offset:36864
	ds_read_b128 v[206:209], v163 offset:37888
	ds_read_b128 v[210:213], v163 offset:38912
	ds_read_b128 v[214:217], v163 offset:39936
	global_load_lds_dwordx4 v[226:227], off
	v_lshl_add_u64 v[226:227], s[0:1], 0, v[134:135]
	s_mov_b32 m0, s39
	s_nop 0
	global_load_lds_dwordx4 v[226:227], off
	s_waitcnt vmcnt(8)
	s_waitcnt lgkmcnt(0)
	s_barrier
	s_setprio 1
	s_waitcnt lgkmcnt(0)
	v_mfma_f32_16x16x32_bf16 v[126:129], v[148:151], v[186:189], v[126:129]
	v_mfma_f32_16x16x32_bf16 v[126:129], v[152:155], v[190:193], v[126:129]
	v_mfma_f32_16x16x32_bf16 v[118:121], v[156:159], v[186:189], v[118:121]
	v_mfma_f32_16x16x32_bf16 v[118:121], v[166:169], v[190:193], v[118:121]
	v_mfma_f32_16x16x32_bf16 v[110:113], v[148:151], v[194:197], v[110:113]
	v_mfma_f32_16x16x32_bf16 v[110:113], v[152:155], v[198:201], v[110:113]
	v_mfma_f32_16x16x32_bf16 v[106:109], v[156:159], v[194:197], v[106:109]
	v_mfma_f32_16x16x32_bf16 v[106:109], v[166:169], v[198:201], v[106:109]
	v_mfma_f32_16x16x32_bf16 v[94:97], v[148:151], v[202:205], v[94:97]
	v_mfma_f32_16x16x32_bf16 v[94:97], v[152:155], v[206:209], v[94:97]
	v_mfma_f32_16x16x32_bf16 v[90:93], v[156:159], v[202:205], v[90:93]
	v_mfma_f32_16x16x32_bf16 v[90:93], v[166:169], v[206:209], v[90:93]
	v_mfma_f32_16x16x32_bf16 v[78:81], v[148:151], v[210:213], v[78:81]
	v_mfma_f32_16x16x32_bf16 v[78:81], v[152:155], v[214:217], v[78:81]
	v_mfma_f32_16x16x32_bf16 v[74:77], v[156:159], v[210:213], v[74:77]
	v_mfma_f32_16x16x32_bf16 v[74:77], v[166:169], v[214:217], v[74:77]
	s_setprio 0
	s_setprio 1
	v_mfma_f32_16x16x32_bf16 v[122:125], v[170:173], v[186:189], v[122:125]
	v_mfma_f32_16x16x32_bf16 v[122:125], v[174:177], v[190:193], v[122:125]
	v_mfma_f32_16x16x32_bf16 v[114:117], v[178:181], v[186:189], v[114:117]
	v_mfma_f32_16x16x32_bf16 v[114:117], v[182:185], v[190:193], v[114:117]
	v_mfma_f32_16x16x32_bf16 v[102:105], v[170:173], v[194:197], v[102:105]
	v_mfma_f32_16x16x32_bf16 v[102:105], v[174:177], v[198:201], v[102:105]
	v_mfma_f32_16x16x32_bf16 v[98:101], v[178:181], v[194:197], v[98:101]
	v_mfma_f32_16x16x32_bf16 v[98:101], v[182:185], v[198:201], v[98:101]
	v_mfma_f32_16x16x32_bf16 v[86:89], v[170:173], v[202:205], v[86:89]
	v_mfma_f32_16x16x32_bf16 v[86:89], v[174:177], v[206:209], v[86:89]
	v_mfma_f32_16x16x32_bf16 v[82:85], v[178:181], v[202:205], v[82:85]
	v_mfma_f32_16x16x32_bf16 v[82:85], v[182:185], v[206:209], v[82:85]
	v_mfma_f32_16x16x32_bf16 v[70:73], v[170:173], v[210:213], v[70:73]
	v_mfma_f32_16x16x32_bf16 v[70:73], v[174:177], v[214:217], v[70:73]
	v_mfma_f32_16x16x32_bf16 v[66:69], v[178:181], v[210:213], v[66:69]
	v_mfma_f32_16x16x32_bf16 v[66:69], v[182:185], v[214:217], v[66:69]
	s_setprio 0
	s_barrier
	s_add_i32 s0, s52, s36
	v_lshl_add_u64 v[218:219], v[218:219], 0, s[14:15]
	s_mov_b32 m0, s0
	ds_read_b128 v[186:189], v163 offset:49152
	ds_read_b128 v[190:193], v163 offset:50176
	ds_read_b128 v[194:197], v163 offset:51200
	ds_read_b128 v[198:201], v163 offset:52224
	ds_read_b128 v[202:205], v163 offset:53248
	ds_read_b128 v[206:209], v163 offset:54272
	ds_read_b128 v[210:213], v163 offset:55296
	ds_read_b128 v[214:217], v163 offset:56320
	global_load_lds_dwordx4 v[218:219], off
	s_add_i32 m0, s0, 0x2000
	s_add_u32 s0, s2, 0x40080
	v_lshl_add_u64 v[218:219], v[220:221], 0, s[14:15]
	s_addc_u32 s1, s3, 0
	s_add_i32 s2, s53, s36
	global_load_lds_dwordx4 v[218:219], off
	v_lshl_add_u64 v[218:219], s[0:1], 0, v[132:133]
	s_mov_b32 m0, s2
	s_nop 0
	global_load_lds_dwordx4 v[218:219], off
	v_lshl_add_u64 v[218:219], s[0:1], 0, v[136:137]
	s_add_i32 m0, s2, 0x2000
	s_nop 0
	global_load_lds_dwordx4 v[218:219], off
	v_lshl_add_u64 v[218:219], v[222:223], 0, s[14:15]
	s_mov_b32 m0, s40
	s_nop 0
	global_load_lds_dwordx4 v[218:219], off
	v_lshl_add_u64 v[218:219], v[224:225], 0, s[14:15]
	s_mov_b32 m0, s41
	s_nop 0
	global_load_lds_dwordx4 v[218:219], off
	s_waitcnt vmcnt(8)
	s_waitcnt lgkmcnt(0)
	s_barrier
	s_setprio 1
	s_waitcnt lgkmcnt(0)
	v_mfma_f32_16x16x32_bf16 v[62:65], v[148:151], v[186:189], v[62:65]
	v_mfma_f32_16x16x32_bf16 v[62:65], v[152:155], v[190:193], v[62:65]
	v_mfma_f32_16x16x32_bf16 v[58:61], v[156:159], v[186:189], v[58:61]
	v_mfma_f32_16x16x32_bf16 v[58:61], v[166:169], v[190:193], v[58:61]
	v_mfma_f32_16x16x32_bf16 v[46:49], v[148:151], v[194:197], v[46:49]
	v_mfma_f32_16x16x32_bf16 v[46:49], v[152:155], v[198:201], v[46:49]
	v_mfma_f32_16x16x32_bf16 v[42:45], v[156:159], v[194:197], v[42:45]
	v_mfma_f32_16x16x32_bf16 v[42:45], v[166:169], v[198:201], v[42:45]
	v_mfma_f32_16x16x32_bf16 v[30:33], v[148:151], v[202:205], v[30:33]
	v_mfma_f32_16x16x32_bf16 v[30:33], v[152:155], v[206:209], v[30:33]
	v_mfma_f32_16x16x32_bf16 v[26:29], v[156:159], v[202:205], v[26:29]
	v_mfma_f32_16x16x32_bf16 v[26:29], v[166:169], v[206:209], v[26:29]
	v_mfma_f32_16x16x32_bf16 v[14:17], v[148:151], v[210:213], v[14:17]
	v_mfma_f32_16x16x32_bf16 v[14:17], v[152:155], v[214:217], v[14:17]
	v_mfma_f32_16x16x32_bf16 v[10:13], v[156:159], v[210:213], v[10:13]
	v_mfma_f32_16x16x32_bf16 v[10:13], v[166:169], v[214:217], v[10:13]
	s_setprio 0
	s_setprio 1
	v_mfma_f32_16x16x32_bf16 v[54:57], v[170:173], v[186:189], v[54:57]
	v_mfma_f32_16x16x32_bf16 v[54:57], v[174:177], v[190:193], v[54:57]
	v_mfma_f32_16x16x32_bf16 v[50:53], v[178:181], v[186:189], v[50:53]
	v_mfma_f32_16x16x32_bf16 v[50:53], v[182:185], v[190:193], v[50:53]
	v_mfma_f32_16x16x32_bf16 v[38:41], v[170:173], v[194:197], v[38:41]
	v_mfma_f32_16x16x32_bf16 v[38:41], v[174:177], v[198:201], v[38:41]
	v_mfma_f32_16x16x32_bf16 v[34:37], v[178:181], v[194:197], v[34:37]
	v_mfma_f32_16x16x32_bf16 v[34:37], v[182:185], v[198:201], v[34:37]
	v_mfma_f32_16x16x32_bf16 v[22:25], v[170:173], v[202:205], v[22:25]
	v_mfma_f32_16x16x32_bf16 v[22:25], v[174:177], v[206:209], v[22:25]
	v_mfma_f32_16x16x32_bf16 v[18:21], v[178:181], v[202:205], v[18:21]
	v_mfma_f32_16x16x32_bf16 v[18:21], v[182:185], v[206:209], v[18:21]
	v_mfma_f32_16x16x32_bf16 v[6:9], v[170:173], v[210:213], v[6:9]
	v_mfma_f32_16x16x32_bf16 v[6:9], v[174:177], v[214:217], v[6:9]
	v_mfma_f32_16x16x32_bf16 v[2:5], v[178:181], v[210:213], v[2:5]
	v_mfma_f32_16x16x32_bf16 v[2:5], v[182:185], v[214:217], v[2:5]
	s_setprio 0
	s_barrier
	s_add_i32 s51, s51, 2
	s_add_u32 s28, s28, 0x100
	s_addc_u32 s29, s29, 0
	s_add_u32 s49, s49, 0x100
	s_addc_u32 s50, s50, 0
	s_cmp_gt_u32 s51, 13
	s_cbranch_scc0 .LBB0_1938
	s_and_b64 vcc, exec, s[16:17]
	s_cbranch_vccz .LBB0_1941
	s_barrier

.LBB0_2019:
	ds_read_b128 v[110:113], v227
	ds_read_b128 v[114:117], v227 offset:1024
	ds_read_b128 v[122:125], v227 offset:2048
	ds_read_b128 v[126:129], v227 offset:3072
	ds_read_b128 v[146:149], v228
	ds_read_b128 v[150:153], v228 offset:1024
	ds_read_b128 v[154:157], v228 offset:2048
	ds_read_b128 v[158:161], v228 offset:3072
	s_add_u32 s0, s10, 0xfffc0080
	s_addc_u32 s1, s11, -1
	s_cmp_eq_u32 s77, 12
	s_cselect_b32 s13, s7, s1
	s_cselect_b32 s12, s9, s0
	s_cselect_b32 s3, s55, s63
	s_cselect_b32 s2, s57, s62
	v_lshl_add_u64 v[212:213], s[10:11], 0, v[180:181]
	s_add_i32 m0, s66, 0xc000
	ds_read_b128 v[162:165], v229
	ds_read_b128 v[166:169], v229 offset:1024
	ds_read_b128 v[188:191], v229 offset:2048
	ds_read_b128 v[192:195], v229 offset:3072
	ds_read_b128 v[196:199], v229 offset:4096
	ds_read_b128 v[200:203], v229 offset:5120
	ds_read_b128 v[204:207], v229 offset:6144
	ds_read_b128 v[208:211], v229 offset:7168
	global_load_lds_dwordx4 v[212:213], off
	v_lshl_add_u64 v[212:213], s[10:11], 0, v[182:183]
	s_add_i32 m0, s66, 0xe000
	s_nop 0
	global_load_lds_dwordx4 v[212:213], off
	s_waitcnt vmcnt(8)
	s_waitcnt lgkmcnt(0)
	s_barrier
	s_setprio 1
	s_waitcnt lgkmcnt(0)
	v_mfma_f32_16x16x32_bf16 v[142:145], v[110:113], v[162:165], v[142:145]
	v_mfma_f32_16x16x32_bf16 v[142:145], v[114:117], v[166:169], v[142:145]
	v_mfma_f32_16x16x32_bf16 v[138:141], v[122:125], v[162:165], v[138:141]
	v_mfma_f32_16x16x32_bf16 v[138:141], v[126:129], v[166:169], v[138:141]
	v_mfma_f32_16x16x32_bf16 v[134:137], v[110:113], v[188:191], v[134:137]
	v_mfma_f32_16x16x32_bf16 v[134:137], v[114:117], v[192:195], v[134:137]
	v_mfma_f32_16x16x32_bf16 v[130:133], v[122:125], v[188:191], v[130:133]
	v_mfma_f32_16x16x32_bf16 v[130:133], v[126:129], v[192:195], v[130:133]
	v_mfma_f32_16x16x32_bf16 v[118:121], v[110:113], v[196:199], v[118:121]
	v_mfma_f32_16x16x32_bf16 v[118:121], v[114:117], v[200:203], v[118:121]
	v_mfma_f32_16x16x32_bf16 v[106:109], v[122:125], v[196:199], v[106:109]
	v_mfma_f32_16x16x32_bf16 v[106:109], v[126:129], v[200:203], v[106:109]
	v_mfma_f32_16x16x32_bf16 v[102:105], v[110:113], v[204:207], v[102:105]
	v_mfma_f32_16x16x32_bf16 v[102:105], v[114:117], v[208:211], v[102:105]
	v_mfma_f32_16x16x32_bf16 v[98:101], v[122:125], v[204:207], v[98:101]
	v_mfma_f32_16x16x32_bf16 v[98:101], v[126:129], v[208:211], v[98:101]
	s_setprio 0
	s_setprio 1
	v_mfma_f32_16x16x32_bf16 v[62:65], v[146:149], v[162:165], v[62:65]
	v_mfma_f32_16x16x32_bf16 v[62:65], v[150:153], v[166:169], v[62:65]
	v_mfma_f32_16x16x32_bf16 v[58:61], v[154:157], v[162:165], v[58:61]
	v_mfma_f32_16x16x32_bf16 v[58:61], v[158:161], v[166:169], v[58:61]
	v_mfma_f32_16x16x32_bf16 v[54:57], v[146:149], v[188:191], v[54:57]
	v_mfma_f32_16x16x32_bf16 v[54:57], v[150:153], v[192:195], v[54:57]
	v_mfma_f32_16x16x32_bf16 v[50:53], v[154:157], v[188:191], v[50:53]
	v_mfma_f32_16x16x32_bf16 v[50:53], v[158:161], v[192:195], v[50:53]
	v_mfma_f32_16x16x32_bf16 v[46:49], v[146:149], v[196:199], v[46:49]
	v_mfma_f32_16x16x32_bf16 v[46:49], v[150:153], v[200:203], v[46:49]
	v_mfma_f32_16x16x32_bf16 v[42:45], v[154:157], v[196:199], v[42:45]
	v_mfma_f32_16x16x32_bf16 v[42:45], v[158:161], v[200:203], v[42:45]
	v_mfma_f32_16x16x32_bf16 v[38:41], v[146:149], v[204:207], v[38:41]
	v_mfma_f32_16x16x32_bf16 v[38:41], v[150:153], v[208:211], v[38:41]
	v_mfma_f32_16x16x32_bf16 v[34:37], v[154:157], v[204:207], v[34:37]
	v_mfma_f32_16x16x32_bf16 v[34:37], v[158:161], v[208:211], v[34:37]
	s_setprio 0
	s_barrier
	s_add_i32 s0, s75, s65
	v_lshl_add_u64 v[212:213], s[2:3], 0, v[172:173]
	s_mov_b32 m0, s0
	ds_read_b128 v[162:165], v229 offset:16384
	ds_read_b128 v[166:169], v229 offset:17408
	ds_read_b128 v[188:191], v229 offset:18432
	ds_read_b128 v[192:195], v229 offset:19456
	ds_read_b128 v[196:199], v229 offset:20480
	ds_read_b128 v[200:203], v229 offset:21504
	ds_read_b128 v[204:207], v229 offset:22528
	ds_read_b128 v[208:211], v229 offset:23552
	global_load_lds_dwordx4 v[212:213], off
	s_add_i32 m0, s0, 0x2000
	s_add_u32 s0, s2, 0x40000
	v_lshl_add_u64 v[214:215], s[2:3], 0, v[176:177]
	s_addc_u32 s1, s3, 0
	s_add_i32 s78, s76, s65
	global_load_lds_dwordx4 v[214:215], off
	v_lshl_add_u64 v[216:217], s[0:1], 0, v[172:173]
	s_mov_b32 m0, s78
	v_lshl_add_u64 v[218:219], s[12:13], 0, v[174:175]
	global_load_lds_dwordx4 v[216:217], off
	v_lshl_add_u64 v[216:217], s[0:1], 0, v[176:177]
	s_add_i32 m0, s78, 0x2000
	s_nop 0
	global_load_lds_dwordx4 v[216:217], off
	v_lshl_add_u64 v[216:217], s[12:13], 0, v[170:171]
	s_mov_b32 m0, s66
	s_nop 0
	global_load_lds_dwordx4 v[216:217], off
	s_mov_b32 m0, s67
	s_nop 0
	global_load_lds_dwordx4 v[218:219], off
	s_waitcnt vmcnt(8)
	s_waitcnt lgkmcnt(0)
	s_barrier
	s_setprio 1
	s_waitcnt lgkmcnt(0)
	v_mfma_f32_16x16x32_bf16 v[94:97], v[110:113], v[162:165], v[94:97]
	v_mfma_f32_16x16x32_bf16 v[94:97], v[114:117], v[166:169], v[94:97]
	v_mfma_f32_16x16x32_bf16 v[90:93], v[122:125], v[162:165], v[90:93]
	v_mfma_f32_16x16x32_bf16 v[90:93], v[126:129], v[166:169], v[90:93]
	v_mfma_f32_16x16x32_bf16 v[86:89], v[110:113], v[188:191], v[86:89]
	v_mfma_f32_16x16x32_bf16 v[86:89], v[114:117], v[192:195], v[86:89]
	v_mfma_f32_16x16x32_bf16 v[82:85], v[122:125], v[188:191], v[82:85]
	v_mfma_f32_16x16x32_bf16 v[82:85], v[126:129], v[192:195], v[82:85]
	v_mfma_f32_16x16x32_bf16 v[78:81], v[110:113], v[196:199], v[78:81]
	v_mfma_f32_16x16x32_bf16 v[78:81], v[114:117], v[200:203], v[78:81]
	v_mfma_f32_16x16x32_bf16 v[74:77], v[122:125], v[196:199], v[74:77]
	v_mfma_f32_16x16x32_bf16 v[74:77], v[126:129], v[200:203], v[74:77]
	v_mfma_f32_16x16x32_bf16 v[70:73], v[110:113], v[204:207], v[70:73]
	v_mfma_f32_16x16x32_bf16 v[70:73], v[114:117], v[208:211], v[70:73]
	v_mfma_f32_16x16x32_bf16 v[66:69], v[122:125], v[204:207], v[66:69]
	v_mfma_f32_16x16x32_bf16 v[66:69], v[126:129], v[208:211], v[66:69]
	s_setprio 0
	s_setprio 1
	v_mfma_f32_16x16x32_bf16 v[30:33], v[146:149], v[162:165], v[30:33]
	v_mfma_f32_16x16x32_bf16 v[30:33], v[150:153], v[166:169], v[30:33]
	v_mfma_f32_16x16x32_bf16 v[26:29], v[154:157], v[162:165], v[26:29]
	v_mfma_f32_16x16x32_bf16 v[26:29], v[158:161], v[166:169], v[26:29]
	v_mfma_f32_16x16x32_bf16 v[22:25], v[146:149], v[188:191], v[22:25]
	v_mfma_f32_16x16x32_bf16 v[22:25], v[150:153], v[192:195], v[22:25]
	v_mfma_f32_16x16x32_bf16 v[18:21], v[154:157], v[188:191], v[18:21]
	v_mfma_f32_16x16x32_bf16 v[18:21], v[158:161], v[192:195], v[18:21]
	v_mfma_f32_16x16x32_bf16 v[14:17], v[146:149], v[196:199], v[14:17]
	v_mfma_f32_16x16x32_bf16 v[14:17], v[150:153], v[200:203], v[14:17]
	v_mfma_f32_16x16x32_bf16 v[10:13], v[154:157], v[196:199], v[10:13]
	v_mfma_f32_16x16x32_bf16 v[10:13], v[158:161], v[200:203], v[10:13]
	v_mfma_f32_16x16x32_bf16 v[6:9], v[146:149], v[204:207], v[6:9]
	v_mfma_f32_16x16x32_bf16 v[6:9], v[150:153], v[208:211], v[6:9]
	v_mfma_f32_16x16x32_bf16 v[2:5], v[154:157], v[204:207], v[2:5]
	v_mfma_f32_16x16x32_bf16 v[2:5], v[158:161], v[208:211], v[2:5]
	s_setprio 0
	s_barrier
	s_add_i32 s78, 0, 0x18000
	s_add_i32 s79, 0, 0x1c000
	v_add_u32_e32 v126, s78, v222
	v_add_u32_e32 v158, s79, v222
	ds_read_b128 v[110:113], v126
	ds_read_b128 v[114:117], v126 offset:1024
	ds_read_b128 v[122:125], v126 offset:2048
	ds_read_b128 v[126:129], v126 offset:3072
	ds_read_b128 v[146:149], v158
	ds_read_b128 v[150:153], v158 offset:1024
	ds_read_b128 v[154:157], v158 offset:2048
	ds_read_b128 v[158:161], v158 offset:3072
	s_add_u32 s0, s12, 0x40000
	s_addc_u32 s1, s13, 0
	s_mov_b32 m0, s68
	v_lshl_add_u64 v[220:221], s[0:1], 0, v[170:171]
	ds_read_b128 v[162:165], v229 offset:32768
	ds_read_b128 v[166:169], v229 offset:33792
	ds_read_b128 v[188:191], v229 offset:34816
	ds_read_b128 v[192:195], v229 offset:35840
	ds_read_b128 v[196:199], v229 offset:36864
	ds_read_b128 v[200:203], v229 offset:37888
	ds_read_b128 v[204:207], v229 offset:38912
	ds_read_b128 v[208:211], v229 offset:39936
	global_load_lds_dwordx4 v[220:221], off
	v_lshl_add_u64 v[220:221], s[0:1], 0, v[174:175]
	s_mov_b32 m0, s69
	s_nop 0
	global_load_lds_dwordx4 v[220:221], off
	s_waitcnt vmcnt(8)
	s_waitcnt lgkmcnt(0)
	s_barrier
	s_setprio 1
	s_waitcnt lgkmcnt(0)
	v_mfma_f32_16x16x32_bf16 v[142:145], v[110:113], v[162:165], v[142:145]
	v_mfma_f32_16x16x32_bf16 v[142:145], v[114:117], v[166:169], v[142:145]
	v_mfma_f32_16x16x32_bf16 v[138:141], v[122:125], v[162:165], v[138:141]
	v_mfma_f32_16x16x32_bf16 v[138:141], v[126:129], v[166:169], v[138:141]
	v_mfma_f32_16x16x32_bf16 v[134:137], v[110:113], v[188:191], v[134:137]
	v_mfma_f32_16x16x32_bf16 v[134:137], v[114:117], v[192:195], v[134:137]
	v_mfma_f32_16x16x32_bf16 v[130:133], v[122:125], v[188:191], v[130:133]
	v_mfma_f32_16x16x32_bf16 v[130:133], v[126:129], v[192:195], v[130:133]
	v_mfma_f32_16x16x32_bf16 v[118:121], v[110:113], v[196:199], v[118:121]
	v_mfma_f32_16x16x32_bf16 v[118:121], v[114:117], v[200:203], v[118:121]
	v_mfma_f32_16x16x32_bf16 v[106:109], v[122:125], v[196:199], v[106:109]
	v_mfma_f32_16x16x32_bf16 v[106:109], v[126:129], v[200:203], v[106:109]
	v_mfma_f32_16x16x32_bf16 v[102:105], v[110:113], v[204:207], v[102:105]
	v_mfma_f32_16x16x32_bf16 v[102:105], v[114:117], v[208:211], v[102:105]
	v_mfma_f32_16x16x32_bf16 v[98:101], v[122:125], v[204:207], v[98:101]
	v_mfma_f32_16x16x32_bf16 v[98:101], v[126:129], v[208:211], v[98:101]
	s_setprio 0
	s_setprio 1
	v_mfma_f32_16x16x32_bf16 v[62:65], v[146:149], v[162:165], v[62:65]
	v_mfma_f32_16x16x32_bf16 v[62:65], v[150:153], v[166:169], v[62:65]
	v_mfma_f32_16x16x32_bf16 v[58:61], v[154:157], v[162:165], v[58:61]
	v_mfma_f32_16x16x32_bf16 v[58:61], v[158:161], v[166:169], v[58:61]
	v_mfma_f32_16x16x32_bf16 v[54:57], v[146:149], v[188:191], v[54:57]
	v_mfma_f32_16x16x32_bf16 v[54:57], v[150:153], v[192:195], v[54:57]
	v_mfma_f32_16x16x32_bf16 v[50:53], v[154:157], v[188:191], v[50:53]
	v_mfma_f32_16x16x32_bf16 v[50:53], v[158:161], v[192:195], v[50:53]
	v_mfma_f32_16x16x32_bf16 v[46:49], v[146:149], v[196:199], v[46:49]
	v_mfma_f32_16x16x32_bf16 v[46:49], v[150:153], v[200:203], v[46:49]
	v_mfma_f32_16x16x32_bf16 v[42:45], v[154:157], v[196:199], v[42:45]
	v_mfma_f32_16x16x32_bf16 v[42:45], v[158:161], v[200:203], v[42:45]
	v_mfma_f32_16x16x32_bf16 v[38:41], v[146:149], v[204:207], v[38:41]
	v_mfma_f32_16x16x32_bf16 v[38:41], v[150:153], v[208:211], v[38:41]
	v_mfma_f32_16x16x32_bf16 v[34:37], v[154:157], v[204:207], v[34:37]
	v_mfma_f32_16x16x32_bf16 v[34:37], v[158:161], v[208:211], v[34:37]
	s_setprio 0
	s_barrier
	s_add_i32 s0, s78, s65
	v_lshl_add_u64 v[212:213], v[212:213], 0, s[24:25]
	s_mov_b32 m0, s0
	ds_read_b128 v[162:165], v229 offset:49152
	ds_read_b128 v[166:169], v229 offset:50176
	ds_read_b128 v[188:191], v229 offset:51200
	ds_read_b128 v[192:195], v229 offset:52224
	ds_read_b128 v[196:199], v229 offset:53248
	ds_read_b128 v[200:203], v229 offset:54272
	ds_read_b128 v[204:207], v229 offset:55296
	ds_read_b128 v[208:211], v229 offset:56320
	global_load_lds_dwordx4 v[212:213], off
	s_add_i32 m0, s0, 0x2000
	s_add_u32 s0, s2, 0x40080
	v_lshl_add_u64 v[212:213], v[214:215], 0, s[24:25]
	s_addc_u32 s1, s3, 0
	s_add_i32 s2, s79, s65
	global_load_lds_dwordx4 v[212:213], off
	v_lshl_add_u64 v[212:213], s[0:1], 0, v[172:173]
	s_mov_b32 m0, s2
	s_nop 0
	global_load_lds_dwordx4 v[212:213], off
	v_lshl_add_u64 v[212:213], s[0:1], 0, v[176:177]
	s_add_i32 m0, s2, 0x2000
	s_nop 0
	global_load_lds_dwordx4 v[212:213], off
	v_lshl_add_u64 v[212:213], v[216:217], 0, s[24:25]
	s_mov_b32 m0, s71
	s_nop 0
	global_load_lds_dwordx4 v[212:213], off
	v_lshl_add_u64 v[212:213], v[218:219], 0, s[24:25]
	s_mov_b32 m0, s72
	s_nop 0
	global_load_lds_dwordx4 v[212:213], off
	s_waitcnt vmcnt(8)
	s_waitcnt lgkmcnt(0)
	s_barrier
	s_setprio 1
	s_waitcnt lgkmcnt(0)
	v_mfma_f32_16x16x32_bf16 v[94:97], v[110:113], v[162:165], v[94:97]
	v_mfma_f32_16x16x32_bf16 v[94:97], v[114:117], v[166:169], v[94:97]
	v_mfma_f32_16x16x32_bf16 v[90:93], v[122:125], v[162:165], v[90:93]
	v_mfma_f32_16x16x32_bf16 v[90:93], v[126:129], v[166:169], v[90:93]
	v_mfma_f32_16x16x32_bf16 v[86:89], v[110:113], v[188:191], v[86:89]
	v_mfma_f32_16x16x32_bf16 v[86:89], v[114:117], v[192:195], v[86:89]
	v_mfma_f32_16x16x32_bf16 v[82:85], v[122:125], v[188:191], v[82:85]
	v_mfma_f32_16x16x32_bf16 v[82:85], v[126:129], v[192:195], v[82:85]
	v_mfma_f32_16x16x32_bf16 v[78:81], v[110:113], v[196:199], v[78:81]
	v_mfma_f32_16x16x32_bf16 v[78:81], v[114:117], v[200:203], v[78:81]
	v_mfma_f32_16x16x32_bf16 v[74:77], v[122:125], v[196:199], v[74:77]
	v_mfma_f32_16x16x32_bf16 v[74:77], v[126:129], v[200:203], v[74:77]
	v_mfma_f32_16x16x32_bf16 v[70:73], v[110:113], v[204:207], v[70:73]
	v_mfma_f32_16x16x32_bf16 v[70:73], v[114:117], v[208:211], v[70:73]
	v_mfma_f32_16x16x32_bf16 v[66:69], v[122:125], v[204:207], v[66:69]
	v_mfma_f32_16x16x32_bf16 v[66:69], v[126:129], v[208:211], v[66:69]
	s_setprio 0
	s_setprio 1
	v_mfma_f32_16x16x32_bf16 v[30:33], v[146:149], v[162:165], v[30:33]
	v_mfma_f32_16x16x32_bf16 v[30:33], v[150:153], v[166:169], v[30:33]
	v_mfma_f32_16x16x32_bf16 v[26:29], v[154:157], v[162:165], v[26:29]
	v_mfma_f32_16x16x32_bf16 v[26:29], v[158:161], v[166:169], v[26:29]
	v_mfma_f32_16x16x32_bf16 v[22:25], v[146:149], v[188:191], v[22:25]
	v_mfma_f32_16x16x32_bf16 v[22:25], v[150:153], v[192:195], v[22:25]
	v_mfma_f32_16x16x32_bf16 v[18:21], v[154:157], v[188:191], v[18:21]
	v_mfma_f32_16x16x32_bf16 v[18:21], v[158:161], v[192:195], v[18:21]
	v_mfma_f32_16x16x32_bf16 v[14:17], v[146:149], v[196:199], v[14:17]
	v_mfma_f32_16x16x32_bf16 v[14:17], v[150:153], v[200:203], v[14:17]
	v_mfma_f32_16x16x32_bf16 v[10:13], v[154:157], v[196:199], v[10:13]
	v_mfma_f32_16x16x32_bf16 v[10:13], v[158:161], v[200:203], v[10:13]
	v_mfma_f32_16x16x32_bf16 v[6:9], v[146:149], v[204:207], v[6:9]
	v_mfma_f32_16x16x32_bf16 v[6:9], v[150:153], v[208:211], v[6:9]
	v_mfma_f32_16x16x32_bf16 v[2:5], v[154:157], v[204:207], v[2:5]
	v_mfma_f32_16x16x32_bf16 v[2:5], v[158:161], v[208:211], v[2:5]
	s_setprio 0
	s_barrier
	s_add_i32 s77, s77, 2
	s_add_u32 s10, s10, 0x100
	s_addc_u32 s11, s11, 0
	s_add_u32 s62, s62, 0x100
	s_addc_u32 s63, s63, 0
	s_cmp_gt_u32 s77, 13
	s_cbranch_scc0 .LBB0_2019
	s_and_b64 vcc, exec, s[26:27]
	s_cbranch_vccz .LBB0_2022
	s_barrier

.LBB0_2118:
	ds_read_b128 v[130:133], v186
	ds_read_b128 v[134:137], v186 offset:1024
	ds_read_b128 v[138:141], v186 offset:2048
	ds_read_b128 v[142:145], v186 offset:3072
	ds_read_b128 v[146:149], v187
	ds_read_b128 v[150:153], v187 offset:1024
	ds_read_b128 v[170:173], v187 offset:2048
	ds_read_b128 v[174:177], v187 offset:3072
	s_add_u32 s0, s38, 0xfffc0080
	s_addc_u32 s1, s39, -1
	s_cmp_eq_u32 s59, 12
	s_cselect_b32 s41, s11, s1
	s_cselect_b32 s40, s29, s0
	s_cselect_b32 s3, s27, s58
	s_cselect_b32 s2, s56, s57
	v_lshl_add_u64 v[218:219], s[38:39], 0, v[162:163]
	s_add_i32 m0, s37, 0xc000
	ds_read_b128 v[178:181], v188
	ds_read_b128 v[190:193], v188 offset:1024
	ds_read_b128 v[194:197], v188 offset:2048
	ds_read_b128 v[198:201], v188 offset:3072
	ds_read_b128 v[202:205], v188 offset:4096
	ds_read_b128 v[206:209], v188 offset:5120
	ds_read_b128 v[210:213], v188 offset:6144
	ds_read_b128 v[214:217], v188 offset:7168
	global_load_lds_dwordx4 v[218:219], off
	v_lshl_add_u64 v[218:219], s[38:39], 0, v[164:165]
	s_add_i32 m0, s37, 0xe000
	s_nop 0
	global_load_lds_dwordx4 v[218:219], off
	s_waitcnt vmcnt(8)
	s_waitcnt lgkmcnt(0)
	s_barrier
	s_setprio 1
	s_waitcnt lgkmcnt(0)
	v_mfma_f32_16x16x32_bf16 v[126:129], v[130:133], v[178:181], v[126:129]
	v_mfma_f32_16x16x32_bf16 v[126:129], v[134:137], v[190:193], v[126:129]
	v_mfma_f32_16x16x32_bf16 v[122:125], v[138:141], v[178:181], v[122:125]
	v_mfma_f32_16x16x32_bf16 v[122:125], v[142:145], v[190:193], v[122:125]
	v_mfma_f32_16x16x32_bf16 v[110:113], v[130:133], v[194:197], v[110:113]
	v_mfma_f32_16x16x32_bf16 v[110:113], v[134:137], v[198:201], v[110:113]
	v_mfma_f32_16x16x32_bf16 v[106:109], v[138:141], v[194:197], v[106:109]
	v_mfma_f32_16x16x32_bf16 v[106:109], v[142:145], v[198:201], v[106:109]
	v_mfma_f32_16x16x32_bf16 v[94:97], v[130:133], v[202:205], v[94:97]
	v_mfma_f32_16x16x32_bf16 v[94:97], v[134:137], v[206:209], v[94:97]
	v_mfma_f32_16x16x32_bf16 v[90:93], v[138:141], v[202:205], v[90:93]
	v_mfma_f32_16x16x32_bf16 v[90:93], v[142:145], v[206:209], v[90:93]
	v_mfma_f32_16x16x32_bf16 v[78:81], v[130:133], v[210:213], v[78:81]
	v_mfma_f32_16x16x32_bf16 v[78:81], v[134:137], v[214:217], v[78:81]
	v_mfma_f32_16x16x32_bf16 v[74:77], v[138:141], v[210:213], v[74:77]
	v_mfma_f32_16x16x32_bf16 v[74:77], v[142:145], v[214:217], v[74:77]
	s_setprio 0
	s_setprio 1
	v_mfma_f32_16x16x32_bf16 v[118:121], v[146:149], v[178:181], v[118:121]
	v_mfma_f32_16x16x32_bf16 v[118:121], v[150:153], v[190:193], v[118:121]
	v_mfma_f32_16x16x32_bf16 v[114:117], v[170:173], v[178:181], v[114:117]
	v_mfma_f32_16x16x32_bf16 v[114:117], v[174:177], v[190:193], v[114:117]
	v_mfma_f32_16x16x32_bf16 v[102:105], v[146:149], v[194:197], v[102:105]
	v_mfma_f32_16x16x32_bf16 v[102:105], v[150:153], v[198:201], v[102:105]
	v_mfma_f32_16x16x32_bf16 v[98:101], v[170:173], v[194:197], v[98:101]
	v_mfma_f32_16x16x32_bf16 v[98:101], v[174:177], v[198:201], v[98:101]
	v_mfma_f32_16x16x32_bf16 v[86:89], v[146:149], v[202:205], v[86:89]
	v_mfma_f32_16x16x32_bf16 v[86:89], v[150:153], v[206:209], v[86:89]
	v_mfma_f32_16x16x32_bf16 v[82:85], v[170:173], v[202:205], v[82:85]
	v_mfma_f32_16x16x32_bf16 v[82:85], v[174:177], v[206:209], v[82:85]
	v_mfma_f32_16x16x32_bf16 v[70:73], v[146:149], v[210:213], v[70:73]
	v_mfma_f32_16x16x32_bf16 v[70:73], v[150:153], v[214:217], v[70:73]
	v_mfma_f32_16x16x32_bf16 v[66:69], v[170:173], v[210:213], v[66:69]
	v_mfma_f32_16x16x32_bf16 v[66:69], v[174:177], v[214:217], v[66:69]
	s_setprio 0
	s_barrier
	s_add_i32 s0, s54, s45
	v_lshl_add_u64 v[218:219], s[2:3], 0, v[156:157]
	s_mov_b32 m0, s0
	ds_read_b128 v[178:181], v188 offset:16384
	ds_read_b128 v[190:193], v188 offset:17408
	ds_read_b128 v[194:197], v188 offset:18432
	ds_read_b128 v[198:201], v188 offset:19456
	ds_read_b128 v[202:205], v188 offset:20480
	ds_read_b128 v[206:209], v188 offset:21504
	ds_read_b128 v[210:213], v188 offset:22528
	ds_read_b128 v[214:217], v188 offset:23552
	global_load_lds_dwordx4 v[218:219], off
	s_add_i32 m0, s0, 0x2000
	s_add_u32 s0, s2, 0x40000
	v_lshl_add_u64 v[220:221], s[2:3], 0, v[160:161]
	s_addc_u32 s1, s3, 0
	s_add_i32 s60, s55, s45
	global_load_lds_dwordx4 v[220:221], off
	v_lshl_add_u64 v[222:223], s[0:1], 0, v[156:157]
	s_mov_b32 m0, s60
	v_lshl_add_u64 v[224:225], s[40:41], 0, v[158:159]
	global_load_lds_dwordx4 v[222:223], off
	v_lshl_add_u64 v[222:223], s[0:1], 0, v[160:161]
	s_add_i32 m0, s60, 0x2000
	s_nop 0
	global_load_lds_dwordx4 v[222:223], off
	v_lshl_add_u64 v[222:223], s[40:41], 0, v[154:155]
	s_mov_b32 m0, s37
	s_nop 0
	global_load_lds_dwordx4 v[222:223], off
	s_mov_b32 m0, s46
	s_nop 0
	global_load_lds_dwordx4 v[224:225], off
	s_waitcnt vmcnt(8)
	s_waitcnt lgkmcnt(0)
	s_barrier
	s_setprio 1
	s_waitcnt lgkmcnt(0)
	v_mfma_f32_16x16x32_bf16 v[62:65], v[130:133], v[178:181], v[62:65]
	v_mfma_f32_16x16x32_bf16 v[62:65], v[134:137], v[190:193], v[62:65]
	v_mfma_f32_16x16x32_bf16 v[58:61], v[138:141], v[178:181], v[58:61]
	v_mfma_f32_16x16x32_bf16 v[58:61], v[142:145], v[190:193], v[58:61]
	v_mfma_f32_16x16x32_bf16 v[46:49], v[130:133], v[194:197], v[46:49]
	v_mfma_f32_16x16x32_bf16 v[46:49], v[134:137], v[198:201], v[46:49]
	v_mfma_f32_16x16x32_bf16 v[42:45], v[138:141], v[194:197], v[42:45]
	v_mfma_f32_16x16x32_bf16 v[42:45], v[142:145], v[198:201], v[42:45]
	v_mfma_f32_16x16x32_bf16 v[30:33], v[130:133], v[202:205], v[30:33]
	v_mfma_f32_16x16x32_bf16 v[30:33], v[134:137], v[206:209], v[30:33]
	v_mfma_f32_16x16x32_bf16 v[26:29], v[138:141], v[202:205], v[26:29]
	v_mfma_f32_16x16x32_bf16 v[26:29], v[142:145], v[206:209], v[26:29]
	v_mfma_f32_16x16x32_bf16 v[14:17], v[130:133], v[210:213], v[14:17]
	v_mfma_f32_16x16x32_bf16 v[14:17], v[134:137], v[214:217], v[14:17]
	v_mfma_f32_16x16x32_bf16 v[10:13], v[138:141], v[210:213], v[10:13]
	v_mfma_f32_16x16x32_bf16 v[10:13], v[142:145], v[214:217], v[10:13]
	s_setprio 0
	s_setprio 1
	v_mfma_f32_16x16x32_bf16 v[54:57], v[146:149], v[178:181], v[54:57]
	v_mfma_f32_16x16x32_bf16 v[54:57], v[150:153], v[190:193], v[54:57]
	v_mfma_f32_16x16x32_bf16 v[50:53], v[170:173], v[178:181], v[50:53]
	v_mfma_f32_16x16x32_bf16 v[50:53], v[174:177], v[190:193], v[50:53]
	v_mfma_f32_16x16x32_bf16 v[38:41], v[146:149], v[194:197], v[38:41]
	v_mfma_f32_16x16x32_bf16 v[38:41], v[150:153], v[198:201], v[38:41]
	v_mfma_f32_16x16x32_bf16 v[34:37], v[170:173], v[194:197], v[34:37]
	v_mfma_f32_16x16x32_bf16 v[34:37], v[174:177], v[198:201], v[34:37]
	v_mfma_f32_16x16x32_bf16 v[22:25], v[146:149], v[202:205], v[22:25]
	v_mfma_f32_16x16x32_bf16 v[22:25], v[150:153], v[206:209], v[22:25]
	v_mfma_f32_16x16x32_bf16 v[18:21], v[170:173], v[202:205], v[18:21]
	v_mfma_f32_16x16x32_bf16 v[18:21], v[174:177], v[206:209], v[18:21]
	v_mfma_f32_16x16x32_bf16 v[6:9], v[146:149], v[210:213], v[6:9]
	v_mfma_f32_16x16x32_bf16 v[6:9], v[150:153], v[214:217], v[6:9]
	v_mfma_f32_16x16x32_bf16 v[2:5], v[170:173], v[210:213], v[2:5]
	v_mfma_f32_16x16x32_bf16 v[2:5], v[174:177], v[214:217], v[2:5]
	s_setprio 0
	s_barrier
	s_add_i32 s60, 0, 0x18000
	s_add_i32 s61, 0, 0x1c000
	v_add_u32_e32 v142, s60, v182
	v_add_u32_e32 v174, s61, v182
	ds_read_b128 v[130:133], v142
	ds_read_b128 v[134:137], v142 offset:1024
	ds_read_b128 v[138:141], v142 offset:2048
	ds_read_b128 v[142:145], v142 offset:3072
	ds_read_b128 v[146:149], v174
	ds_read_b128 v[150:153], v174 offset:1024
	ds_read_b128 v[170:173], v174 offset:2048
	ds_read_b128 v[174:177], v174 offset:3072
	s_add_u32 s0, s40, 0x40000
	s_addc_u32 s1, s41, 0
	s_mov_b32 m0, s47
	v_lshl_add_u64 v[226:227], s[0:1], 0, v[154:155]
	ds_read_b128 v[178:181], v188 offset:32768
	ds_read_b128 v[190:193], v188 offset:33792
	ds_read_b128 v[194:197], v188 offset:34816
	ds_read_b128 v[198:201], v188 offset:35840
	ds_read_b128 v[202:205], v188 offset:36864
	ds_read_b128 v[206:209], v188 offset:37888
	ds_read_b128 v[210:213], v188 offset:38912
	ds_read_b128 v[214:217], v188 offset:39936
	global_load_lds_dwordx4 v[226:227], off
	v_lshl_add_u64 v[226:227], s[0:1], 0, v[158:159]
	s_mov_b32 m0, s48
	s_nop 0
	global_load_lds_dwordx4 v[226:227], off
	s_waitcnt vmcnt(8)
	s_waitcnt lgkmcnt(0)
	s_barrier
	s_setprio 1
	s_waitcnt lgkmcnt(0)
	v_mfma_f32_16x16x32_bf16 v[126:129], v[130:133], v[178:181], v[126:129]
	v_mfma_f32_16x16x32_bf16 v[126:129], v[134:137], v[190:193], v[126:129]
	v_mfma_f32_16x16x32_bf16 v[122:125], v[138:141], v[178:181], v[122:125]
	v_mfma_f32_16x16x32_bf16 v[122:125], v[142:145], v[190:193], v[122:125]
	v_mfma_f32_16x16x32_bf16 v[110:113], v[130:133], v[194:197], v[110:113]
	v_mfma_f32_16x16x32_bf16 v[110:113], v[134:137], v[198:201], v[110:113]
	v_mfma_f32_16x16x32_bf16 v[106:109], v[138:141], v[194:197], v[106:109]
	v_mfma_f32_16x16x32_bf16 v[106:109], v[142:145], v[198:201], v[106:109]
	v_mfma_f32_16x16x32_bf16 v[94:97], v[130:133], v[202:205], v[94:97]
	v_mfma_f32_16x16x32_bf16 v[94:97], v[134:137], v[206:209], v[94:97]
	v_mfma_f32_16x16x32_bf16 v[90:93], v[138:141], v[202:205], v[90:93]
	v_mfma_f32_16x16x32_bf16 v[90:93], v[142:145], v[206:209], v[90:93]
	v_mfma_f32_16x16x32_bf16 v[78:81], v[130:133], v[210:213], v[78:81]
	v_mfma_f32_16x16x32_bf16 v[78:81], v[134:137], v[214:217], v[78:81]
	v_mfma_f32_16x16x32_bf16 v[74:77], v[138:141], v[210:213], v[74:77]
	v_mfma_f32_16x16x32_bf16 v[74:77], v[142:145], v[214:217], v[74:77]
	s_setprio 0
	s_setprio 1
	v_mfma_f32_16x16x32_bf16 v[118:121], v[146:149], v[178:181], v[118:121]
	v_mfma_f32_16x16x32_bf16 v[118:121], v[150:153], v[190:193], v[118:121]
	v_mfma_f32_16x16x32_bf16 v[114:117], v[170:173], v[178:181], v[114:117]
	v_mfma_f32_16x16x32_bf16 v[114:117], v[174:177], v[190:193], v[114:117]
	v_mfma_f32_16x16x32_bf16 v[102:105], v[146:149], v[194:197], v[102:105]
	v_mfma_f32_16x16x32_bf16 v[102:105], v[150:153], v[198:201], v[102:105]
	v_mfma_f32_16x16x32_bf16 v[98:101], v[170:173], v[194:197], v[98:101]
	v_mfma_f32_16x16x32_bf16 v[98:101], v[174:177], v[198:201], v[98:101]
	v_mfma_f32_16x16x32_bf16 v[86:89], v[146:149], v[202:205], v[86:89]
	v_mfma_f32_16x16x32_bf16 v[86:89], v[150:153], v[206:209], v[86:89]
	v_mfma_f32_16x16x32_bf16 v[82:85], v[170:173], v[202:205], v[82:85]
	v_mfma_f32_16x16x32_bf16 v[82:85], v[174:177], v[206:209], v[82:85]
	v_mfma_f32_16x16x32_bf16 v[70:73], v[146:149], v[210:213], v[70:73]
	v_mfma_f32_16x16x32_bf16 v[70:73], v[150:153], v[214:217], v[70:73]
	v_mfma_f32_16x16x32_bf16 v[66:69], v[170:173], v[210:213], v[66:69]
	v_mfma_f32_16x16x32_bf16 v[66:69], v[174:177], v[214:217], v[66:69]
	s_setprio 0
	s_barrier
	s_add_i32 s0, s60, s45
	v_lshl_add_u64 v[218:219], v[218:219], 0, s[16:17]
	s_mov_b32 m0, s0
	ds_read_b128 v[178:181], v188 offset:49152
	ds_read_b128 v[190:193], v188 offset:50176
	ds_read_b128 v[194:197], v188 offset:51200
	ds_read_b128 v[198:201], v188 offset:52224
	ds_read_b128 v[202:205], v188 offset:53248
	ds_read_b128 v[206:209], v188 offset:54272
	ds_read_b128 v[210:213], v188 offset:55296
	ds_read_b128 v[214:217], v188 offset:56320
	global_load_lds_dwordx4 v[218:219], off
	s_add_i32 m0, s0, 0x2000
	s_add_u32 s0, s2, 0x40080
	v_lshl_add_u64 v[218:219], v[220:221], 0, s[16:17]
	s_addc_u32 s1, s3, 0
	s_add_i32 s2, s61, s45
	global_load_lds_dwordx4 v[218:219], off
	v_lshl_add_u64 v[218:219], s[0:1], 0, v[156:157]
	s_mov_b32 m0, s2
	s_nop 0
	global_load_lds_dwordx4 v[218:219], off
	v_lshl_add_u64 v[218:219], s[0:1], 0, v[160:161]
	s_add_i32 m0, s2, 0x2000
	s_nop 0
	global_load_lds_dwordx4 v[218:219], off
	v_lshl_add_u64 v[218:219], v[222:223], 0, s[16:17]
	s_mov_b32 m0, s50
	s_nop 0
	global_load_lds_dwordx4 v[218:219], off
	v_lshl_add_u64 v[218:219], v[224:225], 0, s[16:17]
	s_mov_b32 m0, s51
	s_nop 0
	global_load_lds_dwordx4 v[218:219], off
	s_waitcnt vmcnt(8)
	s_waitcnt lgkmcnt(0)
	s_barrier
	s_setprio 1
	s_waitcnt lgkmcnt(0)
	v_mfma_f32_16x16x32_bf16 v[62:65], v[130:133], v[178:181], v[62:65]
	v_mfma_f32_16x16x32_bf16 v[62:65], v[134:137], v[190:193], v[62:65]
	v_mfma_f32_16x16x32_bf16 v[58:61], v[138:141], v[178:181], v[58:61]
	v_mfma_f32_16x16x32_bf16 v[58:61], v[142:145], v[190:193], v[58:61]
	v_mfma_f32_16x16x32_bf16 v[46:49], v[130:133], v[194:197], v[46:49]
	v_mfma_f32_16x16x32_bf16 v[46:49], v[134:137], v[198:201], v[46:49]
	v_mfma_f32_16x16x32_bf16 v[42:45], v[138:141], v[194:197], v[42:45]
	v_mfma_f32_16x16x32_bf16 v[42:45], v[142:145], v[198:201], v[42:45]
	v_mfma_f32_16x16x32_bf16 v[30:33], v[130:133], v[202:205], v[30:33]
	v_mfma_f32_16x16x32_bf16 v[30:33], v[134:137], v[206:209], v[30:33]
	v_mfma_f32_16x16x32_bf16 v[26:29], v[138:141], v[202:205], v[26:29]
	v_mfma_f32_16x16x32_bf16 v[26:29], v[142:145], v[206:209], v[26:29]
	v_mfma_f32_16x16x32_bf16 v[14:17], v[130:133], v[210:213], v[14:17]
	v_mfma_f32_16x16x32_bf16 v[14:17], v[134:137], v[214:217], v[14:17]
	v_mfma_f32_16x16x32_bf16 v[10:13], v[138:141], v[210:213], v[10:13]
	v_mfma_f32_16x16x32_bf16 v[10:13], v[142:145], v[214:217], v[10:13]
	s_setprio 0
	s_setprio 1
	v_mfma_f32_16x16x32_bf16 v[54:57], v[146:149], v[178:181], v[54:57]
	v_mfma_f32_16x16x32_bf16 v[54:57], v[150:153], v[190:193], v[54:57]
	v_mfma_f32_16x16x32_bf16 v[50:53], v[170:173], v[178:181], v[50:53]
	v_mfma_f32_16x16x32_bf16 v[50:53], v[174:177], v[190:193], v[50:53]
	v_mfma_f32_16x16x32_bf16 v[38:41], v[146:149], v[194:197], v[38:41]
	v_mfma_f32_16x16x32_bf16 v[38:41], v[150:153], v[198:201], v[38:41]
	v_mfma_f32_16x16x32_bf16 v[34:37], v[170:173], v[194:197], v[34:37]
	v_mfma_f32_16x16x32_bf16 v[34:37], v[174:177], v[198:201], v[34:37]
	v_mfma_f32_16x16x32_bf16 v[22:25], v[146:149], v[202:205], v[22:25]
	v_mfma_f32_16x16x32_bf16 v[22:25], v[150:153], v[206:209], v[22:25]
	v_mfma_f32_16x16x32_bf16 v[18:21], v[170:173], v[202:205], v[18:21]
	v_mfma_f32_16x16x32_bf16 v[18:21], v[174:177], v[206:209], v[18:21]
	v_mfma_f32_16x16x32_bf16 v[6:9], v[146:149], v[210:213], v[6:9]
	v_mfma_f32_16x16x32_bf16 v[6:9], v[150:153], v[214:217], v[6:9]
	v_mfma_f32_16x16x32_bf16 v[2:5], v[170:173], v[210:213], v[2:5]
	v_mfma_f32_16x16x32_bf16 v[2:5], v[174:177], v[214:217], v[2:5]
	s_setprio 0
	s_barrier
	s_add_i32 s59, s59, 2
	s_add_u32 s38, s38, 0x100
	s_addc_u32 s39, s39, 0
	s_add_u32 s57, s57, 0x100
	s_addc_u32 s58, s58, 0
	s_cmp_gt_u32 s59, 13
	s_cbranch_scc0 .LBB0_2118
	s_and_b64 vcc, exec, s[18:19]
	s_cbranch_vccz .LBB0_2121
	s_barrier

.LBB0_2207:
	ds_read_b128 v[148:151], v165
	ds_read_b128 v[152:155], v165 offset:1024
	ds_read_b128 v[156:159], v165 offset:2048
	ds_read_b128 v[160:163], v165 offset:3072
	ds_read_b128 v[170:173], v166
	ds_read_b128 v[174:177], v166 offset:1024
	ds_read_b128 v[178:181], v166 offset:2048
	ds_read_b128 v[182:185], v166 offset:3072
	s_add_u32 s0, s28, 0xfffc0080
	s_addc_u32 s1, s29, -1
	s_cmp_eq_u32 s53, 12
	s_cselect_b32 s31, s21, s1
	s_cselect_b32 s30, s49, s0
	s_cselect_b32 s3, s19, s52
	s_cselect_b32 s2, s50, s51
	v_lshl_add_u64 v[218:219], s[28:29], 0, v[140:141]
	s_add_i32 m0, s27, 0xc000
	ds_read_b128 v[186:189], v167
	ds_read_b128 v[190:193], v167 offset:1024
	ds_read_b128 v[194:197], v167 offset:2048
	ds_read_b128 v[198:201], v167 offset:3072
	ds_read_b128 v[202:205], v167 offset:4096
	ds_read_b128 v[206:209], v167 offset:5120
	ds_read_b128 v[210:213], v167 offset:6144
	ds_read_b128 v[214:217], v167 offset:7168
	global_load_lds_dwordx4 v[218:219], off
	v_lshl_add_u64 v[218:219], s[28:29], 0, v[142:143]
	s_add_i32 m0, s27, 0xe000
	s_nop 0
	global_load_lds_dwordx4 v[218:219], off
	s_waitcnt vmcnt(8)
	s_waitcnt lgkmcnt(0)
	s_barrier
	s_setprio 1
	s_waitcnt lgkmcnt(0)
	v_mfma_f32_16x16x32_bf16 v[126:129], v[148:151], v[186:189], v[126:129]
	v_mfma_f32_16x16x32_bf16 v[126:129], v[152:155], v[190:193], v[126:129]
	v_mfma_f32_16x16x32_bf16 v[118:121], v[156:159], v[186:189], v[118:121]
	v_mfma_f32_16x16x32_bf16 v[118:121], v[160:163], v[190:193], v[118:121]
	v_mfma_f32_16x16x32_bf16 v[110:113], v[148:151], v[194:197], v[110:113]
	v_mfma_f32_16x16x32_bf16 v[110:113], v[152:155], v[198:201], v[110:113]
	v_mfma_f32_16x16x32_bf16 v[102:105], v[156:159], v[194:197], v[102:105]
	v_mfma_f32_16x16x32_bf16 v[102:105], v[160:163], v[198:201], v[102:105]
	v_mfma_f32_16x16x32_bf16 v[94:97], v[148:151], v[202:205], v[94:97]
	v_mfma_f32_16x16x32_bf16 v[94:97], v[152:155], v[206:209], v[94:97]
	v_mfma_f32_16x16x32_bf16 v[86:89], v[156:159], v[202:205], v[86:89]
	v_mfma_f32_16x16x32_bf16 v[86:89], v[160:163], v[206:209], v[86:89]
	v_mfma_f32_16x16x32_bf16 v[78:81], v[148:151], v[210:213], v[78:81]
	v_mfma_f32_16x16x32_bf16 v[78:81], v[152:155], v[214:217], v[78:81]
	v_mfma_f32_16x16x32_bf16 v[70:73], v[156:159], v[210:213], v[70:73]
	v_mfma_f32_16x16x32_bf16 v[70:73], v[160:163], v[214:217], v[70:73]
	s_setprio 0
	s_setprio 1
	v_mfma_f32_16x16x32_bf16 v[122:125], v[170:173], v[186:189], v[122:125]
	v_mfma_f32_16x16x32_bf16 v[122:125], v[174:177], v[190:193], v[122:125]
	v_mfma_f32_16x16x32_bf16 v[114:117], v[178:181], v[186:189], v[114:117]
	v_mfma_f32_16x16x32_bf16 v[114:117], v[182:185], v[190:193], v[114:117]
	v_mfma_f32_16x16x32_bf16 v[106:109], v[170:173], v[194:197], v[106:109]
	v_mfma_f32_16x16x32_bf16 v[106:109], v[174:177], v[198:201], v[106:109]
	v_mfma_f32_16x16x32_bf16 v[98:101], v[178:181], v[194:197], v[98:101]
	v_mfma_f32_16x16x32_bf16 v[98:101], v[182:185], v[198:201], v[98:101]
	v_mfma_f32_16x16x32_bf16 v[90:93], v[170:173], v[202:205], v[90:93]
	v_mfma_f32_16x16x32_bf16 v[90:93], v[174:177], v[206:209], v[90:93]
	v_mfma_f32_16x16x32_bf16 v[82:85], v[178:181], v[202:205], v[82:85]
	v_mfma_f32_16x16x32_bf16 v[82:85], v[182:185], v[206:209], v[82:85]
	v_mfma_f32_16x16x32_bf16 v[74:77], v[170:173], v[210:213], v[74:77]
	v_mfma_f32_16x16x32_bf16 v[74:77], v[174:177], v[214:217], v[74:77]
	v_mfma_f32_16x16x32_bf16 v[66:69], v[178:181], v[210:213], v[66:69]
	v_mfma_f32_16x16x32_bf16 v[66:69], v[182:185], v[214:217], v[66:69]
	s_setprio 0
	s_barrier
	s_add_i32 s0, s44, s35
	v_lshl_add_u64 v[218:219], s[2:3], 0, v[134:135]
	s_mov_b32 m0, s0
	ds_read_b128 v[186:189], v167 offset:16384
	ds_read_b128 v[190:193], v167 offset:17408
	ds_read_b128 v[194:197], v167 offset:18432
	ds_read_b128 v[198:201], v167 offset:19456
	ds_read_b128 v[202:205], v167 offset:20480
	ds_read_b128 v[206:209], v167 offset:21504
	ds_read_b128 v[210:213], v167 offset:22528
	ds_read_b128 v[214:217], v167 offset:23552
	global_load_lds_dwordx4 v[218:219], off
	s_add_i32 m0, s0, 0x2000
	s_add_u32 s0, s2, 0x40000
	v_lshl_add_u64 v[220:221], s[2:3], 0, v[130:131]
	s_addc_u32 s1, s3, 0
	s_add_i32 s54, s45, s35
	global_load_lds_dwordx4 v[220:221], off
	v_lshl_add_u64 v[222:223], s[0:1], 0, v[134:135]
	s_mov_b32 m0, s54
	v_lshl_add_u64 v[224:225], s[30:31], 0, v[132:133]
	global_load_lds_dwordx4 v[222:223], off
	v_lshl_add_u64 v[222:223], s[0:1], 0, v[130:131]
	s_add_i32 m0, s54, 0x2000
	s_nop 0
	global_load_lds_dwordx4 v[222:223], off
	v_lshl_add_u64 v[222:223], s[30:31], 0, v[136:137]
	s_mov_b32 m0, s27
	s_nop 0
	global_load_lds_dwordx4 v[222:223], off
	s_mov_b32 m0, s38
	s_nop 0
	global_load_lds_dwordx4 v[224:225], off
	s_waitcnt vmcnt(8)
	s_waitcnt lgkmcnt(0)
	s_barrier
	s_setprio 1
	s_waitcnt lgkmcnt(0)
	v_mfma_f32_16x16x32_bf16 v[62:65], v[148:151], v[186:189], v[62:65]
	v_mfma_f32_16x16x32_bf16 v[62:65], v[152:155], v[190:193], v[62:65]
	v_mfma_f32_16x16x32_bf16 v[54:57], v[156:159], v[186:189], v[54:57]
	v_mfma_f32_16x16x32_bf16 v[54:57], v[160:163], v[190:193], v[54:57]
	v_mfma_f32_16x16x32_bf16 v[46:49], v[148:151], v[194:197], v[46:49]
	v_mfma_f32_16x16x32_bf16 v[46:49], v[152:155], v[198:201], v[46:49]
	v_mfma_f32_16x16x32_bf16 v[38:41], v[156:159], v[194:197], v[38:41]
	v_mfma_f32_16x16x32_bf16 v[38:41], v[160:163], v[198:201], v[38:41]
	v_mfma_f32_16x16x32_bf16 v[30:33], v[148:151], v[202:205], v[30:33]
	v_mfma_f32_16x16x32_bf16 v[30:33], v[152:155], v[206:209], v[30:33]
	v_mfma_f32_16x16x32_bf16 v[22:25], v[156:159], v[202:205], v[22:25]
	v_mfma_f32_16x16x32_bf16 v[22:25], v[160:163], v[206:209], v[22:25]
	v_mfma_f32_16x16x32_bf16 v[14:17], v[148:151], v[210:213], v[14:17]
	v_mfma_f32_16x16x32_bf16 v[14:17], v[152:155], v[214:217], v[14:17]
	v_mfma_f32_16x16x32_bf16 v[6:9], v[156:159], v[210:213], v[6:9]
	v_mfma_f32_16x16x32_bf16 v[6:9], v[160:163], v[214:217], v[6:9]
	s_setprio 0
	s_setprio 1
	v_mfma_f32_16x16x32_bf16 v[58:61], v[170:173], v[186:189], v[58:61]
	v_mfma_f32_16x16x32_bf16 v[58:61], v[174:177], v[190:193], v[58:61]
	v_mfma_f32_16x16x32_bf16 v[50:53], v[178:181], v[186:189], v[50:53]
	v_mfma_f32_16x16x32_bf16 v[50:53], v[182:185], v[190:193], v[50:53]
	v_mfma_f32_16x16x32_bf16 v[42:45], v[170:173], v[194:197], v[42:45]
	v_mfma_f32_16x16x32_bf16 v[42:45], v[174:177], v[198:201], v[42:45]
	v_mfma_f32_16x16x32_bf16 v[34:37], v[178:181], v[194:197], v[34:37]
	v_mfma_f32_16x16x32_bf16 v[34:37], v[182:185], v[198:201], v[34:37]
	v_mfma_f32_16x16x32_bf16 v[26:29], v[170:173], v[202:205], v[26:29]
	v_mfma_f32_16x16x32_bf16 v[26:29], v[174:177], v[206:209], v[26:29]
	v_mfma_f32_16x16x32_bf16 v[18:21], v[178:181], v[202:205], v[18:21]
	v_mfma_f32_16x16x32_bf16 v[18:21], v[182:185], v[206:209], v[18:21]
	v_mfma_f32_16x16x32_bf16 v[10:13], v[170:173], v[210:213], v[10:13]
	v_mfma_f32_16x16x32_bf16 v[10:13], v[174:177], v[214:217], v[10:13]
	v_mfma_f32_16x16x32_bf16 v[2:5], v[178:181], v[210:213], v[2:5]
	v_mfma_f32_16x16x32_bf16 v[2:5], v[182:185], v[214:217], v[2:5]
	s_setprio 0
	s_barrier
	s_add_i32 s54, 0, 0x18000
	s_add_i32 s55, 0, 0x1c000
	v_add_u32_e32 v160, s54, v164
	v_add_u32_e32 v169, s55, v164
	ds_read_b128 v[148:151], v160
	ds_read_b128 v[152:155], v160 offset:1024
	ds_read_b128 v[156:159], v160 offset:2048
	ds_read_b128 v[160:163], v160 offset:3072
	ds_read_b128 v[170:173], v169
	ds_read_b128 v[174:177], v169 offset:1024
	ds_read_b128 v[178:181], v169 offset:2048
	ds_read_b128 v[182:185], v169 offset:3072
	s_add_u32 s0, s30, 0x40000
	s_addc_u32 s1, s31, 0
	s_mov_b32 m0, s39
	v_lshl_add_u64 v[226:227], s[0:1], 0, v[136:137]
	ds_read_b128 v[186:189], v167 offset:32768
	ds_read_b128 v[190:193], v167 offset:33792
	ds_read_b128 v[194:197], v167 offset:34816
	ds_read_b128 v[198:201], v167 offset:35840
	ds_read_b128 v[202:205], v167 offset:36864
	ds_read_b128 v[206:209], v167 offset:37888
	ds_read_b128 v[210:213], v167 offset:38912
	ds_read_b128 v[214:217], v167 offset:39936
	global_load_lds_dwordx4 v[226:227], off
	v_lshl_add_u64 v[226:227], s[0:1], 0, v[132:133]
	s_mov_b32 m0, s40
	s_nop 0
	global_load_lds_dwordx4 v[226:227], off
	s_waitcnt vmcnt(8)
	s_waitcnt lgkmcnt(0)
	s_barrier
	s_setprio 1
	s_waitcnt lgkmcnt(0)
	v_mfma_f32_16x16x32_bf16 v[126:129], v[148:151], v[186:189], v[126:129]
	v_mfma_f32_16x16x32_bf16 v[126:129], v[152:155], v[190:193], v[126:129]
	v_mfma_f32_16x16x32_bf16 v[118:121], v[156:159], v[186:189], v[118:121]
	v_mfma_f32_16x16x32_bf16 v[118:121], v[160:163], v[190:193], v[118:121]
	v_mfma_f32_16x16x32_bf16 v[110:113], v[148:151], v[194:197], v[110:113]
	v_mfma_f32_16x16x32_bf16 v[110:113], v[152:155], v[198:201], v[110:113]
	v_mfma_f32_16x16x32_bf16 v[102:105], v[156:159], v[194:197], v[102:105]
	v_mfma_f32_16x16x32_bf16 v[102:105], v[160:163], v[198:201], v[102:105]
	v_mfma_f32_16x16x32_bf16 v[94:97], v[148:151], v[202:205], v[94:97]
	v_mfma_f32_16x16x32_bf16 v[94:97], v[152:155], v[206:209], v[94:97]
	v_mfma_f32_16x16x32_bf16 v[86:89], v[156:159], v[202:205], v[86:89]
	v_mfma_f32_16x16x32_bf16 v[86:89], v[160:163], v[206:209], v[86:89]
	v_mfma_f32_16x16x32_bf16 v[78:81], v[148:151], v[210:213], v[78:81]
	v_mfma_f32_16x16x32_bf16 v[78:81], v[152:155], v[214:217], v[78:81]
	v_mfma_f32_16x16x32_bf16 v[70:73], v[156:159], v[210:213], v[70:73]
	v_mfma_f32_16x16x32_bf16 v[70:73], v[160:163], v[214:217], v[70:73]
	s_setprio 0
	s_setprio 1
	v_mfma_f32_16x16x32_bf16 v[122:125], v[170:173], v[186:189], v[122:125]
	v_mfma_f32_16x16x32_bf16 v[122:125], v[174:177], v[190:193], v[122:125]
	v_mfma_f32_16x16x32_bf16 v[114:117], v[178:181], v[186:189], v[114:117]
	v_mfma_f32_16x16x32_bf16 v[114:117], v[182:185], v[190:193], v[114:117]
	v_mfma_f32_16x16x32_bf16 v[106:109], v[170:173], v[194:197], v[106:109]
	v_mfma_f32_16x16x32_bf16 v[106:109], v[174:177], v[198:201], v[106:109]
	v_mfma_f32_16x16x32_bf16 v[98:101], v[178:181], v[194:197], v[98:101]
	v_mfma_f32_16x16x32_bf16 v[98:101], v[182:185], v[198:201], v[98:101]
	v_mfma_f32_16x16x32_bf16 v[90:93], v[170:173], v[202:205], v[90:93]
	v_mfma_f32_16x16x32_bf16 v[90:93], v[174:177], v[206:209], v[90:93]
	v_mfma_f32_16x16x32_bf16 v[82:85], v[178:181], v[202:205], v[82:85]
	v_mfma_f32_16x16x32_bf16 v[82:85], v[182:185], v[206:209], v[82:85]
	v_mfma_f32_16x16x32_bf16 v[74:77], v[170:173], v[210:213], v[74:77]
	v_mfma_f32_16x16x32_bf16 v[74:77], v[174:177], v[214:217], v[74:77]
	v_mfma_f32_16x16x32_bf16 v[66:69], v[178:181], v[210:213], v[66:69]
	v_mfma_f32_16x16x32_bf16 v[66:69], v[182:185], v[214:217], v[66:69]
	s_setprio 0
	s_barrier
	s_add_i32 s0, s54, s35
	v_lshl_add_u64 v[218:219], v[218:219], 0, s[14:15]
	s_mov_b32 m0, s0
	ds_read_b128 v[186:189], v167 offset:49152
	ds_read_b128 v[190:193], v167 offset:50176
	ds_read_b128 v[194:197], v167 offset:51200
	ds_read_b128 v[198:201], v167 offset:52224
	ds_read_b128 v[202:205], v167 offset:53248
	ds_read_b128 v[206:209], v167 offset:54272
	ds_read_b128 v[210:213], v167 offset:55296
	ds_read_b128 v[214:217], v167 offset:56320
	global_load_lds_dwordx4 v[218:219], off
	s_add_i32 m0, s0, 0x2000
	s_add_u32 s0, s2, 0x40080
	v_lshl_add_u64 v[218:219], v[220:221], 0, s[14:15]
	s_addc_u32 s1, s3, 0
	s_add_i32 s2, s55, s35
	global_load_lds_dwordx4 v[218:219], off
	v_lshl_add_u64 v[218:219], s[0:1], 0, v[134:135]
	s_mov_b32 m0, s2
	s_nop 0
	global_load_lds_dwordx4 v[218:219], off
	v_lshl_add_u64 v[218:219], s[0:1], 0, v[130:131]
	s_add_i32 m0, s2, 0x2000
	s_nop 0
	global_load_lds_dwordx4 v[218:219], off
	v_lshl_add_u64 v[218:219], v[222:223], 0, s[14:15]
	s_mov_b32 m0, s41
	s_nop 0
	global_load_lds_dwordx4 v[218:219], off
	v_lshl_add_u64 v[218:219], v[224:225], 0, s[14:15]
	s_mov_b32 m0, s42
	s_nop 0
	global_load_lds_dwordx4 v[218:219], off
	s_waitcnt vmcnt(8)
	s_waitcnt lgkmcnt(0)
	s_barrier
	s_setprio 1
	s_waitcnt lgkmcnt(0)
	v_mfma_f32_16x16x32_bf16 v[62:65], v[148:151], v[186:189], v[62:65]
	v_mfma_f32_16x16x32_bf16 v[62:65], v[152:155], v[190:193], v[62:65]
	v_mfma_f32_16x16x32_bf16 v[54:57], v[156:159], v[186:189], v[54:57]
	v_mfma_f32_16x16x32_bf16 v[54:57], v[160:163], v[190:193], v[54:57]
	v_mfma_f32_16x16x32_bf16 v[46:49], v[148:151], v[194:197], v[46:49]
	v_mfma_f32_16x16x32_bf16 v[46:49], v[152:155], v[198:201], v[46:49]
	v_mfma_f32_16x16x32_bf16 v[38:41], v[156:159], v[194:197], v[38:41]
	v_mfma_f32_16x16x32_bf16 v[38:41], v[160:163], v[198:201], v[38:41]
	v_mfma_f32_16x16x32_bf16 v[30:33], v[148:151], v[202:205], v[30:33]
	v_mfma_f32_16x16x32_bf16 v[30:33], v[152:155], v[206:209], v[30:33]
	v_mfma_f32_16x16x32_bf16 v[22:25], v[156:159], v[202:205], v[22:25]
	v_mfma_f32_16x16x32_bf16 v[22:25], v[160:163], v[206:209], v[22:25]
	v_mfma_f32_16x16x32_bf16 v[14:17], v[148:151], v[210:213], v[14:17]
	v_mfma_f32_16x16x32_bf16 v[14:17], v[152:155], v[214:217], v[14:17]
	v_mfma_f32_16x16x32_bf16 v[6:9], v[156:159], v[210:213], v[6:9]
	v_mfma_f32_16x16x32_bf16 v[6:9], v[160:163], v[214:217], v[6:9]
	s_setprio 0
	s_setprio 1
	v_mfma_f32_16x16x32_bf16 v[58:61], v[170:173], v[186:189], v[58:61]
	v_mfma_f32_16x16x32_bf16 v[58:61], v[174:177], v[190:193], v[58:61]
	v_mfma_f32_16x16x32_bf16 v[50:53], v[178:181], v[186:189], v[50:53]
	v_mfma_f32_16x16x32_bf16 v[50:53], v[182:185], v[190:193], v[50:53]
	v_mfma_f32_16x16x32_bf16 v[42:45], v[170:173], v[194:197], v[42:45]
	v_mfma_f32_16x16x32_bf16 v[42:45], v[174:177], v[198:201], v[42:45]
	v_mfma_f32_16x16x32_bf16 v[34:37], v[178:181], v[194:197], v[34:37]
	v_mfma_f32_16x16x32_bf16 v[34:37], v[182:185], v[198:201], v[34:37]
	v_mfma_f32_16x16x32_bf16 v[26:29], v[170:173], v[202:205], v[26:29]
	v_mfma_f32_16x16x32_bf16 v[26:29], v[174:177], v[206:209], v[26:29]
	v_mfma_f32_16x16x32_bf16 v[18:21], v[178:181], v[202:205], v[18:21]
	v_mfma_f32_16x16x32_bf16 v[18:21], v[182:185], v[206:209], v[18:21]
	v_mfma_f32_16x16x32_bf16 v[10:13], v[170:173], v[210:213], v[10:13]
	v_mfma_f32_16x16x32_bf16 v[10:13], v[174:177], v[214:217], v[10:13]
	v_mfma_f32_16x16x32_bf16 v[2:5], v[178:181], v[210:213], v[2:5]
	v_mfma_f32_16x16x32_bf16 v[2:5], v[182:185], v[214:217], v[2:5]
	s_setprio 0
	s_barrier
	s_add_i32 s53, s53, 2
	s_add_u32 s28, s28, 0x100
	s_addc_u32 s29, s29, 0
	s_add_u32 s51, s51, 0x100
	s_addc_u32 s52, s52, 0
	s_cmp_gt_u32 s53, 13
	s_cbranch_scc0 .LBB0_2207
	s_and_b64 vcc, exec, s[16:17]
	s_cbranch_vccz .LBB0_2210
	s_barrier

.LBB0_2290:
	ds_read_b128 v[144:147], v153
	ds_read_b128 v[156:159], v153 offset:1024
	ds_read_b128 v[160:163], v153 offset:2048
	ds_read_b128 v[164:167], v153 offset:3072
	ds_read_b128 v[168:171], v154
	ds_read_b128 v[172:175], v154 offset:1024
	ds_read_b128 v[176:179], v154 offset:2048
	ds_read_b128 v[180:183], v154 offset:3072
	s_add_u32 s2, s16, 0xfff50080
	s_addc_u32 s3, s17, -1
	s_cmp_eq_u32 s43, 40
	s_cselect_b32 s19, s5, s3
	s_cselect_b32 s18, s4, s2
	s_cselect_b32 s3, s15, s42
	s_cselect_b32 s2, s14, s41
	v_lshl_add_u64 v[148:149], s[16:17], 0, v[136:137]
	s_add_i32 m0, s26, 0xc000
	ds_read_b128 v[184:187], v155
	ds_read_b128 v[188:191], v155 offset:1024
	ds_read_b128 v[192:195], v155 offset:2048
	ds_read_b128 v[196:199], v155 offset:3072
	ds_read_b128 v[200:203], v155 offset:4096
	ds_read_b128 v[204:207], v155 offset:5120
	ds_read_b128 v[208:211], v155 offset:6144
	ds_read_b128 v[212:215], v155 offset:7168
	global_load_lds_dwordx4 v[148:149], off
	v_lshl_add_u64 v[148:149], s[16:17], 0, v[138:139]
	s_add_i32 m0, s26, 0xe000
	s_nop 0
	global_load_lds_dwordx4 v[148:149], off
	s_waitcnt vmcnt(8)
	s_waitcnt lgkmcnt(0)
	s_barrier
	s_setprio 1
	s_waitcnt lgkmcnt(0)
	v_mfma_f32_16x16x32_bf16 v[124:127], v[144:147], v[184:187], v[124:127]
	v_mfma_f32_16x16x32_bf16 v[124:127], v[156:159], v[188:191], v[124:127]
	v_mfma_f32_16x16x32_bf16 v[120:123], v[160:163], v[184:187], v[120:123]
	v_mfma_f32_16x16x32_bf16 v[120:123], v[164:167], v[188:191], v[120:123]
	v_mfma_f32_16x16x32_bf16 v[112:115], v[144:147], v[192:195], v[112:115]
	v_mfma_f32_16x16x32_bf16 v[112:115], v[156:159], v[196:199], v[112:115]
	v_mfma_f32_16x16x32_bf16 v[104:107], v[160:163], v[192:195], v[104:107]
	v_mfma_f32_16x16x32_bf16 v[104:107], v[164:167], v[196:199], v[104:107]
	v_mfma_f32_16x16x32_bf16 v[96:99], v[144:147], v[200:203], v[96:99]
	v_mfma_f32_16x16x32_bf16 v[96:99], v[156:159], v[204:207], v[96:99]
	v_mfma_f32_16x16x32_bf16 v[88:91], v[160:163], v[200:203], v[88:91]
	v_mfma_f32_16x16x32_bf16 v[88:91], v[164:167], v[204:207], v[88:91]
	v_mfma_f32_16x16x32_bf16 v[80:83], v[144:147], v[208:211], v[80:83]
	v_mfma_f32_16x16x32_bf16 v[80:83], v[156:159], v[212:215], v[80:83]
	v_mfma_f32_16x16x32_bf16 v[72:75], v[160:163], v[208:211], v[72:75]
	v_mfma_f32_16x16x32_bf16 v[72:75], v[164:167], v[212:215], v[72:75]
	s_setprio 0
	s_setprio 1
	v_mfma_f32_16x16x32_bf16 v[116:119], v[168:171], v[184:187], v[116:119]
	v_mfma_f32_16x16x32_bf16 v[116:119], v[172:175], v[188:191], v[116:119]
	v_mfma_f32_16x16x32_bf16 v[108:111], v[176:179], v[184:187], v[108:111]
	v_mfma_f32_16x16x32_bf16 v[108:111], v[180:183], v[188:191], v[108:111]
	v_mfma_f32_16x16x32_bf16 v[100:103], v[168:171], v[192:195], v[100:103]
	v_mfma_f32_16x16x32_bf16 v[100:103], v[172:175], v[196:199], v[100:103]
	v_mfma_f32_16x16x32_bf16 v[92:95], v[176:179], v[192:195], v[92:95]
	v_mfma_f32_16x16x32_bf16 v[92:95], v[180:183], v[196:199], v[92:95]
	v_mfma_f32_16x16x32_bf16 v[84:87], v[168:171], v[200:203], v[84:87]
	v_mfma_f32_16x16x32_bf16 v[84:87], v[172:175], v[204:207], v[84:87]
	v_mfma_f32_16x16x32_bf16 v[76:79], v[176:179], v[200:203], v[76:79]
	v_mfma_f32_16x16x32_bf16 v[76:79], v[180:183], v[204:207], v[76:79]
	v_mfma_f32_16x16x32_bf16 v[68:71], v[168:171], v[208:211], v[68:71]
	v_mfma_f32_16x16x32_bf16 v[68:71], v[172:175], v[212:215], v[68:71]
	v_mfma_f32_16x16x32_bf16 v[64:67], v[176:179], v[208:211], v[64:67]
	v_mfma_f32_16x16x32_bf16 v[64:67], v[180:183], v[212:215], v[64:67]
	s_setprio 0
	s_barrier
	s_add_i32 s44, s35, s25
	v_lshl_add_u64 v[148:149], s[2:3], 0, v[130:131]
	s_mov_b32 m0, s44
	ds_read_b128 v[184:187], v155 offset:16384
	ds_read_b128 v[188:191], v155 offset:17408
	ds_read_b128 v[192:195], v155 offset:18432
	ds_read_b128 v[196:199], v155 offset:19456
	ds_read_b128 v[200:203], v155 offset:20480
	ds_read_b128 v[204:207], v155 offset:21504
	ds_read_b128 v[208:211], v155 offset:22528
	ds_read_b128 v[212:215], v155 offset:23552
	global_load_lds_dwordx4 v[148:149], off
	s_add_i32 m0, s44, 0x2000
	s_add_u32 s44, s2, 0xb0000
	v_lshl_add_u64 v[216:217], s[2:3], 0, v[134:135]
	s_addc_u32 s45, s3, 0
	s_add_i32 s46, s36, s25
	global_load_lds_dwordx4 v[216:217], off
	v_lshl_add_u64 v[218:219], s[44:45], 0, v[130:131]
	s_mov_b32 m0, s46
	v_lshl_add_u64 v[220:221], s[18:19], 0, v[132:133]
	global_load_lds_dwordx4 v[218:219], off
	v_lshl_add_u64 v[218:219], s[44:45], 0, v[134:135]
	s_add_i32 m0, s46, 0x2000
	s_nop 0
	global_load_lds_dwordx4 v[218:219], off
	v_lshl_add_u64 v[218:219], s[18:19], 0, v[128:129]
	s_mov_b32 m0, s26
	s_nop 0
	global_load_lds_dwordx4 v[218:219], off
	s_mov_b32 m0, s27
	s_nop 0
	global_load_lds_dwordx4 v[220:221], off
	s_waitcnt vmcnt(8)
	s_waitcnt lgkmcnt(0)
	s_barrier
	s_setprio 1
	s_waitcnt lgkmcnt(0)
	v_mfma_f32_16x16x32_bf16 v[60:63], v[144:147], v[184:187], v[60:63]
	v_mfma_f32_16x16x32_bf16 v[60:63], v[156:159], v[188:191], v[60:63]
	v_mfma_f32_16x16x32_bf16 v[56:59], v[160:163], v[184:187], v[56:59]
	v_mfma_f32_16x16x32_bf16 v[56:59], v[164:167], v[188:191], v[56:59]
	v_mfma_f32_16x16x32_bf16 v[48:51], v[144:147], v[192:195], v[48:51]
	v_mfma_f32_16x16x32_bf16 v[48:51], v[156:159], v[196:199], v[48:51]
	v_mfma_f32_16x16x32_bf16 v[40:43], v[160:163], v[192:195], v[40:43]
	v_mfma_f32_16x16x32_bf16 v[40:43], v[164:167], v[196:199], v[40:43]
	v_mfma_f32_16x16x32_bf16 v[32:35], v[144:147], v[200:203], v[32:35]
	v_mfma_f32_16x16x32_bf16 v[32:35], v[156:159], v[204:207], v[32:35]
	v_mfma_f32_16x16x32_bf16 v[24:27], v[160:163], v[200:203], v[24:27]
	v_mfma_f32_16x16x32_bf16 v[24:27], v[164:167], v[204:207], v[24:27]
	v_mfma_f32_16x16x32_bf16 v[16:19], v[144:147], v[208:211], v[16:19]
	v_mfma_f32_16x16x32_bf16 v[16:19], v[156:159], v[212:215], v[16:19]
	v_mfma_f32_16x16x32_bf16 v[8:11], v[160:163], v[208:211], v[8:11]
	v_mfma_f32_16x16x32_bf16 v[8:11], v[164:167], v[212:215], v[8:11]
	s_setprio 0
	s_setprio 1
	v_mfma_f32_16x16x32_bf16 v[52:55], v[168:171], v[184:187], v[52:55]
	v_mfma_f32_16x16x32_bf16 v[52:55], v[172:175], v[188:191], v[52:55]
	v_mfma_f32_16x16x32_bf16 v[44:47], v[176:179], v[184:187], v[44:47]
	v_mfma_f32_16x16x32_bf16 v[44:47], v[180:183], v[188:191], v[44:47]
	v_mfma_f32_16x16x32_bf16 v[36:39], v[168:171], v[192:195], v[36:39]
	v_mfma_f32_16x16x32_bf16 v[36:39], v[172:175], v[196:199], v[36:39]
	v_mfma_f32_16x16x32_bf16 v[28:31], v[176:179], v[192:195], v[28:31]
	v_mfma_f32_16x16x32_bf16 v[28:31], v[180:183], v[196:199], v[28:31]
	v_mfma_f32_16x16x32_bf16 v[20:23], v[168:171], v[200:203], v[20:23]
	v_mfma_f32_16x16x32_bf16 v[20:23], v[172:175], v[204:207], v[20:23]
	v_mfma_f32_16x16x32_bf16 v[12:15], v[176:179], v[200:203], v[12:15]
	v_mfma_f32_16x16x32_bf16 v[12:15], v[180:183], v[204:207], v[12:15]
	v_mfma_f32_16x16x32_bf16 v[4:7], v[168:171], v[208:211], v[4:7]
	v_mfma_f32_16x16x32_bf16 v[4:7], v[172:175], v[212:215], v[4:7]
	v_mfma_f32_16x16x32_bf16 v[0:3], v[176:179], v[208:211], v[0:3]
	v_mfma_f32_16x16x32_bf16 v[0:3], v[180:183], v[212:215], v[0:3]
	s_setprio 0
	s_barrier
	s_add_i32 s44, 0, 0x18000
	s_add_i32 s45, 0, 0x1c000
	v_add_u32_e32 v164, s44, v151
	v_add_u32_e32 v180, s45, v151
	ds_read_b128 v[144:147], v164
	ds_read_b128 v[156:159], v164 offset:1024
	ds_read_b128 v[160:163], v164 offset:2048
	ds_read_b128 v[164:167], v164 offset:3072
	ds_read_b128 v[168:171], v180
	ds_read_b128 v[172:175], v180 offset:1024
	ds_read_b128 v[176:179], v180 offset:2048
	ds_read_b128 v[180:183], v180 offset:3072
	s_add_u32 s18, s18, 0xb0000
	s_addc_u32 s19, s19, 0
	s_mov_b32 m0, s28
	v_lshl_add_u64 v[222:223], s[18:19], 0, v[128:129]
	ds_read_b128 v[184:187], v155 offset:32768
	ds_read_b128 v[188:191], v155 offset:33792
	ds_read_b128 v[192:195], v155 offset:34816
	ds_read_b128 v[196:199], v155 offset:35840
	ds_read_b128 v[200:203], v155 offset:36864
	ds_read_b128 v[204:207], v155 offset:37888
	ds_read_b128 v[208:211], v155 offset:38912
	ds_read_b128 v[212:215], v155 offset:39936
	global_load_lds_dwordx4 v[222:223], off
	v_lshl_add_u64 v[222:223], s[18:19], 0, v[132:133]
	s_mov_b32 m0, s29
	s_nop 0
	global_load_lds_dwordx4 v[222:223], off
	s_waitcnt vmcnt(8)
	s_waitcnt lgkmcnt(0)
	s_barrier
	s_setprio 1
	s_waitcnt lgkmcnt(0)
	v_mfma_f32_16x16x32_bf16 v[124:127], v[144:147], v[184:187], v[124:127]
	v_mfma_f32_16x16x32_bf16 v[124:127], v[156:159], v[188:191], v[124:127]
	v_mfma_f32_16x16x32_bf16 v[120:123], v[160:163], v[184:187], v[120:123]
	v_mfma_f32_16x16x32_bf16 v[120:123], v[164:167], v[188:191], v[120:123]
	v_mfma_f32_16x16x32_bf16 v[112:115], v[144:147], v[192:195], v[112:115]
	v_mfma_f32_16x16x32_bf16 v[112:115], v[156:159], v[196:199], v[112:115]
	v_mfma_f32_16x16x32_bf16 v[104:107], v[160:163], v[192:195], v[104:107]
	v_mfma_f32_16x16x32_bf16 v[104:107], v[164:167], v[196:199], v[104:107]
	v_mfma_f32_16x16x32_bf16 v[96:99], v[144:147], v[200:203], v[96:99]
	v_mfma_f32_16x16x32_bf16 v[96:99], v[156:159], v[204:207], v[96:99]
	v_mfma_f32_16x16x32_bf16 v[88:91], v[160:163], v[200:203], v[88:91]
	v_mfma_f32_16x16x32_bf16 v[88:91], v[164:167], v[204:207], v[88:91]
	v_mfma_f32_16x16x32_bf16 v[80:83], v[144:147], v[208:211], v[80:83]
	v_mfma_f32_16x16x32_bf16 v[80:83], v[156:159], v[212:215], v[80:83]
	v_mfma_f32_16x16x32_bf16 v[72:75], v[160:163], v[208:211], v[72:75]
	v_mfma_f32_16x16x32_bf16 v[72:75], v[164:167], v[212:215], v[72:75]
	s_setprio 0
	s_setprio 1
	v_mfma_f32_16x16x32_bf16 v[116:119], v[168:171], v[184:187], v[116:119]
	v_mfma_f32_16x16x32_bf16 v[116:119], v[172:175], v[188:191], v[116:119]
	v_mfma_f32_16x16x32_bf16 v[108:111], v[176:179], v[184:187], v[108:111]
	v_mfma_f32_16x16x32_bf16 v[108:111], v[180:183], v[188:191], v[108:111]
	v_mfma_f32_16x16x32_bf16 v[100:103], v[168:171], v[192:195], v[100:103]
	v_mfma_f32_16x16x32_bf16 v[100:103], v[172:175], v[196:199], v[100:103]
	v_mfma_f32_16x16x32_bf16 v[92:95], v[176:179], v[192:195], v[92:95]
	v_mfma_f32_16x16x32_bf16 v[92:95], v[180:183], v[196:199], v[92:95]
	v_mfma_f32_16x16x32_bf16 v[84:87], v[168:171], v[200:203], v[84:87]
	v_mfma_f32_16x16x32_bf16 v[84:87], v[172:175], v[204:207], v[84:87]
	v_mfma_f32_16x16x32_bf16 v[76:79], v[176:179], v[200:203], v[76:79]
	v_mfma_f32_16x16x32_bf16 v[76:79], v[180:183], v[204:207], v[76:79]
	v_mfma_f32_16x16x32_bf16 v[68:71], v[168:171], v[208:211], v[68:71]
	v_mfma_f32_16x16x32_bf16 v[68:71], v[172:175], v[212:215], v[68:71]
	v_mfma_f32_16x16x32_bf16 v[64:67], v[176:179], v[208:211], v[64:67]
	v_mfma_f32_16x16x32_bf16 v[64:67], v[180:183], v[212:215], v[64:67]
	s_setprio 0
	s_barrier
	s_add_i32 s18, s44, s25
	v_lshl_add_u64 v[148:149], v[148:149], 0, s[10:11]
	s_mov_b32 m0, s18
	ds_read_b128 v[184:187], v155 offset:49152
	ds_read_b128 v[188:191], v155 offset:50176
	ds_read_b128 v[192:195], v155 offset:51200
	ds_read_b128 v[196:199], v155 offset:52224
	ds_read_b128 v[200:203], v155 offset:53248
	ds_read_b128 v[204:207], v155 offset:54272
	ds_read_b128 v[208:211], v155 offset:55296
	ds_read_b128 v[212:215], v155 offset:56320
	global_load_lds_dwordx4 v[148:149], off
	s_add_i32 m0, s18, 0x2000
	s_add_u32 s2, s2, 0xb0080
	v_lshl_add_u64 v[148:149], v[216:217], 0, s[10:11]
	s_addc_u32 s3, s3, 0
	s_add_i32 s18, s45, s25
	global_load_lds_dwordx4 v[148:149], off
	v_lshl_add_u64 v[148:149], s[2:3], 0, v[130:131]
	s_mov_b32 m0, s18
	s_nop 0
	global_load_lds_dwordx4 v[148:149], off
	v_lshl_add_u64 v[148:149], s[2:3], 0, v[134:135]
	s_add_i32 m0, s18, 0x2000
	s_nop 0
	global_load_lds_dwordx4 v[148:149], off
	v_lshl_add_u64 v[148:149], v[218:219], 0, s[10:11]
	s_mov_b32 m0, s31
	s_nop 0
	global_load_lds_dwordx4 v[148:149], off
	v_lshl_add_u64 v[148:149], v[220:221], 0, s[10:11]
	s_mov_b32 m0, s33
	s_nop 0
	global_load_lds_dwordx4 v[148:149], off
	s_waitcnt vmcnt(8)
	s_waitcnt lgkmcnt(0)
	s_barrier
	s_setprio 1
	s_waitcnt lgkmcnt(0)
	v_mfma_f32_16x16x32_bf16 v[60:63], v[144:147], v[184:187], v[60:63]
	v_mfma_f32_16x16x32_bf16 v[60:63], v[156:159], v[188:191], v[60:63]
	v_mfma_f32_16x16x32_bf16 v[56:59], v[160:163], v[184:187], v[56:59]
	v_mfma_f32_16x16x32_bf16 v[56:59], v[164:167], v[188:191], v[56:59]
	v_mfma_f32_16x16x32_bf16 v[48:51], v[144:147], v[192:195], v[48:51]
	v_mfma_f32_16x16x32_bf16 v[48:51], v[156:159], v[196:199], v[48:51]
	v_mfma_f32_16x16x32_bf16 v[40:43], v[160:163], v[192:195], v[40:43]
	v_mfma_f32_16x16x32_bf16 v[40:43], v[164:167], v[196:199], v[40:43]
	v_mfma_f32_16x16x32_bf16 v[32:35], v[144:147], v[200:203], v[32:35]
	v_mfma_f32_16x16x32_bf16 v[32:35], v[156:159], v[204:207], v[32:35]
	v_mfma_f32_16x16x32_bf16 v[24:27], v[160:163], v[200:203], v[24:27]
	v_mfma_f32_16x16x32_bf16 v[24:27], v[164:167], v[204:207], v[24:27]
	v_mfma_f32_16x16x32_bf16 v[16:19], v[144:147], v[208:211], v[16:19]
	v_mfma_f32_16x16x32_bf16 v[16:19], v[156:159], v[212:215], v[16:19]
	v_mfma_f32_16x16x32_bf16 v[8:11], v[160:163], v[208:211], v[8:11]
	v_mfma_f32_16x16x32_bf16 v[8:11], v[164:167], v[212:215], v[8:11]
	s_setprio 0
	s_setprio 1
	v_mfma_f32_16x16x32_bf16 v[52:55], v[168:171], v[184:187], v[52:55]
	v_mfma_f32_16x16x32_bf16 v[52:55], v[172:175], v[188:191], v[52:55]
	v_mfma_f32_16x16x32_bf16 v[44:47], v[176:179], v[184:187], v[44:47]
	v_mfma_f32_16x16x32_bf16 v[44:47], v[180:183], v[188:191], v[44:47]
	v_mfma_f32_16x16x32_bf16 v[36:39], v[168:171], v[192:195], v[36:39]
	v_mfma_f32_16x16x32_bf16 v[36:39], v[172:175], v[196:199], v[36:39]
	v_mfma_f32_16x16x32_bf16 v[28:31], v[176:179], v[192:195], v[28:31]
	v_mfma_f32_16x16x32_bf16 v[28:31], v[180:183], v[196:199], v[28:31]
	v_mfma_f32_16x16x32_bf16 v[20:23], v[168:171], v[200:203], v[20:23]
	v_mfma_f32_16x16x32_bf16 v[20:23], v[172:175], v[204:207], v[20:23]
	v_mfma_f32_16x16x32_bf16 v[12:15], v[176:179], v[200:203], v[12:15]
	v_mfma_f32_16x16x32_bf16 v[12:15], v[180:183], v[204:207], v[12:15]
	v_mfma_f32_16x16x32_bf16 v[4:7], v[168:171], v[208:211], v[4:7]
	v_mfma_f32_16x16x32_bf16 v[4:7], v[172:175], v[212:215], v[4:7]
	v_mfma_f32_16x16x32_bf16 v[0:3], v[176:179], v[208:211], v[0:3]
	v_mfma_f32_16x16x32_bf16 v[0:3], v[180:183], v[212:215], v[0:3]
	s_setprio 0
	s_barrier
	s_add_i32 s43, s43, 2
	s_add_u32 s16, s16, 0x100
	s_addc_u32 s17, s17, 0
	s_add_u32 s41, s41, 0x100
	s_addc_u32 s42, s42, 0
	s_cmp_gt_u32 s43, 41
	s_cbranch_scc0 .LBB0_2290
	s_and_b64 vcc, exec, s[12:13]
	s_cbranch_vccz .LBB0_2293
	s_barrier
